# scan loops v2: per-chunk y reduce-scatter, even-lane stores; no context scans on the latent scan partners
# baseline (speedup 1.0000x reference)
.LBB0_209:
	s_and_b64 vcc, exec, s[2:3]
	s_cbranch_vccz .LBB0_288
	v_readlane_b32 s6, v226, 3
	v_readlane_b32 s7, v226, 4
	s_mov_b64 s[2:3], -1
	s_and_b64 vcc, exec, s[6:7]
	s_cbranch_vccz .LBB0_276
	v_readlane_b32 s2, v227, 0
	s_mov_b32 s61, 0x2aaaaaab
	s_movk_i32 s67, 0xffa0
	v_readlane_b32 s4, v224, 20
	s_and_b32 s3, s2, 0x180
	s_cmpk_eq_u32 s3, 0x100
	s_cbranch_scc1 .LBB0_224
	v_readlane_b32 s8, v224, 34
	v_readlane_b32 s9, v224, 35
	s_load_dwordx4 s[56:59], s[8:9], 0x1c8
	s_load_dwordx2 s[6:7], s[8:9], 0x1f0
	s_nop 0
	s_load_dwordx2 s[8:9], s[8:9], 0xf8
	s_waitcnt lgkmcnt(0)
	s_sub_u32 s2, s58, s56
	s_subb_u32 s3, s59, s57
	s_lshr_b64 s[2:3], s[2:3], 2
	v_readlane_b32 s3, v227, 0
	s_nop 0
	s_add_i32 s12, s3, 0xffffff80
	s_add_i32 s3, s3, 0xffffff00
	s_cmp_lt_i32 s3, 0
	s_cselect_b32 s3, s12, s3
	s_branch .LBB0_214
.LBB0_213:
	s_lshl_b32 s12, s16, 2
	s_add_i32 s12, s12, s38
	s_ashr_i32 s13, s12, 31
	s_lshl_b64 s[12:13], s[12:13], 3
	s_lshl_b32 s14, s14, 2
	s_or_b32 s12, s12, s14
	s_or_b32 s12, s12, s15
	s_lshl_b64 s[12:13], s[12:13], 14
	s_add_u32 s12, s8, s12
	s_addc_u32 s13, s9, s13
	s_waitcnt vmcnt(11)
	v_lshlrev_b64 v[2:3], 8, v[54:55]
	v_lshl_add_u64 v[2:3], s[12:13], 0, v[2:3]
	s_movk_i32 s12, 0x100
	v_lshlrev_b32_e32 v0, 2, v0
	s_add_i32 s3, s3, s12
	v_lshl_add_u64 v[2:3], v[2:3], 0, v[0:1]
	s_cmpk_gt_i32 s3, 0x1ff
	global_store_dwordx4 v[2:3], v[50:53], off
	s_cbranch_scc1 .LBB0_224
.LBB0_214:
	s_waitcnt vmcnt(8)
	v_mov_b32_e32 v14, v131
	s_lshl_b32 s12, s3, 1
	v_ashrrev_i32_e32 v2, 4, v14
	s_and_b32 s12, s12, 48
	v_and_b32_e32 v2, -4, v2
	s_ashr_i32 s16, s3, 5
	v_lshrrev_b32_e32 v0, 4, v14
	v_add_u32_e32 v2, s12, v2
	s_and_b32 s14, s3, 1
	s_bfe_i32 s13, s3, 0x10000
	s_bfe_u32 s15, s3, 0x20001
	s_lshl_b32 s21, s16, 8
	v_and_or_b32 v54, v0, 3, v2
	v_mul_hi_i32 v2, v14, s61
	s_cmp_eq_u32 s14, 0
	s_mul_i32 s40, s14, 0x900000
	s_mul_i32 s41, s15, 0xc0
	v_lshrrev_b32_e32 v3, 31, v2
	v_ashrrev_i32_e32 v2, 4, v2
	s_cselect_b32 s12, 1, -1
	s_or_b32 s40, s40, s41
	v_add_u32_e32 v4, v2, v3
	s_mul_i32 s42, s12, 0x300
	s_add_i32 s43, s40, 0xffffff40
	s_add_i32 s44, s41, s2
	v_mad_u64_u32 v[2:3], s[40:41], v4, s67, v[14:15]
	v_mul_lo_u32 v3, s42, v4
	v_cmp_gt_i32_e32 vcc, 48, v2
	v_mov_b32_e32 v4, s43
	v_mov_b32_e32 v5, s44
	v_lshlrev_b32_e32 v2, 2, v2
	v_cndmask_b32_e32 v6, v4, v5, vcc
	v_add3_u32 v58, v2, v3, v6
	v_add_u32_e32 v2, 0x100, v14
	v_mul_hi_i32 v3, v2, s61
	v_lshrrev_b32_e32 v6, 31, v3
	v_ashrrev_i32_e32 v3, 4, v3
	v_add_u32_e32 v6, v3, v6
	v_mad_u64_u32 v[2:3], s[40:41], v6, s67, v[2:3]
	v_cmp_gt_i32_e32 vcc, 48, v2
	v_mul_lo_u32 v3, s42, v6
	v_lshlrev_b32_e32 v2, 2, v2
	v_cndmask_b32_e32 v6, v4, v5, vcc
	v_add3_u32 v59, v2, v3, v6
	v_add_u32_e32 v2, 0x200, v14
	v_mul_hi_i32 v3, v2, s61
	s_and_b32 s13, s13, 0xff
	v_lshrrev_b32_e32 v6, 31, v3
	v_ashrrev_i32_e32 v3, 4, v3
	v_add_u32_e32 v6, v3, v6
	s_or_b32 s21, s13, s21
	s_mul_i32 s13, s14, 0xc00000
	v_mad_u64_u32 v[2:3], s[40:41], v6, s67, v[2:3]
	s_add_u32 s13, s6, s13
	v_cmp_gt_i32_e32 vcc, 48, v2
	s_addc_u32 s41, s7, 0
	s_lshl_b32 s40, s15, 8
	v_mul_lo_u32 v3, s42, v6
	v_cndmask_b32_e32 v4, v4, v5, vcc
	v_lshlrev_b32_e32 v2, 2, v2
	s_add_u32 s40, s13, s40
	s_mul_i32 s13, s21, 0x300
	v_add3_u32 v60, v2, v3, v4
	v_add_u32_e32 v2, s13, v58
	v_ashrrev_i32_e32 v3, 31, v2
	v_add_u32_e32 v6, s13, v59
	v_lshl_add_u64 v[2:3], v[2:3], 2, s[56:57]
	v_ashrrev_i32_e32 v7, 31, v6
	v_add_u32_e32 v10, s13, v60
	global_load_dwordx4 v[2:5], v[2:3], off
	v_lshl_add_u64 v[6:7], v[6:7], 2, s[56:57]
	v_ashrrev_i32_e32 v11, 31, v10
	global_load_dwordx4 v[6:9], v[6:7], off
	v_lshl_add_u64 v[10:11], v[10:11], 2, s[56:57]
	global_load_dwordx4 v[10:13], v[10:11], off
	s_addc_u32 s41, s41, 0
	s_lshl_b32 s58, s12, 3
	v_ashrrev_i32_e32 v55, 31, v54
	s_add_i32 s13, s58, s21
	v_lshl_add_u64 v[56:57], v[54:55], 2, s[40:41]
	v_lshlrev_b32_e32 v61, 4, v14
	s_mul_i32 s40, s13, 0x300
	s_add_i32 s13, s13, s58
	v_and_b32_e32 v50, 15, v14
	v_lshlrev_b32_e32 v0, 2, v50
	v_add_u32_e32 v51, 8, v50
	v_add_u32_e32 v52, 24, v50
	v_lshlrev_b32_e32 v62, 4, v50
	v_cmp_gt_u32_e32 vcc, 8, v50
	v_cmp_eq_u32_e64 s[42:43], 6, v50
	v_cmp_eq_u32_e64 s[44:45], 5, v50
	v_cmp_eq_u32_e64 s[46:47], 4, v50
	v_cmp_eq_u32_e64 s[48:49], 3, v50
	v_cmp_eq_u32_e64 s[50:51], 2, v50
	v_cmp_eq_u32_e64 s[52:53], 1, v50
	v_cmp_eq_u32_e64 s[54:55], 0, v50
	v_mul_i32_i24_e32 v64, s12, v50
	s_mov_b32 s20, -4
	v_lshlrev_b32_e32 v63, 2, v54
	s_lshl_b32 s59, s12, 5
	v_mul_i32_i24_e32 v65, s12, v51
	v_mul_i32_i24_e32 v67, s12, v52
	s_mov_b32 s60, s21
	s_waitcnt vmcnt(2)
	ds_write_b128 v61, v[2:5]
	s_waitcnt vmcnt(1)
	ds_write_b128 v61, v[6:9] offset:4096
	s_waitcnt vmcnt(0)
	ds_write_b128 v61, v[10:13] offset:8192
	v_add_u32_e32 v2, s40, v58
	v_add_u32_e32 v6, s40, v59
	v_add_u32_e32 v10, s40, v60
	s_mul_i32 s40, s13, 0x300
	s_add_i32 s13, s13, s58
	v_add_u32_e32 v14, s40, v58
	v_add_u32_e32 v18, s40, v59
	v_add_u32_e32 v22, s40, v60
	s_mul_i32 s40, s13, 0x300
	s_add_i32 s13, s13, s58
	s_mulk_i32 s13, 0x300
	v_add_u32_e32 v26, s40, v58
	v_add_u32_e32 v30, s40, v59
	v_add_u32_e32 v34, s40, v60
	v_add_u32_e32 v38, s13, v58
	v_add_u32_e32 v42, s13, v59
	v_add_u32_e32 v46, s13, v60
	v_ashrrev_i32_e32 v3, 31, v2
	v_ashrrev_i32_e32 v7, 31, v6
	v_ashrrev_i32_e32 v11, 31, v10
	v_ashrrev_i32_e32 v15, 31, v14
	v_ashrrev_i32_e32 v19, 31, v18
	v_ashrrev_i32_e32 v23, 31, v22
	v_ashrrev_i32_e32 v27, 31, v26
	v_ashrrev_i32_e32 v31, 31, v30
	v_ashrrev_i32_e32 v35, 31, v34
	v_ashrrev_i32_e32 v39, 31, v38
	v_ashrrev_i32_e32 v43, 31, v42
	v_ashrrev_i32_e32 v47, 31, v46
	v_lshl_add_u64 v[2:3], v[2:3], 2, s[56:57]
	v_lshl_add_u64 v[6:7], v[6:7], 2, s[56:57]
	v_lshl_add_u64 v[10:11], v[10:11], 2, s[56:57]
	v_lshl_add_u64 v[14:15], v[14:15], 2, s[56:57]
	v_lshl_add_u64 v[18:19], v[18:19], 2, s[56:57]
	v_lshl_add_u64 v[22:23], v[22:23], 2, s[56:57]
	v_lshl_add_u64 v[26:27], v[26:27], 2, s[56:57]
	v_lshl_add_u64 v[30:31], v[30:31], 2, s[56:57]
	v_lshl_add_u64 v[34:35], v[34:35], 2, s[56:57]
	v_lshl_add_u64 v[38:39], v[38:39], 2, s[56:57]
	v_lshl_add_u64 v[42:43], v[42:43], 2, s[56:57]
	v_lshl_add_u64 v[46:47], v[46:47], 2, s[56:57]
	global_load_dwordx4 v[2:5], v[2:3], off
	v_cmp_eq_u32_e64 s[40:41], 7, v50
	global_load_dwordx4 v[6:9], v[6:7], off
	v_or_b32_e32 v50, 16, v50
	global_load_dwordx4 v[10:13], v[10:11], off
	v_mul_i32_i24_e32 v66, s12, v50
	global_load_dwordx4 v[14:17], v[14:15], off
	v_mov_b32_e32 v50, 0
	global_load_dwordx4 v[18:21], v[18:19], off
	v_mov_b32_e32 v51, v50
	global_load_dwordx4 v[22:25], v[22:23], off
	v_mov_b32_e32 v52, v50
	global_load_dwordx4 v[26:29], v[26:27], off
	v_mov_b32_e32 v53, v50
	global_load_dwordx4 v[30:33], v[30:31], off
	s_nop 0
	global_load_dwordx4 v[34:37], v[34:35], off
	s_nop 0
	global_load_dwordx4 v[38:41], v[38:39], off
	s_nop 0
	global_load_dwordx4 v[42:45], v[42:43], off
	s_nop 0
	global_load_dwordx4 v[46:49], v[46:47], off
	v_lshrrev_b32_e32 v68, 5, v62
	v_mul_i32_i24_e32 v64, s12, v68
	v_add_u32_e32 v69, 8, v68
	v_mul_i32_i24_e32 v65, s12, v69
	v_add_u32_e32 v69, 16, v68
	v_mul_i32_i24_e32 v66, s12, v69
	v_add_u32_e32 v69, 24, v68
	v_mul_i32_i24_e32 v67, s12, v69
	v_and_b32_e32 v68, 0x80, v62
	v_cmp_ne_u32_e64 s[40:41], 0, v68
	v_and_b32_e32 v68, 64, v62
	v_cmp_ne_u32_e64 s[42:43], 0, v68
	v_and_b32_e32 v68, 32, v62
	v_cmp_ne_u32_e64 s[44:45], 0, v68
	v_and_b32_e32 v68, 16, v62
	v_cmp_eq_u32_e32 vcc, 0, v68
	s_waitcnt lgkmcnt(0)
	s_barrier
	s_branch .LBB0_216
.LBB0_216:
	s_add_i32 s20, s20, 4
	ds_read_b128 v[68:71], v62 offset:0
	ds_read_b128 v[76:79], v62 offset:1280
	ds_read_b32 v88, v63 offset:512
	ds_read_b128 v[72:75], v62 offset:768
	ds_read_b128 v[100:103], v62 offset:2816
	ds_read_b32 v90, v63 offset:2048
	ds_read_b128 v[80:83], v62 offset:1024
	ds_read_b128 v[92:95], v62 offset:1536
	ds_read_b128 v[84:87], v62 offset:256
	ds_read_b128 v[96:99], v62 offset:2304
	ds_read_b128 v[104:107], v62 offset:2560
	s_min_u32 s12, s20, 26
	s_add_i32 s12, s12, 5
	s_mul_i32 s12, s12, s58
	s_add_i32 s12, s12, s21
	s_mulk_i32 s12, 0x300
	s_waitcnt vmcnt(11)
	ds_write_b128 v61, v[2:5] offset:12288
	s_waitcnt vmcnt(10)
	ds_write_b128 v61, v[6:9] offset:16384
	s_waitcnt vmcnt(9)
	ds_write_b128 v61, v[10:13] offset:20480
	v_add_u32_e32 v2, s12, v58
	v_add_u32_e32 v4, s12, v59
	v_add_u32_e32 v10, s12, v60
	v_ashrrev_i32_e32 v3, 31, v2
	v_ashrrev_i32_e32 v5, 31, v4
	v_ashrrev_i32_e32 v11, 31, v10
	v_lshl_add_u64 v[2:3], v[2:3], 2, s[56:57]
	v_lshl_add_u64 v[6:7], v[4:5], 2, s[56:57]
	v_lshl_add_u64 v[10:11], v[10:11], 2, s[56:57]
	global_load_dwordx4 v[2:5], v[2:3], off
	s_nop 0
	global_load_dwordx4 v[6:9], v[6:7], off
	s_nop 0
	global_load_dwordx4 v[10:13], v[10:11], off
	s_waitcnt lgkmcnt(11)
	v_pk_mul_f32 v[112:113], v[76:77], v[88:89] op_sel_hi:[1,0]
	v_pk_mul_f32 v[114:115], v[78:79], v[88:89] op_sel_hi:[1,0]
	ds_read_b128 v[76:79], v62 offset:4352
	ds_read_b32 v88, v63 offset:3584
	s_waitcnt lgkmcnt(9)
	v_pk_mul_f32 v[120:121], v[52:53], v[70:71]
	v_pk_fma_f32 v[120:121], v[50:51], v[68:69], v[120:121]
	ds_read_b128 v[68:71], v62 offset:3072
	v_add_f32_e32 v124, v120, v121
	v_pk_fma_f32 v[112:113], v[50:51], v[72:73], v[112:113]
	v_pk_fma_f32 v[114:115], v[52:53], v[74:75], v[114:115]
	ds_read_b128 v[72:75], v62 offset:3840
	v_add_f32_dpp v124, v124, v124 quad_perm:[1,0,3,2] row_mask:0xf bank_mask:0xf bound_ctrl:1
	ds_read_b128 v[108:111], v62 offset:1792
	s_nop 0
	v_add_f32_dpp v124, v124, v124 quad_perm:[2,3,0,1] row_mask:0xf bank_mask:0xf bound_ctrl:1
	v_pk_mul_f32 v[116:117], v[100:101], v[90:91] op_sel_hi:[1,0]
	v_pk_mul_f32 v[118:119], v[102:103], v[90:91] op_sel_hi:[1,0]
	v_add_f32_dpp v124, v124, v124 row_half_mirror row_mask:0xf bank_mask:0xf bound_ctrl:1
	ds_read_b128 v[100:103], v62 offset:5888
	ds_read_b32 v90, v63 offset:5120
	v_add_f32_dpp v124, v124, v124 row_mirror row_mask:0xf bank_mask:0xf bound_ctrl:1
	v_pk_fma_f32 v[50:51], v[80:81], v[124:125], v[112:113] op_sel_hi:[1,0,1]
	v_pk_fma_f32 v[52:53], v[82:83], v[124:125], v[114:115] op_sel_hi:[1,0,1]
	ds_read_b128 v[80:83], v62 offset:4096
	s_waitcnt lgkmcnt(6)
	v_pk_mul_f32 v[120:121], v[52:53], v[94:95]
	v_pk_fma_f32 v[120:121], v[50:51], v[92:93], v[120:121]
	ds_read_b128 v[92:95], v62 offset:4608
	v_add_f32_e32 v124, v120, v121
	v_pk_fma_f32 v[116:117], v[50:51], v[96:97], v[116:117]
	v_pk_fma_f32 v[118:119], v[52:53], v[98:99], v[118:119]
	ds_read_b128 v[96:99], v62 offset:5376
	v_add_f32_dpp v124, v124, v124 quad_perm:[1,0,3,2] row_mask:0xf bank_mask:0xf bound_ctrl:1
	v_pk_mul_f32 v[122:123], v[52:53], v[86:87]
	v_pk_fma_f32 v[122:123], v[50:51], v[84:85], v[122:123]
	ds_read_b128 v[84:87], v62 offset:3328
	v_add_f32_dpp v124, v124, v124 quad_perm:[2,3,0,1] row_mask:0xf bank_mask:0xf bound_ctrl:1
	v_pk_mul_f32 v[112:113], v[76:77], v[88:89] op_sel_hi:[1,0]
	v_pk_mul_f32 v[114:115], v[78:79], v[88:89] op_sel_hi:[1,0]
	v_add_f32_dpp v124, v124, v124 row_half_mirror row_mask:0xf bank_mask:0xf bound_ctrl:1
	v_add_f32_e32 v216, v122, v123
	ds_read_b128 v[76:79], v62 offset:7424
	ds_read_b32 v88, v63 offset:6656
	v_add_f32_dpp v124, v124, v124 row_mirror row_mask:0xf bank_mask:0xf bound_ctrl:1
	v_pk_fma_f32 v[50:51], v[104:105], v[124:125], v[116:117] op_sel_hi:[1,0,1]
	v_pk_fma_f32 v[52:53], v[106:107], v[124:125], v[118:119] op_sel_hi:[1,0,1]
	ds_read_b128 v[104:107], v62 offset:5632
	s_waitcnt lgkmcnt(6)
	v_pk_mul_f32 v[120:121], v[52:53], v[70:71]
	v_pk_fma_f32 v[120:121], v[50:51], v[68:69], v[120:121]
	ds_read_b128 v[68:71], v62 offset:6144
	v_add_f32_e32 v124, v120, v121
	v_pk_fma_f32 v[112:113], v[50:51], v[72:73], v[112:113]
	v_pk_fma_f32 v[114:115], v[52:53], v[74:75], v[114:115]
	ds_read_b128 v[72:75], v62 offset:6912
	v_add_f32_dpp v124, v124, v124 quad_perm:[1,0,3,2] row_mask:0xf bank_mask:0xf bound_ctrl:1
	v_pk_mul_f32 v[122:123], v[52:53], v[110:111]
	v_pk_fma_f32 v[122:123], v[50:51], v[108:109], v[122:123]
	ds_read_b128 v[108:111], v62 offset:4864
	v_add_f32_dpp v124, v124, v124 quad_perm:[2,3,0,1] row_mask:0xf bank_mask:0xf bound_ctrl:1
	v_pk_mul_f32 v[116:117], v[100:101], v[90:91] op_sel_hi:[1,0]
	v_pk_mul_f32 v[118:119], v[102:103], v[90:91] op_sel_hi:[1,0]
	v_add_f32_dpp v124, v124, v124 row_half_mirror row_mask:0xf bank_mask:0xf bound_ctrl:1
	v_add_f32_e32 v217, v122, v123
	ds_read_b128 v[100:103], v62 offset:8960
	ds_read_b32 v90, v63 offset:8192
	v_add_f32_dpp v124, v124, v124 row_mirror row_mask:0xf bank_mask:0xf bound_ctrl:1
	v_pk_fma_f32 v[50:51], v[80:81], v[124:125], v[112:113] op_sel_hi:[1,0,1]
	v_pk_fma_f32 v[52:53], v[82:83], v[124:125], v[114:115] op_sel_hi:[1,0,1]
	ds_read_b128 v[80:83], v62 offset:7168
	s_waitcnt lgkmcnt(6)
	v_pk_mul_f32 v[120:121], v[52:53], v[94:95]
	v_pk_fma_f32 v[120:121], v[50:51], v[92:93], v[120:121]
	ds_read_b128 v[92:95], v62 offset:7680
	v_add_f32_e32 v124, v120, v121
	v_pk_fma_f32 v[116:117], v[50:51], v[96:97], v[116:117]
	v_pk_fma_f32 v[118:119], v[52:53], v[98:99], v[118:119]
	ds_read_b128 v[96:99], v62 offset:8448
	v_add_f32_dpp v124, v124, v124 quad_perm:[1,0,3,2] row_mask:0xf bank_mask:0xf bound_ctrl:1
	v_pk_mul_f32 v[122:123], v[52:53], v[86:87]
	v_pk_fma_f32 v[122:123], v[50:51], v[84:85], v[122:123]
	ds_read_b128 v[84:87], v62 offset:6400
	v_add_f32_dpp v124, v124, v124 quad_perm:[2,3,0,1] row_mask:0xf bank_mask:0xf bound_ctrl:1
	v_pk_mul_f32 v[112:113], v[76:77], v[88:89] op_sel_hi:[1,0]
	v_pk_mul_f32 v[114:115], v[78:79], v[88:89] op_sel_hi:[1,0]
	v_add_f32_dpp v124, v124, v124 row_half_mirror row_mask:0xf bank_mask:0xf bound_ctrl:1
	v_add_f32_e32 v218, v122, v123
	ds_read_b128 v[76:79], v62 offset:10496
	ds_read_b32 v88, v63 offset:9728
	v_add_f32_dpp v124, v124, v124 row_mirror row_mask:0xf bank_mask:0xf bound_ctrl:1
	v_pk_fma_f32 v[50:51], v[104:105], v[124:125], v[116:117] op_sel_hi:[1,0,1]
	v_pk_fma_f32 v[52:53], v[106:107], v[124:125], v[118:119] op_sel_hi:[1,0,1]
	ds_read_b128 v[104:107], v62 offset:8704
	s_waitcnt lgkmcnt(6)
	v_pk_mul_f32 v[120:121], v[52:53], v[70:71]
	v_pk_fma_f32 v[120:121], v[50:51], v[68:69], v[120:121]
	ds_read_b128 v[68:71], v62 offset:9216
	v_add_f32_e32 v124, v120, v121
	v_pk_fma_f32 v[112:113], v[50:51], v[72:73], v[112:113]
	v_pk_fma_f32 v[114:115], v[52:53], v[74:75], v[114:115]
	ds_read_b128 v[72:75], v62 offset:9984
	v_add_f32_dpp v124, v124, v124 quad_perm:[1,0,3,2] row_mask:0xf bank_mask:0xf bound_ctrl:1
	v_pk_mul_f32 v[122:123], v[52:53], v[110:111]
	v_pk_fma_f32 v[122:123], v[50:51], v[108:109], v[122:123]
	ds_read_b128 v[108:111], v62 offset:7936
	v_add_f32_dpp v124, v124, v124 quad_perm:[2,3,0,1] row_mask:0xf bank_mask:0xf bound_ctrl:1
	v_pk_mul_f32 v[116:117], v[100:101], v[90:91] op_sel_hi:[1,0]
	v_pk_mul_f32 v[118:119], v[102:103], v[90:91] op_sel_hi:[1,0]
	v_add_f32_dpp v124, v124, v124 row_half_mirror row_mask:0xf bank_mask:0xf bound_ctrl:1
	v_add_f32_e32 v219, v122, v123
	ds_read_b128 v[100:103], v62 offset:12032
	ds_read_b32 v90, v63 offset:11264
	v_add_f32_dpp v124, v124, v124 row_mirror row_mask:0xf bank_mask:0xf bound_ctrl:1
	v_pk_fma_f32 v[50:51], v[80:81], v[124:125], v[112:113] op_sel_hi:[1,0,1]
	v_pk_fma_f32 v[52:53], v[82:83], v[124:125], v[114:115] op_sel_hi:[1,0,1]
	ds_read_b128 v[80:83], v62 offset:10240
	s_waitcnt lgkmcnt(6)
	v_pk_mul_f32 v[120:121], v[52:53], v[94:95]
	v_pk_fma_f32 v[120:121], v[50:51], v[92:93], v[120:121]
	ds_read_b128 v[92:95], v62 offset:10752
	v_add_f32_e32 v124, v120, v121
	v_pk_fma_f32 v[116:117], v[50:51], v[96:97], v[116:117]
	v_pk_fma_f32 v[118:119], v[52:53], v[98:99], v[118:119]
	ds_read_b128 v[96:99], v62 offset:11520
	v_add_f32_dpp v124, v124, v124 quad_perm:[1,0,3,2] row_mask:0xf bank_mask:0xf bound_ctrl:1
	v_pk_mul_f32 v[122:123], v[52:53], v[86:87]
	v_pk_fma_f32 v[122:123], v[50:51], v[84:85], v[122:123]
	ds_read_b128 v[84:87], v62 offset:9472
	v_add_f32_dpp v124, v124, v124 quad_perm:[2,3,0,1] row_mask:0xf bank_mask:0xf bound_ctrl:1
	v_pk_mul_f32 v[112:113], v[76:77], v[88:89] op_sel_hi:[1,0]
	v_pk_mul_f32 v[114:115], v[78:79], v[88:89] op_sel_hi:[1,0]
	v_add_f32_dpp v124, v124, v124 row_half_mirror row_mask:0xf bank_mask:0xf bound_ctrl:1
	v_add_f32_e32 v220, v122, v123
	s_nop 0
	v_add_f32_dpp v124, v124, v124 row_mirror row_mask:0xf bank_mask:0xf bound_ctrl:1
	v_pk_fma_f32 v[50:51], v[104:105], v[124:125], v[116:117] op_sel_hi:[1,0,1]
	v_pk_fma_f32 v[52:53], v[106:107], v[124:125], v[118:119] op_sel_hi:[1,0,1]
	ds_read_b128 v[104:107], v62 offset:11776
	s_waitcnt lgkmcnt(4)
	v_pk_mul_f32 v[120:121], v[52:53], v[70:71]
	v_pk_fma_f32 v[120:121], v[50:51], v[68:69], v[120:121]
	v_add_f32_e32 v124, v120, v121
	v_pk_fma_f32 v[112:113], v[50:51], v[72:73], v[112:113]
	v_pk_fma_f32 v[114:115], v[52:53], v[74:75], v[114:115]
	v_add_f32_dpp v124, v124, v124 quad_perm:[1,0,3,2] row_mask:0xf bank_mask:0xf bound_ctrl:1
	v_pk_mul_f32 v[122:123], v[52:53], v[110:111]
	v_pk_fma_f32 v[122:123], v[50:51], v[108:109], v[122:123]
	ds_read_b128 v[108:111], v62 offset:11008
	v_add_f32_dpp v124, v124, v124 quad_perm:[2,3,0,1] row_mask:0xf bank_mask:0xf bound_ctrl:1
	v_pk_mul_f32 v[116:117], v[100:101], v[90:91] op_sel_hi:[1,0]
	v_pk_mul_f32 v[118:119], v[102:103], v[90:91] op_sel_hi:[1,0]
	v_add_f32_dpp v124, v124, v124 row_half_mirror row_mask:0xf bank_mask:0xf bound_ctrl:1
	v_add_f32_e32 v221, v122, v123
	s_nop 0
	v_add_f32_dpp v124, v124, v124 row_mirror row_mask:0xf bank_mask:0xf bound_ctrl:1
	v_pk_fma_f32 v[50:51], v[80:81], v[124:125], v[112:113] op_sel_hi:[1,0,1]
	v_pk_fma_f32 v[52:53], v[82:83], v[124:125], v[114:115] op_sel_hi:[1,0,1]
	s_waitcnt lgkmcnt(1)
	v_pk_mul_f32 v[120:121], v[52:53], v[94:95]
	v_pk_fma_f32 v[120:121], v[50:51], v[92:93], v[120:121]
	v_add_f32_e32 v124, v120, v121
	v_pk_fma_f32 v[116:117], v[50:51], v[96:97], v[116:117]
	v_pk_fma_f32 v[118:119], v[52:53], v[98:99], v[118:119]
	v_add_f32_dpp v124, v124, v124 quad_perm:[1,0,3,2] row_mask:0xf bank_mask:0xf bound_ctrl:1
	v_pk_mul_f32 v[122:123], v[52:53], v[86:87]
	v_pk_fma_f32 v[122:123], v[50:51], v[84:85], v[122:123]
	v_add_f32_dpp v124, v124, v124 quad_perm:[2,3,0,1] row_mask:0xf bank_mask:0xf bound_ctrl:1
	s_nop 1
	v_add_f32_dpp v124, v124, v124 row_half_mirror row_mask:0xf bank_mask:0xf bound_ctrl:1
	v_add_f32_e32 v222, v122, v123
	s_nop 0
	v_add_f32_dpp v124, v124, v124 row_mirror row_mask:0xf bank_mask:0xf bound_ctrl:1
	v_pk_fma_f32 v[50:51], v[104:105], v[124:125], v[116:117] op_sel_hi:[1,0,1]
	v_pk_fma_f32 v[52:53], v[106:107], v[124:125], v[118:119] op_sel_hi:[1,0,1]
	s_waitcnt lgkmcnt(0)
	v_pk_mul_f32 v[122:123], v[52:53], v[110:111]
	v_pk_fma_f32 v[122:123], v[50:51], v[108:109], v[122:123]
	v_add_f32_e32 v223, v122, v123
	v_cndmask_b32_e64 v68, v216, v220, s[40:41]
	v_cndmask_b32_e64 v72, v220, v216, s[40:41]
	v_cndmask_b32_e64 v69, v217, v221, s[40:41]
	v_cndmask_b32_e64 v73, v221, v217, s[40:41]
	v_cndmask_b32_e64 v70, v218, v222, s[40:41]
	v_cndmask_b32_e64 v74, v222, v218, s[40:41]
	v_cndmask_b32_e64 v71, v219, v223, s[40:41]
	v_cndmask_b32_e64 v75, v223, v219, s[40:41]
	v_add_f32_dpp v68, v72, v68 row_mirror row_mask:0xf bank_mask:0xf bound_ctrl:1
	v_add_f32_dpp v69, v73, v69 row_mirror row_mask:0xf bank_mask:0xf bound_ctrl:1
	v_add_f32_dpp v70, v74, v70 row_mirror row_mask:0xf bank_mask:0xf bound_ctrl:1
	v_add_f32_dpp v71, v75, v71 row_mirror row_mask:0xf bank_mask:0xf bound_ctrl:1
	v_cndmask_b32_e64 v76, v68, v70, s[42:43]
	v_cndmask_b32_e64 v78, v70, v68, s[42:43]
	v_cndmask_b32_e64 v77, v69, v71, s[42:43]
	v_cndmask_b32_e64 v79, v71, v69, s[42:43]
	v_add_u32_e32 v128, s60, v64
	v_add_f32_dpp v76, v78, v76 row_half_mirror row_mask:0xf bank_mask:0xf bound_ctrl:1
	v_add_f32_dpp v77, v79, v77 row_half_mirror row_mask:0xf bank_mask:0xf bound_ctrl:1
	v_cndmask_b32_e64 v80, v76, v77, s[44:45]
	v_cndmask_b32_e64 v81, v77, v76, s[44:45]
	v_ashrrev_i32_e32 v129, 31, v128
	v_lshlrev_b64 v[128:129], 10, v[128:129]
	v_add_f32_dpp v80, v81, v80 quad_perm:[2,3,0,1] row_mask:0xf bank_mask:0xf bound_ctrl:1
	v_lshl_add_u64 v[128:129], v[56:57], 0, v[128:129]
	s_nop 0
	v_add_f32_dpp v127, v80, v80 quad_perm:[1,0,3,2] row_mask:0xf bank_mask:0xf bound_ctrl:1
	s_and_saveexec_b64 s[12:13], vcc
	global_store_dword v[128:129], v127, off
	s_or_b64 exec, exec, s[12:13]
	s_waitcnt lgkmcnt(0)
	s_barrier
	ds_read_b128 v[68:71], v62 offset:12288
	ds_read_b128 v[76:79], v62 offset:13568
	ds_read_b32 v88, v63 offset:12800
	ds_read_b128 v[72:75], v62 offset:13056
	ds_read_b128 v[100:103], v62 offset:15104
	ds_read_b32 v90, v63 offset:14336
	ds_read_b128 v[80:83], v62 offset:13312
	ds_read_b128 v[92:95], v62 offset:13824
	ds_read_b128 v[84:87], v62 offset:12544
	ds_read_b128 v[96:99], v62 offset:14592
	ds_read_b128 v[104:107], v62 offset:14848
	s_min_u32 s12, s20, 25
	s_add_i32 s12, s12, 6
	s_mul_i32 s12, s12, s58
	s_add_i32 s12, s12, s21
	s_mulk_i32 s12, 0x300
	s_waitcnt vmcnt(11)
	ds_write_b128 v61, v[14:17]
	s_waitcnt vmcnt(10)
	ds_write_b128 v61, v[18:21] offset:4096
	s_waitcnt vmcnt(9)
	ds_write_b128 v61, v[22:25] offset:8192
	v_add_u32_e32 v14, s12, v58
	v_add_u32_e32 v16, s12, v59
	v_add_u32_e32 v22, s12, v60
	v_ashrrev_i32_e32 v15, 31, v14
	v_ashrrev_i32_e32 v17, 31, v16
	v_ashrrev_i32_e32 v23, 31, v22
	v_lshl_add_u64 v[14:15], v[14:15], 2, s[56:57]
	v_lshl_add_u64 v[18:19], v[16:17], 2, s[56:57]
	v_lshl_add_u64 v[22:23], v[22:23], 2, s[56:57]
	global_load_dwordx4 v[14:17], v[14:15], off
	s_nop 0
	global_load_dwordx4 v[18:21], v[18:19], off
	s_nop 0
	global_load_dwordx4 v[22:25], v[22:23], off
	s_waitcnt lgkmcnt(11)
	v_pk_mul_f32 v[112:113], v[76:77], v[88:89] op_sel_hi:[1,0]
	v_pk_mul_f32 v[114:115], v[78:79], v[88:89] op_sel_hi:[1,0]
	ds_read_b128 v[76:79], v62 offset:16640
	ds_read_b32 v88, v63 offset:15872
	s_waitcnt lgkmcnt(9)
	v_pk_mul_f32 v[120:121], v[52:53], v[70:71]
	v_pk_fma_f32 v[120:121], v[50:51], v[68:69], v[120:121]
	ds_read_b128 v[68:71], v62 offset:15360
	v_add_f32_e32 v124, v120, v121
	v_pk_fma_f32 v[112:113], v[50:51], v[72:73], v[112:113]
	v_pk_fma_f32 v[114:115], v[52:53], v[74:75], v[114:115]
	ds_read_b128 v[72:75], v62 offset:16128
	v_add_f32_dpp v124, v124, v124 quad_perm:[1,0,3,2] row_mask:0xf bank_mask:0xf bound_ctrl:1
	ds_read_b128 v[108:111], v62 offset:14080
	s_nop 0
	v_add_f32_dpp v124, v124, v124 quad_perm:[2,3,0,1] row_mask:0xf bank_mask:0xf bound_ctrl:1
	v_pk_mul_f32 v[116:117], v[100:101], v[90:91] op_sel_hi:[1,0]
	v_pk_mul_f32 v[118:119], v[102:103], v[90:91] op_sel_hi:[1,0]
	v_add_f32_dpp v124, v124, v124 row_half_mirror row_mask:0xf bank_mask:0xf bound_ctrl:1
	ds_read_b128 v[100:103], v62 offset:18176
	ds_read_b32 v90, v63 offset:17408
	v_add_f32_dpp v124, v124, v124 row_mirror row_mask:0xf bank_mask:0xf bound_ctrl:1
	v_pk_fma_f32 v[50:51], v[80:81], v[124:125], v[112:113] op_sel_hi:[1,0,1]
	v_pk_fma_f32 v[52:53], v[82:83], v[124:125], v[114:115] op_sel_hi:[1,0,1]
	ds_read_b128 v[80:83], v62 offset:16384
	s_waitcnt lgkmcnt(6)
	v_pk_mul_f32 v[120:121], v[52:53], v[94:95]
	v_pk_fma_f32 v[120:121], v[50:51], v[92:93], v[120:121]
	ds_read_b128 v[92:95], v62 offset:16896
	v_add_f32_e32 v124, v120, v121
	v_pk_fma_f32 v[116:117], v[50:51], v[96:97], v[116:117]
	v_pk_fma_f32 v[118:119], v[52:53], v[98:99], v[118:119]
	ds_read_b128 v[96:99], v62 offset:17664
	v_add_f32_dpp v124, v124, v124 quad_perm:[1,0,3,2] row_mask:0xf bank_mask:0xf bound_ctrl:1
	v_pk_mul_f32 v[122:123], v[52:53], v[86:87]
	v_pk_fma_f32 v[122:123], v[50:51], v[84:85], v[122:123]
	ds_read_b128 v[84:87], v62 offset:15616
	v_add_f32_dpp v124, v124, v124 quad_perm:[2,3,0,1] row_mask:0xf bank_mask:0xf bound_ctrl:1
	v_pk_mul_f32 v[112:113], v[76:77], v[88:89] op_sel_hi:[1,0]
	v_pk_mul_f32 v[114:115], v[78:79], v[88:89] op_sel_hi:[1,0]
	v_add_f32_dpp v124, v124, v124 row_half_mirror row_mask:0xf bank_mask:0xf bound_ctrl:1
	v_add_f32_e32 v216, v122, v123
	ds_read_b128 v[76:79], v62 offset:19712
	ds_read_b32 v88, v63 offset:18944
	v_add_f32_dpp v124, v124, v124 row_mirror row_mask:0xf bank_mask:0xf bound_ctrl:1
	v_pk_fma_f32 v[50:51], v[104:105], v[124:125], v[116:117] op_sel_hi:[1,0,1]
	v_pk_fma_f32 v[52:53], v[106:107], v[124:125], v[118:119] op_sel_hi:[1,0,1]
	ds_read_b128 v[104:107], v62 offset:17920
	s_waitcnt lgkmcnt(6)
	v_pk_mul_f32 v[120:121], v[52:53], v[70:71]
	v_pk_fma_f32 v[120:121], v[50:51], v[68:69], v[120:121]
	ds_read_b128 v[68:71], v62 offset:18432
	v_add_f32_e32 v124, v120, v121
	v_pk_fma_f32 v[112:113], v[50:51], v[72:73], v[112:113]
	v_pk_fma_f32 v[114:115], v[52:53], v[74:75], v[114:115]
	ds_read_b128 v[72:75], v62 offset:19200
	v_add_f32_dpp v124, v124, v124 quad_perm:[1,0,3,2] row_mask:0xf bank_mask:0xf bound_ctrl:1
	v_pk_mul_f32 v[122:123], v[52:53], v[110:111]
	v_pk_fma_f32 v[122:123], v[50:51], v[108:109], v[122:123]
	ds_read_b128 v[108:111], v62 offset:17152
	v_add_f32_dpp v124, v124, v124 quad_perm:[2,3,0,1] row_mask:0xf bank_mask:0xf bound_ctrl:1
	v_pk_mul_f32 v[116:117], v[100:101], v[90:91] op_sel_hi:[1,0]
	v_pk_mul_f32 v[118:119], v[102:103], v[90:91] op_sel_hi:[1,0]
	v_add_f32_dpp v124, v124, v124 row_half_mirror row_mask:0xf bank_mask:0xf bound_ctrl:1
	v_add_f32_e32 v217, v122, v123
	ds_read_b128 v[100:103], v62 offset:21248
	ds_read_b32 v90, v63 offset:20480
	v_add_f32_dpp v124, v124, v124 row_mirror row_mask:0xf bank_mask:0xf bound_ctrl:1
	v_pk_fma_f32 v[50:51], v[80:81], v[124:125], v[112:113] op_sel_hi:[1,0,1]
	v_pk_fma_f32 v[52:53], v[82:83], v[124:125], v[114:115] op_sel_hi:[1,0,1]
	ds_read_b128 v[80:83], v62 offset:19456
	s_waitcnt lgkmcnt(6)
	v_pk_mul_f32 v[120:121], v[52:53], v[94:95]
	v_pk_fma_f32 v[120:121], v[50:51], v[92:93], v[120:121]
	ds_read_b128 v[92:95], v62 offset:19968
	v_add_f32_e32 v124, v120, v121
	v_pk_fma_f32 v[116:117], v[50:51], v[96:97], v[116:117]
	v_pk_fma_f32 v[118:119], v[52:53], v[98:99], v[118:119]
	ds_read_b128 v[96:99], v62 offset:20736
	v_add_f32_dpp v124, v124, v124 quad_perm:[1,0,3,2] row_mask:0xf bank_mask:0xf bound_ctrl:1
	v_pk_mul_f32 v[122:123], v[52:53], v[86:87]
	v_pk_fma_f32 v[122:123], v[50:51], v[84:85], v[122:123]
	ds_read_b128 v[84:87], v62 offset:18688
	v_add_f32_dpp v124, v124, v124 quad_perm:[2,3,0,1] row_mask:0xf bank_mask:0xf bound_ctrl:1
	v_pk_mul_f32 v[112:113], v[76:77], v[88:89] op_sel_hi:[1,0]
	v_pk_mul_f32 v[114:115], v[78:79], v[88:89] op_sel_hi:[1,0]
	v_add_f32_dpp v124, v124, v124 row_half_mirror row_mask:0xf bank_mask:0xf bound_ctrl:1
	v_add_f32_e32 v218, v122, v123
	ds_read_b128 v[76:79], v62 offset:22784
	ds_read_b32 v88, v63 offset:22016
	v_add_f32_dpp v124, v124, v124 row_mirror row_mask:0xf bank_mask:0xf bound_ctrl:1
	v_pk_fma_f32 v[50:51], v[104:105], v[124:125], v[116:117] op_sel_hi:[1,0,1]
	v_pk_fma_f32 v[52:53], v[106:107], v[124:125], v[118:119] op_sel_hi:[1,0,1]
	ds_read_b128 v[104:107], v62 offset:20992
	s_waitcnt lgkmcnt(6)
	v_pk_mul_f32 v[120:121], v[52:53], v[70:71]
	v_pk_fma_f32 v[120:121], v[50:51], v[68:69], v[120:121]
	ds_read_b128 v[68:71], v62 offset:21504
	v_add_f32_e32 v124, v120, v121
	v_pk_fma_f32 v[112:113], v[50:51], v[72:73], v[112:113]
	v_pk_fma_f32 v[114:115], v[52:53], v[74:75], v[114:115]
	ds_read_b128 v[72:75], v62 offset:22272
	v_add_f32_dpp v124, v124, v124 quad_perm:[1,0,3,2] row_mask:0xf bank_mask:0xf bound_ctrl:1
	v_pk_mul_f32 v[122:123], v[52:53], v[110:111]
	v_pk_fma_f32 v[122:123], v[50:51], v[108:109], v[122:123]
	ds_read_b128 v[108:111], v62 offset:20224
	v_add_f32_dpp v124, v124, v124 quad_perm:[2,3,0,1] row_mask:0xf bank_mask:0xf bound_ctrl:1
	v_pk_mul_f32 v[116:117], v[100:101], v[90:91] op_sel_hi:[1,0]
	v_pk_mul_f32 v[118:119], v[102:103], v[90:91] op_sel_hi:[1,0]
	v_add_f32_dpp v124, v124, v124 row_half_mirror row_mask:0xf bank_mask:0xf bound_ctrl:1
	v_add_f32_e32 v219, v122, v123
	ds_read_b128 v[100:103], v62 offset:24320
	ds_read_b32 v90, v63 offset:23552
	v_add_f32_dpp v124, v124, v124 row_mirror row_mask:0xf bank_mask:0xf bound_ctrl:1
	v_pk_fma_f32 v[50:51], v[80:81], v[124:125], v[112:113] op_sel_hi:[1,0,1]
	v_pk_fma_f32 v[52:53], v[82:83], v[124:125], v[114:115] op_sel_hi:[1,0,1]
	ds_read_b128 v[80:83], v62 offset:22528
	s_waitcnt lgkmcnt(6)
	v_pk_mul_f32 v[120:121], v[52:53], v[94:95]
	v_pk_fma_f32 v[120:121], v[50:51], v[92:93], v[120:121]
	ds_read_b128 v[92:95], v62 offset:23040
	v_add_f32_e32 v124, v120, v121
	v_pk_fma_f32 v[116:117], v[50:51], v[96:97], v[116:117]
	v_pk_fma_f32 v[118:119], v[52:53], v[98:99], v[118:119]
	ds_read_b128 v[96:99], v62 offset:23808
	v_add_f32_dpp v124, v124, v124 quad_perm:[1,0,3,2] row_mask:0xf bank_mask:0xf bound_ctrl:1
	v_pk_mul_f32 v[122:123], v[52:53], v[86:87]
	v_pk_fma_f32 v[122:123], v[50:51], v[84:85], v[122:123]
	ds_read_b128 v[84:87], v62 offset:21760
	v_add_f32_dpp v124, v124, v124 quad_perm:[2,3,0,1] row_mask:0xf bank_mask:0xf bound_ctrl:1
	v_pk_mul_f32 v[112:113], v[76:77], v[88:89] op_sel_hi:[1,0]
	v_pk_mul_f32 v[114:115], v[78:79], v[88:89] op_sel_hi:[1,0]
	v_add_f32_dpp v124, v124, v124 row_half_mirror row_mask:0xf bank_mask:0xf bound_ctrl:1
	v_add_f32_e32 v220, v122, v123
	s_nop 0
	v_add_f32_dpp v124, v124, v124 row_mirror row_mask:0xf bank_mask:0xf bound_ctrl:1
	v_pk_fma_f32 v[50:51], v[104:105], v[124:125], v[116:117] op_sel_hi:[1,0,1]
	v_pk_fma_f32 v[52:53], v[106:107], v[124:125], v[118:119] op_sel_hi:[1,0,1]
	ds_read_b128 v[104:107], v62 offset:24064
	s_waitcnt lgkmcnt(4)
	v_pk_mul_f32 v[120:121], v[52:53], v[70:71]
	v_pk_fma_f32 v[120:121], v[50:51], v[68:69], v[120:121]
	v_add_f32_e32 v124, v120, v121
	v_pk_fma_f32 v[112:113], v[50:51], v[72:73], v[112:113]
	v_pk_fma_f32 v[114:115], v[52:53], v[74:75], v[114:115]
	v_add_f32_dpp v124, v124, v124 quad_perm:[1,0,3,2] row_mask:0xf bank_mask:0xf bound_ctrl:1
	v_pk_mul_f32 v[122:123], v[52:53], v[110:111]
	v_pk_fma_f32 v[122:123], v[50:51], v[108:109], v[122:123]
	ds_read_b128 v[108:111], v62 offset:23296
	v_add_f32_dpp v124, v124, v124 quad_perm:[2,3,0,1] row_mask:0xf bank_mask:0xf bound_ctrl:1
	v_pk_mul_f32 v[116:117], v[100:101], v[90:91] op_sel_hi:[1,0]
	v_pk_mul_f32 v[118:119], v[102:103], v[90:91] op_sel_hi:[1,0]
	v_add_f32_dpp v124, v124, v124 row_half_mirror row_mask:0xf bank_mask:0xf bound_ctrl:1
	v_add_f32_e32 v221, v122, v123
	s_nop 0
	v_add_f32_dpp v124, v124, v124 row_mirror row_mask:0xf bank_mask:0xf bound_ctrl:1
	v_pk_fma_f32 v[50:51], v[80:81], v[124:125], v[112:113] op_sel_hi:[1,0,1]
	v_pk_fma_f32 v[52:53], v[82:83], v[124:125], v[114:115] op_sel_hi:[1,0,1]
	s_waitcnt lgkmcnt(1)
	v_pk_mul_f32 v[120:121], v[52:53], v[94:95]
	v_pk_fma_f32 v[120:121], v[50:51], v[92:93], v[120:121]
	v_add_f32_e32 v124, v120, v121
	v_pk_fma_f32 v[116:117], v[50:51], v[96:97], v[116:117]
	v_pk_fma_f32 v[118:119], v[52:53], v[98:99], v[118:119]
	v_add_f32_dpp v124, v124, v124 quad_perm:[1,0,3,2] row_mask:0xf bank_mask:0xf bound_ctrl:1
	v_pk_mul_f32 v[122:123], v[52:53], v[86:87]
	v_pk_fma_f32 v[122:123], v[50:51], v[84:85], v[122:123]
	v_add_f32_dpp v124, v124, v124 quad_perm:[2,3,0,1] row_mask:0xf bank_mask:0xf bound_ctrl:1
	s_nop 1
	v_add_f32_dpp v124, v124, v124 row_half_mirror row_mask:0xf bank_mask:0xf bound_ctrl:1
	v_add_f32_e32 v222, v122, v123
	s_nop 0
	v_add_f32_dpp v124, v124, v124 row_mirror row_mask:0xf bank_mask:0xf bound_ctrl:1
	v_pk_fma_f32 v[50:51], v[104:105], v[124:125], v[116:117] op_sel_hi:[1,0,1]
	v_pk_fma_f32 v[52:53], v[106:107], v[124:125], v[118:119] op_sel_hi:[1,0,1]
	s_waitcnt lgkmcnt(0)
	v_pk_mul_f32 v[122:123], v[52:53], v[110:111]
	v_pk_fma_f32 v[122:123], v[50:51], v[108:109], v[122:123]
	v_add_f32_e32 v223, v122, v123
	v_cndmask_b32_e64 v68, v216, v220, s[40:41]
	v_cndmask_b32_e64 v72, v220, v216, s[40:41]
	v_cndmask_b32_e64 v69, v217, v221, s[40:41]
	v_cndmask_b32_e64 v73, v221, v217, s[40:41]
	v_cndmask_b32_e64 v70, v218, v222, s[40:41]
	v_cndmask_b32_e64 v74, v222, v218, s[40:41]
	v_cndmask_b32_e64 v71, v219, v223, s[40:41]
	v_cndmask_b32_e64 v75, v223, v219, s[40:41]
	v_add_f32_dpp v68, v72, v68 row_mirror row_mask:0xf bank_mask:0xf bound_ctrl:1
	v_add_f32_dpp v69, v73, v69 row_mirror row_mask:0xf bank_mask:0xf bound_ctrl:1
	v_add_f32_dpp v70, v74, v70 row_mirror row_mask:0xf bank_mask:0xf bound_ctrl:1
	v_add_f32_dpp v71, v75, v71 row_mirror row_mask:0xf bank_mask:0xf bound_ctrl:1
	v_cndmask_b32_e64 v76, v68, v70, s[42:43]
	v_cndmask_b32_e64 v78, v70, v68, s[42:43]
	v_cndmask_b32_e64 v77, v69, v71, s[42:43]
	v_cndmask_b32_e64 v79, v71, v69, s[42:43]
	v_add_u32_e32 v128, s60, v65
	v_add_f32_dpp v76, v78, v76 row_half_mirror row_mask:0xf bank_mask:0xf bound_ctrl:1
	v_add_f32_dpp v77, v79, v77 row_half_mirror row_mask:0xf bank_mask:0xf bound_ctrl:1
	v_cndmask_b32_e64 v80, v76, v77, s[44:45]
	v_cndmask_b32_e64 v81, v77, v76, s[44:45]
	v_ashrrev_i32_e32 v129, 31, v128
	v_lshlrev_b64 v[128:129], 10, v[128:129]
	v_add_f32_dpp v80, v81, v80 quad_perm:[2,3,0,1] row_mask:0xf bank_mask:0xf bound_ctrl:1
	v_lshl_add_u64 v[128:129], v[56:57], 0, v[128:129]
	s_nop 0
	v_add_f32_dpp v127, v80, v80 quad_perm:[1,0,3,2] row_mask:0xf bank_mask:0xf bound_ctrl:1
	s_and_saveexec_b64 s[12:13], vcc
	global_store_dword v[128:129], v127, off
	s_or_b64 exec, exec, s[12:13]
	s_waitcnt lgkmcnt(0)
	s_barrier
	ds_read_b128 v[68:71], v62 offset:0
	ds_read_b128 v[76:79], v62 offset:1280
	ds_read_b32 v88, v63 offset:512
	ds_read_b128 v[72:75], v62 offset:768
	ds_read_b128 v[100:103], v62 offset:2816
	ds_read_b32 v90, v63 offset:2048
	ds_read_b128 v[80:83], v62 offset:1024
	ds_read_b128 v[92:95], v62 offset:1536
	ds_read_b128 v[84:87], v62 offset:256
	ds_read_b128 v[96:99], v62 offset:2304
	ds_read_b128 v[104:107], v62 offset:2560
	s_min_u32 s12, s20, 24
	s_add_i32 s12, s12, 7
	s_mul_i32 s12, s12, s58
	s_add_i32 s12, s12, s21
	s_mulk_i32 s12, 0x300
	s_waitcnt vmcnt(11)
	ds_write_b128 v61, v[26:29] offset:12288
	s_waitcnt vmcnt(10)
	ds_write_b128 v61, v[30:33] offset:16384
	s_waitcnt vmcnt(9)
	ds_write_b128 v61, v[34:37] offset:20480
	v_add_u32_e32 v26, s12, v58
	v_add_u32_e32 v28, s12, v59
	v_add_u32_e32 v34, s12, v60
	v_ashrrev_i32_e32 v27, 31, v26
	v_ashrrev_i32_e32 v29, 31, v28
	v_ashrrev_i32_e32 v35, 31, v34
	v_lshl_add_u64 v[26:27], v[26:27], 2, s[56:57]
	v_lshl_add_u64 v[30:31], v[28:29], 2, s[56:57]
	v_lshl_add_u64 v[34:35], v[34:35], 2, s[56:57]
	global_load_dwordx4 v[26:29], v[26:27], off
	s_nop 0
	global_load_dwordx4 v[30:33], v[30:31], off
	s_nop 0
	global_load_dwordx4 v[34:37], v[34:35], off
	s_waitcnt lgkmcnt(11)
	v_pk_mul_f32 v[112:113], v[76:77], v[88:89] op_sel_hi:[1,0]
	v_pk_mul_f32 v[114:115], v[78:79], v[88:89] op_sel_hi:[1,0]
	ds_read_b128 v[76:79], v62 offset:4352
	ds_read_b32 v88, v63 offset:3584
	s_waitcnt lgkmcnt(9)
	v_pk_mul_f32 v[120:121], v[52:53], v[70:71]
	v_pk_fma_f32 v[120:121], v[50:51], v[68:69], v[120:121]
	ds_read_b128 v[68:71], v62 offset:3072
	v_add_f32_e32 v124, v120, v121
	v_pk_fma_f32 v[112:113], v[50:51], v[72:73], v[112:113]
	v_pk_fma_f32 v[114:115], v[52:53], v[74:75], v[114:115]
	ds_read_b128 v[72:75], v62 offset:3840
	v_add_f32_dpp v124, v124, v124 quad_perm:[1,0,3,2] row_mask:0xf bank_mask:0xf bound_ctrl:1
	ds_read_b128 v[108:111], v62 offset:1792
	s_nop 0
	v_add_f32_dpp v124, v124, v124 quad_perm:[2,3,0,1] row_mask:0xf bank_mask:0xf bound_ctrl:1
	v_pk_mul_f32 v[116:117], v[100:101], v[90:91] op_sel_hi:[1,0]
	v_pk_mul_f32 v[118:119], v[102:103], v[90:91] op_sel_hi:[1,0]
	v_add_f32_dpp v124, v124, v124 row_half_mirror row_mask:0xf bank_mask:0xf bound_ctrl:1
	ds_read_b128 v[100:103], v62 offset:5888
	ds_read_b32 v90, v63 offset:5120
	v_add_f32_dpp v124, v124, v124 row_mirror row_mask:0xf bank_mask:0xf bound_ctrl:1
	v_pk_fma_f32 v[50:51], v[80:81], v[124:125], v[112:113] op_sel_hi:[1,0,1]
	v_pk_fma_f32 v[52:53], v[82:83], v[124:125], v[114:115] op_sel_hi:[1,0,1]
	ds_read_b128 v[80:83], v62 offset:4096
	s_waitcnt lgkmcnt(6)
	v_pk_mul_f32 v[120:121], v[52:53], v[94:95]
	v_pk_fma_f32 v[120:121], v[50:51], v[92:93], v[120:121]
	ds_read_b128 v[92:95], v62 offset:4608
	v_add_f32_e32 v124, v120, v121
	v_pk_fma_f32 v[116:117], v[50:51], v[96:97], v[116:117]
	v_pk_fma_f32 v[118:119], v[52:53], v[98:99], v[118:119]
	ds_read_b128 v[96:99], v62 offset:5376
	v_add_f32_dpp v124, v124, v124 quad_perm:[1,0,3,2] row_mask:0xf bank_mask:0xf bound_ctrl:1
	v_pk_mul_f32 v[122:123], v[52:53], v[86:87]
	v_pk_fma_f32 v[122:123], v[50:51], v[84:85], v[122:123]
	ds_read_b128 v[84:87], v62 offset:3328
	v_add_f32_dpp v124, v124, v124 quad_perm:[2,3,0,1] row_mask:0xf bank_mask:0xf bound_ctrl:1
	v_pk_mul_f32 v[112:113], v[76:77], v[88:89] op_sel_hi:[1,0]
	v_pk_mul_f32 v[114:115], v[78:79], v[88:89] op_sel_hi:[1,0]
	v_add_f32_dpp v124, v124, v124 row_half_mirror row_mask:0xf bank_mask:0xf bound_ctrl:1
	v_add_f32_e32 v216, v122, v123
	ds_read_b128 v[76:79], v62 offset:7424
	ds_read_b32 v88, v63 offset:6656
	v_add_f32_dpp v124, v124, v124 row_mirror row_mask:0xf bank_mask:0xf bound_ctrl:1
	v_pk_fma_f32 v[50:51], v[104:105], v[124:125], v[116:117] op_sel_hi:[1,0,1]
	v_pk_fma_f32 v[52:53], v[106:107], v[124:125], v[118:119] op_sel_hi:[1,0,1]
	ds_read_b128 v[104:107], v62 offset:5632
	s_waitcnt lgkmcnt(6)
	v_pk_mul_f32 v[120:121], v[52:53], v[70:71]
	v_pk_fma_f32 v[120:121], v[50:51], v[68:69], v[120:121]
	ds_read_b128 v[68:71], v62 offset:6144
	v_add_f32_e32 v124, v120, v121
	v_pk_fma_f32 v[112:113], v[50:51], v[72:73], v[112:113]
	v_pk_fma_f32 v[114:115], v[52:53], v[74:75], v[114:115]
	ds_read_b128 v[72:75], v62 offset:6912
	v_add_f32_dpp v124, v124, v124 quad_perm:[1,0,3,2] row_mask:0xf bank_mask:0xf bound_ctrl:1
	v_pk_mul_f32 v[122:123], v[52:53], v[110:111]
	v_pk_fma_f32 v[122:123], v[50:51], v[108:109], v[122:123]
	ds_read_b128 v[108:111], v62 offset:4864
	v_add_f32_dpp v124, v124, v124 quad_perm:[2,3,0,1] row_mask:0xf bank_mask:0xf bound_ctrl:1
	v_pk_mul_f32 v[116:117], v[100:101], v[90:91] op_sel_hi:[1,0]
	v_pk_mul_f32 v[118:119], v[102:103], v[90:91] op_sel_hi:[1,0]
	v_add_f32_dpp v124, v124, v124 row_half_mirror row_mask:0xf bank_mask:0xf bound_ctrl:1
	v_add_f32_e32 v217, v122, v123
	ds_read_b128 v[100:103], v62 offset:8960
	ds_read_b32 v90, v63 offset:8192
	v_add_f32_dpp v124, v124, v124 row_mirror row_mask:0xf bank_mask:0xf bound_ctrl:1
	v_pk_fma_f32 v[50:51], v[80:81], v[124:125], v[112:113] op_sel_hi:[1,0,1]
	v_pk_fma_f32 v[52:53], v[82:83], v[124:125], v[114:115] op_sel_hi:[1,0,1]
	ds_read_b128 v[80:83], v62 offset:7168
	s_waitcnt lgkmcnt(6)
	v_pk_mul_f32 v[120:121], v[52:53], v[94:95]
	v_pk_fma_f32 v[120:121], v[50:51], v[92:93], v[120:121]
	ds_read_b128 v[92:95], v62 offset:7680
	v_add_f32_e32 v124, v120, v121
	v_pk_fma_f32 v[116:117], v[50:51], v[96:97], v[116:117]
	v_pk_fma_f32 v[118:119], v[52:53], v[98:99], v[118:119]
	ds_read_b128 v[96:99], v62 offset:8448
	v_add_f32_dpp v124, v124, v124 quad_perm:[1,0,3,2] row_mask:0xf bank_mask:0xf bound_ctrl:1
	v_pk_mul_f32 v[122:123], v[52:53], v[86:87]
	v_pk_fma_f32 v[122:123], v[50:51], v[84:85], v[122:123]
	ds_read_b128 v[84:87], v62 offset:6400
	v_add_f32_dpp v124, v124, v124 quad_perm:[2,3,0,1] row_mask:0xf bank_mask:0xf bound_ctrl:1
	v_pk_mul_f32 v[112:113], v[76:77], v[88:89] op_sel_hi:[1,0]
	v_pk_mul_f32 v[114:115], v[78:79], v[88:89] op_sel_hi:[1,0]
	v_add_f32_dpp v124, v124, v124 row_half_mirror row_mask:0xf bank_mask:0xf bound_ctrl:1
	v_add_f32_e32 v218, v122, v123
	ds_read_b128 v[76:79], v62 offset:10496
	ds_read_b32 v88, v63 offset:9728
	v_add_f32_dpp v124, v124, v124 row_mirror row_mask:0xf bank_mask:0xf bound_ctrl:1
	v_pk_fma_f32 v[50:51], v[104:105], v[124:125], v[116:117] op_sel_hi:[1,0,1]
	v_pk_fma_f32 v[52:53], v[106:107], v[124:125], v[118:119] op_sel_hi:[1,0,1]
	ds_read_b128 v[104:107], v62 offset:8704
	s_waitcnt lgkmcnt(6)
	v_pk_mul_f32 v[120:121], v[52:53], v[70:71]
	v_pk_fma_f32 v[120:121], v[50:51], v[68:69], v[120:121]
	ds_read_b128 v[68:71], v62 offset:9216
	v_add_f32_e32 v124, v120, v121
	v_pk_fma_f32 v[112:113], v[50:51], v[72:73], v[112:113]
	v_pk_fma_f32 v[114:115], v[52:53], v[74:75], v[114:115]
	ds_read_b128 v[72:75], v62 offset:9984
	v_add_f32_dpp v124, v124, v124 quad_perm:[1,0,3,2] row_mask:0xf bank_mask:0xf bound_ctrl:1
	v_pk_mul_f32 v[122:123], v[52:53], v[110:111]
	v_pk_fma_f32 v[122:123], v[50:51], v[108:109], v[122:123]
	ds_read_b128 v[108:111], v62 offset:7936
	v_add_f32_dpp v124, v124, v124 quad_perm:[2,3,0,1] row_mask:0xf bank_mask:0xf bound_ctrl:1
	v_pk_mul_f32 v[116:117], v[100:101], v[90:91] op_sel_hi:[1,0]
	v_pk_mul_f32 v[118:119], v[102:103], v[90:91] op_sel_hi:[1,0]
	v_add_f32_dpp v124, v124, v124 row_half_mirror row_mask:0xf bank_mask:0xf bound_ctrl:1
	v_add_f32_e32 v219, v122, v123
	ds_read_b128 v[100:103], v62 offset:12032
	ds_read_b32 v90, v63 offset:11264
	v_add_f32_dpp v124, v124, v124 row_mirror row_mask:0xf bank_mask:0xf bound_ctrl:1
	v_pk_fma_f32 v[50:51], v[80:81], v[124:125], v[112:113] op_sel_hi:[1,0,1]
	v_pk_fma_f32 v[52:53], v[82:83], v[124:125], v[114:115] op_sel_hi:[1,0,1]
	ds_read_b128 v[80:83], v62 offset:10240
	s_waitcnt lgkmcnt(6)
	v_pk_mul_f32 v[120:121], v[52:53], v[94:95]
	v_pk_fma_f32 v[120:121], v[50:51], v[92:93], v[120:121]
	ds_read_b128 v[92:95], v62 offset:10752
	v_add_f32_e32 v124, v120, v121
	v_pk_fma_f32 v[116:117], v[50:51], v[96:97], v[116:117]
	v_pk_fma_f32 v[118:119], v[52:53], v[98:99], v[118:119]
	ds_read_b128 v[96:99], v62 offset:11520
	v_add_f32_dpp v124, v124, v124 quad_perm:[1,0,3,2] row_mask:0xf bank_mask:0xf bound_ctrl:1
	v_pk_mul_f32 v[122:123], v[52:53], v[86:87]
	v_pk_fma_f32 v[122:123], v[50:51], v[84:85], v[122:123]
	ds_read_b128 v[84:87], v62 offset:9472
	v_add_f32_dpp v124, v124, v124 quad_perm:[2,3,0,1] row_mask:0xf bank_mask:0xf bound_ctrl:1
	v_pk_mul_f32 v[112:113], v[76:77], v[88:89] op_sel_hi:[1,0]
	v_pk_mul_f32 v[114:115], v[78:79], v[88:89] op_sel_hi:[1,0]
	v_add_f32_dpp v124, v124, v124 row_half_mirror row_mask:0xf bank_mask:0xf bound_ctrl:1
	v_add_f32_e32 v220, v122, v123
	s_nop 0
	v_add_f32_dpp v124, v124, v124 row_mirror row_mask:0xf bank_mask:0xf bound_ctrl:1
	v_pk_fma_f32 v[50:51], v[104:105], v[124:125], v[116:117] op_sel_hi:[1,0,1]
	v_pk_fma_f32 v[52:53], v[106:107], v[124:125], v[118:119] op_sel_hi:[1,0,1]
	ds_read_b128 v[104:107], v62 offset:11776
	s_waitcnt lgkmcnt(4)
	v_pk_mul_f32 v[120:121], v[52:53], v[70:71]
	v_pk_fma_f32 v[120:121], v[50:51], v[68:69], v[120:121]
	v_add_f32_e32 v124, v120, v121
	v_pk_fma_f32 v[112:113], v[50:51], v[72:73], v[112:113]
	v_pk_fma_f32 v[114:115], v[52:53], v[74:75], v[114:115]
	v_add_f32_dpp v124, v124, v124 quad_perm:[1,0,3,2] row_mask:0xf bank_mask:0xf bound_ctrl:1
	v_pk_mul_f32 v[122:123], v[52:53], v[110:111]
	v_pk_fma_f32 v[122:123], v[50:51], v[108:109], v[122:123]
	ds_read_b128 v[108:111], v62 offset:11008
	v_add_f32_dpp v124, v124, v124 quad_perm:[2,3,0,1] row_mask:0xf bank_mask:0xf bound_ctrl:1
	v_pk_mul_f32 v[116:117], v[100:101], v[90:91] op_sel_hi:[1,0]
	v_pk_mul_f32 v[118:119], v[102:103], v[90:91] op_sel_hi:[1,0]
	v_add_f32_dpp v124, v124, v124 row_half_mirror row_mask:0xf bank_mask:0xf bound_ctrl:1
	v_add_f32_e32 v221, v122, v123
	s_nop 0
	v_add_f32_dpp v124, v124, v124 row_mirror row_mask:0xf bank_mask:0xf bound_ctrl:1
	v_pk_fma_f32 v[50:51], v[80:81], v[124:125], v[112:113] op_sel_hi:[1,0,1]
	v_pk_fma_f32 v[52:53], v[82:83], v[124:125], v[114:115] op_sel_hi:[1,0,1]
	s_waitcnt lgkmcnt(1)
	v_pk_mul_f32 v[120:121], v[52:53], v[94:95]
	v_pk_fma_f32 v[120:121], v[50:51], v[92:93], v[120:121]
	v_add_f32_e32 v124, v120, v121
	v_pk_fma_f32 v[116:117], v[50:51], v[96:97], v[116:117]
	v_pk_fma_f32 v[118:119], v[52:53], v[98:99], v[118:119]
	v_add_f32_dpp v124, v124, v124 quad_perm:[1,0,3,2] row_mask:0xf bank_mask:0xf bound_ctrl:1
	v_pk_mul_f32 v[122:123], v[52:53], v[86:87]
	v_pk_fma_f32 v[122:123], v[50:51], v[84:85], v[122:123]
	v_add_f32_dpp v124, v124, v124 quad_perm:[2,3,0,1] row_mask:0xf bank_mask:0xf bound_ctrl:1
	s_nop 1
	v_add_f32_dpp v124, v124, v124 row_half_mirror row_mask:0xf bank_mask:0xf bound_ctrl:1
	v_add_f32_e32 v222, v122, v123
	s_nop 0
	v_add_f32_dpp v124, v124, v124 row_mirror row_mask:0xf bank_mask:0xf bound_ctrl:1
	v_pk_fma_f32 v[50:51], v[104:105], v[124:125], v[116:117] op_sel_hi:[1,0,1]
	v_pk_fma_f32 v[52:53], v[106:107], v[124:125], v[118:119] op_sel_hi:[1,0,1]
	s_waitcnt lgkmcnt(0)
	v_pk_mul_f32 v[122:123], v[52:53], v[110:111]
	v_pk_fma_f32 v[122:123], v[50:51], v[108:109], v[122:123]
	v_add_f32_e32 v223, v122, v123
	v_cndmask_b32_e64 v68, v216, v220, s[40:41]
	v_cndmask_b32_e64 v72, v220, v216, s[40:41]
	v_cndmask_b32_e64 v69, v217, v221, s[40:41]
	v_cndmask_b32_e64 v73, v221, v217, s[40:41]
	v_cndmask_b32_e64 v70, v218, v222, s[40:41]
	v_cndmask_b32_e64 v74, v222, v218, s[40:41]
	v_cndmask_b32_e64 v71, v219, v223, s[40:41]
	v_cndmask_b32_e64 v75, v223, v219, s[40:41]
	v_add_f32_dpp v68, v72, v68 row_mirror row_mask:0xf bank_mask:0xf bound_ctrl:1
	v_add_f32_dpp v69, v73, v69 row_mirror row_mask:0xf bank_mask:0xf bound_ctrl:1
	v_add_f32_dpp v70, v74, v70 row_mirror row_mask:0xf bank_mask:0xf bound_ctrl:1
	v_add_f32_dpp v71, v75, v71 row_mirror row_mask:0xf bank_mask:0xf bound_ctrl:1
	v_cndmask_b32_e64 v76, v68, v70, s[42:43]
	v_cndmask_b32_e64 v78, v70, v68, s[42:43]
	v_cndmask_b32_e64 v77, v69, v71, s[42:43]
	v_cndmask_b32_e64 v79, v71, v69, s[42:43]
	v_add_u32_e32 v128, s60, v66
	v_add_f32_dpp v76, v78, v76 row_half_mirror row_mask:0xf bank_mask:0xf bound_ctrl:1
	v_add_f32_dpp v77, v79, v77 row_half_mirror row_mask:0xf bank_mask:0xf bound_ctrl:1
	v_cndmask_b32_e64 v80, v76, v77, s[44:45]
	v_cndmask_b32_e64 v81, v77, v76, s[44:45]
	v_ashrrev_i32_e32 v129, 31, v128
	v_lshlrev_b64 v[128:129], 10, v[128:129]
	v_add_f32_dpp v80, v81, v80 quad_perm:[2,3,0,1] row_mask:0xf bank_mask:0xf bound_ctrl:1
	v_lshl_add_u64 v[128:129], v[56:57], 0, v[128:129]
	s_nop 0
	v_add_f32_dpp v127, v80, v80 quad_perm:[1,0,3,2] row_mask:0xf bank_mask:0xf bound_ctrl:1
	s_and_saveexec_b64 s[12:13], vcc
	global_store_dword v[128:129], v127, off
	s_or_b64 exec, exec, s[12:13]
	s_waitcnt lgkmcnt(0)
	s_barrier
	ds_read_b128 v[68:71], v62 offset:12288
	ds_read_b128 v[76:79], v62 offset:13568
	ds_read_b32 v88, v63 offset:12800
	ds_read_b128 v[72:75], v62 offset:13056
	ds_read_b128 v[100:103], v62 offset:15104
	ds_read_b32 v90, v63 offset:14336
	ds_read_b128 v[80:83], v62 offset:13312
	ds_read_b128 v[92:95], v62 offset:13824
	ds_read_b128 v[84:87], v62 offset:12544
	ds_read_b128 v[96:99], v62 offset:14592
	ds_read_b128 v[104:107], v62 offset:14848
	s_min_u32 s12, s20, 23
	s_add_i32 s12, s12, 8
	s_mul_i32 s12, s12, s58
	s_add_i32 s12, s12, s21
	s_mulk_i32 s12, 0x300
	s_waitcnt vmcnt(11)
	ds_write_b128 v61, v[38:41]
	s_waitcnt vmcnt(10)
	ds_write_b128 v61, v[42:45] offset:4096
	s_waitcnt vmcnt(9)
	ds_write_b128 v61, v[46:49] offset:8192
	v_add_u32_e32 v38, s12, v58
	v_add_u32_e32 v40, s12, v59
	v_add_u32_e32 v46, s12, v60
	v_ashrrev_i32_e32 v39, 31, v38
	v_ashrrev_i32_e32 v41, 31, v40
	v_ashrrev_i32_e32 v47, 31, v46
	v_lshl_add_u64 v[38:39], v[38:39], 2, s[56:57]
	v_lshl_add_u64 v[42:43], v[40:41], 2, s[56:57]
	v_lshl_add_u64 v[46:47], v[46:47], 2, s[56:57]
	global_load_dwordx4 v[38:41], v[38:39], off
	s_nop 0
	global_load_dwordx4 v[42:45], v[42:43], off
	s_nop 0
	global_load_dwordx4 v[46:49], v[46:47], off
	s_waitcnt lgkmcnt(11)
	v_pk_mul_f32 v[112:113], v[76:77], v[88:89] op_sel_hi:[1,0]
	v_pk_mul_f32 v[114:115], v[78:79], v[88:89] op_sel_hi:[1,0]
	ds_read_b128 v[76:79], v62 offset:16640
	ds_read_b32 v88, v63 offset:15872
	s_waitcnt lgkmcnt(9)
	v_pk_mul_f32 v[120:121], v[52:53], v[70:71]
	v_pk_fma_f32 v[120:121], v[50:51], v[68:69], v[120:121]
	ds_read_b128 v[68:71], v62 offset:15360
	v_add_f32_e32 v124, v120, v121
	v_pk_fma_f32 v[112:113], v[50:51], v[72:73], v[112:113]
	v_pk_fma_f32 v[114:115], v[52:53], v[74:75], v[114:115]
	ds_read_b128 v[72:75], v62 offset:16128
	v_add_f32_dpp v124, v124, v124 quad_perm:[1,0,3,2] row_mask:0xf bank_mask:0xf bound_ctrl:1
	ds_read_b128 v[108:111], v62 offset:14080
	s_nop 0
	v_add_f32_dpp v124, v124, v124 quad_perm:[2,3,0,1] row_mask:0xf bank_mask:0xf bound_ctrl:1
	v_pk_mul_f32 v[116:117], v[100:101], v[90:91] op_sel_hi:[1,0]
	v_pk_mul_f32 v[118:119], v[102:103], v[90:91] op_sel_hi:[1,0]
	v_add_f32_dpp v124, v124, v124 row_half_mirror row_mask:0xf bank_mask:0xf bound_ctrl:1
	ds_read_b128 v[100:103], v62 offset:18176
	ds_read_b32 v90, v63 offset:17408
	v_add_f32_dpp v124, v124, v124 row_mirror row_mask:0xf bank_mask:0xf bound_ctrl:1
	v_pk_fma_f32 v[50:51], v[80:81], v[124:125], v[112:113] op_sel_hi:[1,0,1]
	v_pk_fma_f32 v[52:53], v[82:83], v[124:125], v[114:115] op_sel_hi:[1,0,1]
	ds_read_b128 v[80:83], v62 offset:16384
	s_waitcnt lgkmcnt(6)
	v_pk_mul_f32 v[120:121], v[52:53], v[94:95]
	v_pk_fma_f32 v[120:121], v[50:51], v[92:93], v[120:121]
	ds_read_b128 v[92:95], v62 offset:16896
	v_add_f32_e32 v124, v120, v121
	v_pk_fma_f32 v[116:117], v[50:51], v[96:97], v[116:117]
	v_pk_fma_f32 v[118:119], v[52:53], v[98:99], v[118:119]
	ds_read_b128 v[96:99], v62 offset:17664
	v_add_f32_dpp v124, v124, v124 quad_perm:[1,0,3,2] row_mask:0xf bank_mask:0xf bound_ctrl:1
	v_pk_mul_f32 v[122:123], v[52:53], v[86:87]
	v_pk_fma_f32 v[122:123], v[50:51], v[84:85], v[122:123]
	ds_read_b128 v[84:87], v62 offset:15616
	v_add_f32_dpp v124, v124, v124 quad_perm:[2,3,0,1] row_mask:0xf bank_mask:0xf bound_ctrl:1
	v_pk_mul_f32 v[112:113], v[76:77], v[88:89] op_sel_hi:[1,0]
	v_pk_mul_f32 v[114:115], v[78:79], v[88:89] op_sel_hi:[1,0]
	v_add_f32_dpp v124, v124, v124 row_half_mirror row_mask:0xf bank_mask:0xf bound_ctrl:1
	v_add_f32_e32 v216, v122, v123
	ds_read_b128 v[76:79], v62 offset:19712
	ds_read_b32 v88, v63 offset:18944
	v_add_f32_dpp v124, v124, v124 row_mirror row_mask:0xf bank_mask:0xf bound_ctrl:1
	v_pk_fma_f32 v[50:51], v[104:105], v[124:125], v[116:117] op_sel_hi:[1,0,1]
	v_pk_fma_f32 v[52:53], v[106:107], v[124:125], v[118:119] op_sel_hi:[1,0,1]
	ds_read_b128 v[104:107], v62 offset:17920
	s_waitcnt lgkmcnt(6)
	v_pk_mul_f32 v[120:121], v[52:53], v[70:71]
	v_pk_fma_f32 v[120:121], v[50:51], v[68:69], v[120:121]
	ds_read_b128 v[68:71], v62 offset:18432
	v_add_f32_e32 v124, v120, v121
	v_pk_fma_f32 v[112:113], v[50:51], v[72:73], v[112:113]
	v_pk_fma_f32 v[114:115], v[52:53], v[74:75], v[114:115]
	ds_read_b128 v[72:75], v62 offset:19200
	v_add_f32_dpp v124, v124, v124 quad_perm:[1,0,3,2] row_mask:0xf bank_mask:0xf bound_ctrl:1
	v_pk_mul_f32 v[122:123], v[52:53], v[110:111]
	v_pk_fma_f32 v[122:123], v[50:51], v[108:109], v[122:123]
	ds_read_b128 v[108:111], v62 offset:17152
	v_add_f32_dpp v124, v124, v124 quad_perm:[2,3,0,1] row_mask:0xf bank_mask:0xf bound_ctrl:1
	v_pk_mul_f32 v[116:117], v[100:101], v[90:91] op_sel_hi:[1,0]
	v_pk_mul_f32 v[118:119], v[102:103], v[90:91] op_sel_hi:[1,0]
	v_add_f32_dpp v124, v124, v124 row_half_mirror row_mask:0xf bank_mask:0xf bound_ctrl:1
	v_add_f32_e32 v217, v122, v123
	ds_read_b128 v[100:103], v62 offset:21248
	ds_read_b32 v90, v63 offset:20480
	v_add_f32_dpp v124, v124, v124 row_mirror row_mask:0xf bank_mask:0xf bound_ctrl:1
	v_pk_fma_f32 v[50:51], v[80:81], v[124:125], v[112:113] op_sel_hi:[1,0,1]
	v_pk_fma_f32 v[52:53], v[82:83], v[124:125], v[114:115] op_sel_hi:[1,0,1]
	ds_read_b128 v[80:83], v62 offset:19456
	s_waitcnt lgkmcnt(6)
	v_pk_mul_f32 v[120:121], v[52:53], v[94:95]
	v_pk_fma_f32 v[120:121], v[50:51], v[92:93], v[120:121]
	ds_read_b128 v[92:95], v62 offset:19968
	v_add_f32_e32 v124, v120, v121
	v_pk_fma_f32 v[116:117], v[50:51], v[96:97], v[116:117]
	v_pk_fma_f32 v[118:119], v[52:53], v[98:99], v[118:119]
	ds_read_b128 v[96:99], v62 offset:20736
	v_add_f32_dpp v124, v124, v124 quad_perm:[1,0,3,2] row_mask:0xf bank_mask:0xf bound_ctrl:1
	v_pk_mul_f32 v[122:123], v[52:53], v[86:87]
	v_pk_fma_f32 v[122:123], v[50:51], v[84:85], v[122:123]
	ds_read_b128 v[84:87], v62 offset:18688
	v_add_f32_dpp v124, v124, v124 quad_perm:[2,3,0,1] row_mask:0xf bank_mask:0xf bound_ctrl:1
	v_pk_mul_f32 v[112:113], v[76:77], v[88:89] op_sel_hi:[1,0]
	v_pk_mul_f32 v[114:115], v[78:79], v[88:89] op_sel_hi:[1,0]
	v_add_f32_dpp v124, v124, v124 row_half_mirror row_mask:0xf bank_mask:0xf bound_ctrl:1
	v_add_f32_e32 v218, v122, v123
	ds_read_b128 v[76:79], v62 offset:22784
	ds_read_b32 v88, v63 offset:22016
	v_add_f32_dpp v124, v124, v124 row_mirror row_mask:0xf bank_mask:0xf bound_ctrl:1
	v_pk_fma_f32 v[50:51], v[104:105], v[124:125], v[116:117] op_sel_hi:[1,0,1]
	v_pk_fma_f32 v[52:53], v[106:107], v[124:125], v[118:119] op_sel_hi:[1,0,1]
	ds_read_b128 v[104:107], v62 offset:20992
	s_waitcnt lgkmcnt(6)
	v_pk_mul_f32 v[120:121], v[52:53], v[70:71]
	v_pk_fma_f32 v[120:121], v[50:51], v[68:69], v[120:121]
	ds_read_b128 v[68:71], v62 offset:21504
	v_add_f32_e32 v124, v120, v121
	v_pk_fma_f32 v[112:113], v[50:51], v[72:73], v[112:113]
	v_pk_fma_f32 v[114:115], v[52:53], v[74:75], v[114:115]
	ds_read_b128 v[72:75], v62 offset:22272
	v_add_f32_dpp v124, v124, v124 quad_perm:[1,0,3,2] row_mask:0xf bank_mask:0xf bound_ctrl:1
	v_pk_mul_f32 v[122:123], v[52:53], v[110:111]
	v_pk_fma_f32 v[122:123], v[50:51], v[108:109], v[122:123]
	ds_read_b128 v[108:111], v62 offset:20224
	v_add_f32_dpp v124, v124, v124 quad_perm:[2,3,0,1] row_mask:0xf bank_mask:0xf bound_ctrl:1
	v_pk_mul_f32 v[116:117], v[100:101], v[90:91] op_sel_hi:[1,0]
	v_pk_mul_f32 v[118:119], v[102:103], v[90:91] op_sel_hi:[1,0]
	v_add_f32_dpp v124, v124, v124 row_half_mirror row_mask:0xf bank_mask:0xf bound_ctrl:1
	v_add_f32_e32 v219, v122, v123
	ds_read_b128 v[100:103], v62 offset:24320
	ds_read_b32 v90, v63 offset:23552
	v_add_f32_dpp v124, v124, v124 row_mirror row_mask:0xf bank_mask:0xf bound_ctrl:1
	v_pk_fma_f32 v[50:51], v[80:81], v[124:125], v[112:113] op_sel_hi:[1,0,1]
	v_pk_fma_f32 v[52:53], v[82:83], v[124:125], v[114:115] op_sel_hi:[1,0,1]
	ds_read_b128 v[80:83], v62 offset:22528
	s_waitcnt lgkmcnt(6)
	v_pk_mul_f32 v[120:121], v[52:53], v[94:95]
	v_pk_fma_f32 v[120:121], v[50:51], v[92:93], v[120:121]
	ds_read_b128 v[92:95], v62 offset:23040
	v_add_f32_e32 v124, v120, v121
	v_pk_fma_f32 v[116:117], v[50:51], v[96:97], v[116:117]
	v_pk_fma_f32 v[118:119], v[52:53], v[98:99], v[118:119]
	ds_read_b128 v[96:99], v62 offset:23808
	v_add_f32_dpp v124, v124, v124 quad_perm:[1,0,3,2] row_mask:0xf bank_mask:0xf bound_ctrl:1
	v_pk_mul_f32 v[122:123], v[52:53], v[86:87]
	v_pk_fma_f32 v[122:123], v[50:51], v[84:85], v[122:123]
	ds_read_b128 v[84:87], v62 offset:21760
	v_add_f32_dpp v124, v124, v124 quad_perm:[2,3,0,1] row_mask:0xf bank_mask:0xf bound_ctrl:1
	v_pk_mul_f32 v[112:113], v[76:77], v[88:89] op_sel_hi:[1,0]
	v_pk_mul_f32 v[114:115], v[78:79], v[88:89] op_sel_hi:[1,0]
	v_add_f32_dpp v124, v124, v124 row_half_mirror row_mask:0xf bank_mask:0xf bound_ctrl:1
	v_add_f32_e32 v220, v122, v123
	s_nop 0
	v_add_f32_dpp v124, v124, v124 row_mirror row_mask:0xf bank_mask:0xf bound_ctrl:1
	v_pk_fma_f32 v[50:51], v[104:105], v[124:125], v[116:117] op_sel_hi:[1,0,1]
	v_pk_fma_f32 v[52:53], v[106:107], v[124:125], v[118:119] op_sel_hi:[1,0,1]
	ds_read_b128 v[104:107], v62 offset:24064
	s_waitcnt lgkmcnt(4)
	v_pk_mul_f32 v[120:121], v[52:53], v[70:71]
	v_pk_fma_f32 v[120:121], v[50:51], v[68:69], v[120:121]
	v_add_f32_e32 v124, v120, v121
	v_pk_fma_f32 v[112:113], v[50:51], v[72:73], v[112:113]
	v_pk_fma_f32 v[114:115], v[52:53], v[74:75], v[114:115]
	v_add_f32_dpp v124, v124, v124 quad_perm:[1,0,3,2] row_mask:0xf bank_mask:0xf bound_ctrl:1
	v_pk_mul_f32 v[122:123], v[52:53], v[110:111]
	v_pk_fma_f32 v[122:123], v[50:51], v[108:109], v[122:123]
	ds_read_b128 v[108:111], v62 offset:23296
	v_add_f32_dpp v124, v124, v124 quad_perm:[2,3,0,1] row_mask:0xf bank_mask:0xf bound_ctrl:1
	v_pk_mul_f32 v[116:117], v[100:101], v[90:91] op_sel_hi:[1,0]
	v_pk_mul_f32 v[118:119], v[102:103], v[90:91] op_sel_hi:[1,0]
	v_add_f32_dpp v124, v124, v124 row_half_mirror row_mask:0xf bank_mask:0xf bound_ctrl:1
	v_add_f32_e32 v221, v122, v123
	s_nop 0
	v_add_f32_dpp v124, v124, v124 row_mirror row_mask:0xf bank_mask:0xf bound_ctrl:1
	v_pk_fma_f32 v[50:51], v[80:81], v[124:125], v[112:113] op_sel_hi:[1,0,1]
	v_pk_fma_f32 v[52:53], v[82:83], v[124:125], v[114:115] op_sel_hi:[1,0,1]
	s_waitcnt lgkmcnt(1)
	v_pk_mul_f32 v[120:121], v[52:53], v[94:95]
	v_pk_fma_f32 v[120:121], v[50:51], v[92:93], v[120:121]
	v_add_f32_e32 v124, v120, v121
	v_pk_fma_f32 v[116:117], v[50:51], v[96:97], v[116:117]
	v_pk_fma_f32 v[118:119], v[52:53], v[98:99], v[118:119]
	v_add_f32_dpp v124, v124, v124 quad_perm:[1,0,3,2] row_mask:0xf bank_mask:0xf bound_ctrl:1
	v_pk_mul_f32 v[122:123], v[52:53], v[86:87]
	v_pk_fma_f32 v[122:123], v[50:51], v[84:85], v[122:123]
	v_add_f32_dpp v124, v124, v124 quad_perm:[2,3,0,1] row_mask:0xf bank_mask:0xf bound_ctrl:1
	s_nop 1
	v_add_f32_dpp v124, v124, v124 row_half_mirror row_mask:0xf bank_mask:0xf bound_ctrl:1
	v_add_f32_e32 v222, v122, v123
	s_nop 0
	v_add_f32_dpp v124, v124, v124 row_mirror row_mask:0xf bank_mask:0xf bound_ctrl:1
	v_pk_fma_f32 v[50:51], v[104:105], v[124:125], v[116:117] op_sel_hi:[1,0,1]
	v_pk_fma_f32 v[52:53], v[106:107], v[124:125], v[118:119] op_sel_hi:[1,0,1]
	s_waitcnt lgkmcnt(0)
	v_pk_mul_f32 v[122:123], v[52:53], v[110:111]
	v_pk_fma_f32 v[122:123], v[50:51], v[108:109], v[122:123]
	v_add_f32_e32 v223, v122, v123
	v_cndmask_b32_e64 v68, v216, v220, s[40:41]
	v_cndmask_b32_e64 v72, v220, v216, s[40:41]
	v_cndmask_b32_e64 v69, v217, v221, s[40:41]
	v_cndmask_b32_e64 v73, v221, v217, s[40:41]
	v_cndmask_b32_e64 v70, v218, v222, s[40:41]
	v_cndmask_b32_e64 v74, v222, v218, s[40:41]
	v_cndmask_b32_e64 v71, v219, v223, s[40:41]
	v_cndmask_b32_e64 v75, v223, v219, s[40:41]
	v_add_f32_dpp v68, v72, v68 row_mirror row_mask:0xf bank_mask:0xf bound_ctrl:1
	v_add_f32_dpp v69, v73, v69 row_mirror row_mask:0xf bank_mask:0xf bound_ctrl:1
	v_add_f32_dpp v70, v74, v70 row_mirror row_mask:0xf bank_mask:0xf bound_ctrl:1
	v_add_f32_dpp v71, v75, v71 row_mirror row_mask:0xf bank_mask:0xf bound_ctrl:1
	v_cndmask_b32_e64 v76, v68, v70, s[42:43]
	v_cndmask_b32_e64 v78, v70, v68, s[42:43]
	v_cndmask_b32_e64 v77, v69, v71, s[42:43]
	v_cndmask_b32_e64 v79, v71, v69, s[42:43]
	v_add_u32_e32 v128, s60, v67
	v_add_f32_dpp v76, v78, v76 row_half_mirror row_mask:0xf bank_mask:0xf bound_ctrl:1
	v_add_f32_dpp v77, v79, v77 row_half_mirror row_mask:0xf bank_mask:0xf bound_ctrl:1
	v_cndmask_b32_e64 v80, v76, v77, s[44:45]
	v_cndmask_b32_e64 v81, v77, v76, s[44:45]
	v_ashrrev_i32_e32 v129, 31, v128
	v_lshlrev_b64 v[128:129], 10, v[128:129]
	v_add_f32_dpp v80, v81, v80 quad_perm:[2,3,0,1] row_mask:0xf bank_mask:0xf bound_ctrl:1
	v_lshl_add_u64 v[128:129], v[56:57], 0, v[128:129]
	s_nop 0
	v_add_f32_dpp v127, v80, v80 quad_perm:[1,0,3,2] row_mask:0xf bank_mask:0xf bound_ctrl:1
	s_and_saveexec_b64 s[12:13], vcc
	global_store_dword v[128:129], v127, off
	s_or_b64 exec, exec, s[12:13]
	s_add_i32 s60, s60, s59
	s_cmp_lt_u32 s20, 28
	s_waitcnt lgkmcnt(0)
	s_barrier
	s_cbranch_scc1 .LBB0_216
	s_branch .LBB0_213

.LBB0_276:
	s_and_b64 vcc, exec, s[2:3]
	s_cbranch_vccz .LBB0_288
	s_setprio 3
	s_waitcnt vmcnt(8)
	v_mov_b32_e32 v14, v131
	v_readlane_b32 s14, v224, 34
	s_waitcnt lgkmcnt(0)
	v_ashrrev_i32_e32 v2, 4, v14
	v_and_b32_e32 v2, -4, v2
	v_readlane_b32 s2, v226, 15
	v_readlane_b32 s15, v224, 35
	v_readlane_b32 s7, v226, 16
	v_add_u32_e32 v2, s2, v2
	s_load_dwordx2 s[2:3], s[14:15], 0x20
	s_load_dwordx4 s[56:59], s[14:15], 0x1c8
	s_add_i32 s8, s38, s7
	s_ashr_i32 s9, s8, 31
	s_lshl_b64 s[8:9], s[8:9], 17
	v_lshrrev_b32_e32 v0, 4, v14
	s_waitcnt lgkmcnt(0)
	s_add_u32 s2, s2, s8
	v_and_or_b32 v56, v0, 3, v2
	s_addc_u32 s3, s3, s9
	v_readlane_b32 s7, v225, 19
	v_ashrrev_i32_e32 v57, 31, v56
	s_add_u32 s2, s2, s7
	v_and_b32_e32 v63, 15, v14
	s_addc_u32 s3, s3, 0
	v_lshlrev_b64 v[2:3], 8, v[56:57]
	v_lshl_add_u64 v[2:3], s[2:3], 0, v[2:3]
	v_lshlrev_b32_e32 v0, 4, v63
	v_lshl_add_u64 v[2:3], v[2:3], 0, v[0:1]
	s_sub_u32 s2, s58, s56
	s_mov_b32 s9, 0x2aaaaaab
	global_load_dwordx4 v[50:53], v[2:3], off
	s_subb_u32 s3, s59, s57
	v_mul_hi_i32 v2, v14, s9
	s_lshr_b64 s[2:3], s[2:3], 2
	v_lshrrev_b32_e32 v3, 31, v2
	v_ashrrev_i32_e32 v2, 4, v2
	v_readlane_b32 s3, v226, 18
	v_add_u32_e32 v4, v2, v3
	s_movk_i32 s12, 0xffa0
	s_add_i32 s7, s3, s2
	v_mad_u64_u32 v[2:3], s[2:3], v4, s12, v[14:15]
	v_readlane_b32 s8, v226, 17
	v_readlane_b32 s2, v226, 19
	v_cmp_gt_i32_e32 vcc, 48, v2
	v_mul_lo_u32 v3, v4, s8
	v_mov_b32_e32 v4, s2
	v_mov_b32_e32 v5, s7
	v_lshlrev_b32_e32 v2, 2, v2
	v_cndmask_b32_e32 v6, v4, v5, vcc
	v_add3_u32 v58, v2, v3, v6
	v_add_u32_e32 v2, 0x100, v14
	v_mul_hi_i32 v3, v2, s9
	v_lshrrev_b32_e32 v6, 31, v3
	v_ashrrev_i32_e32 v3, 4, v3
	v_add_u32_e32 v6, v3, v6
	v_mad_u64_u32 v[2:3], s[2:3], v6, s12, v[2:3]
	v_cmp_gt_i32_e32 vcc, 48, v2
	v_mul_lo_u32 v3, v6, s8
	v_lshlrev_b32_e32 v2, 2, v2
	v_cndmask_b32_e32 v6, v4, v5, vcc
	v_add3_u32 v59, v2, v3, v6
	v_add_u32_e32 v2, 0x200, v14
	v_mul_hi_i32 v3, v2, s9
	v_lshrrev_b32_e32 v6, 31, v3
	v_ashrrev_i32_e32 v3, 4, v3
	v_add_u32_e32 v6, v3, v6
	v_mad_u64_u32 v[2:3], s[2:3], v6, s12, v[2:3]
	s_load_dwordx2 s[2:3], s[14:15], 0x1f0
	v_readlane_b32 s7, v226, 20
	v_cmp_gt_i32_e32 vcc, 48, v2
	v_mul_lo_u32 v3, v6, s8
	v_lshlrev_b32_e32 v2, 2, v2
	s_waitcnt lgkmcnt(0)
	s_add_u32 s2, s2, s7
	s_addc_u32 s3, s3, 0
	v_readlane_b32 s7, v224, 18
	s_add_u32 s2, s2, s7
	s_addc_u32 s3, s3, 0
	v_cndmask_b32_e32 v4, v4, v5, vcc
	v_lshl_add_u64 v[54:55], v[56:57], 2, s[2:3]
	v_readlane_b32 s2, v226, 21
	v_add3_u32 v60, v2, v3, v4
	v_lshlrev_b32_e32 v57, 4, v14
	v_add_u32_e32 v2, s2, v58
	v_ashrrev_i32_e32 v3, 31, v2
	v_add_u32_e32 v6, s2, v59
	v_lshl_add_u64 v[2:3], v[2:3], 2, s[56:57]
	v_ashrrev_i32_e32 v7, 31, v6
	v_add_u32_e32 v10, s2, v60
	global_load_dwordx4 v[2:5], v[2:3], off
	v_lshl_add_u64 v[6:7], v[6:7], 2, s[56:57]
	v_ashrrev_i32_e32 v11, 31, v10
	global_load_dwordx4 v[6:9], v[6:7], off
	v_lshl_add_u64 v[10:11], v[10:11], 2, s[56:57]
	global_load_dwordx4 v[10:13], v[10:11], off
	v_readlane_b32 s2, v226, 22
	v_add_u32_e32 v62, 8, v63
	v_add_u32_e32 v64, 24, v63
	v_cmp_gt_u32_e32 vcc, 8, v63
	v_cmp_eq_u32_e64 s[40:41], 7, v63
	v_cmp_eq_u32_e64 s[42:43], 6, v63
	v_cmp_eq_u32_e64 s[44:45], 5, v63
	v_cmp_eq_u32_e64 s[46:47], 4, v63
	v_cmp_eq_u32_e64 s[48:49], 3, v63
	v_cmp_eq_u32_e64 s[50:51], 2, v63
	v_cmp_eq_u32_e64 s[52:53], 1, v63
	v_cmp_eq_u32_e64 s[54:55], 0, v63
	s_mov_b32 s6, -4
	v_lshlrev_b32_e32 v56, 2, v56
	v_readlane_b32 s7, v226, 14
	s_waitcnt vmcnt(2)
	ds_write_b128 v57, v[2:5]
	s_waitcnt vmcnt(1)
	ds_write_b128 v57, v[6:9] offset:4096
	s_waitcnt vmcnt(0)
	ds_write_b128 v57, v[10:13] offset:8192
	v_add_u32_e32 v2, s2, v58
	v_add_u32_e32 v6, s2, v59
	v_add_u32_e32 v10, s2, v60
	v_readlane_b32 s2, v226, 23
	v_ashrrev_i32_e32 v3, 31, v2
	v_ashrrev_i32_e32 v7, 31, v6
	v_add_u32_e32 v14, s2, v58
	v_add_u32_e32 v18, s2, v59
	v_add_u32_e32 v22, s2, v60
	v_readlane_b32 s2, v226, 24
	v_ashrrev_i32_e32 v11, 31, v10
	v_ashrrev_i32_e32 v15, 31, v14
	v_add_u32_e32 v26, s2, v58
	v_add_u32_e32 v30, s2, v59
	v_add_u32_e32 v34, s2, v60
	v_readlane_b32 s2, v226, 25
	v_ashrrev_i32_e32 v19, 31, v18
	v_ashrrev_i32_e32 v23, 31, v22
	v_add_u32_e32 v38, s2, v58
	v_add_u32_e32 v42, s2, v59
	v_add_u32_e32 v46, s2, v60
	v_ashrrev_i32_e32 v27, 31, v26
	v_ashrrev_i32_e32 v31, 31, v30
	v_ashrrev_i32_e32 v35, 31, v34
	v_ashrrev_i32_e32 v39, 31, v38
	v_ashrrev_i32_e32 v43, 31, v42
	v_ashrrev_i32_e32 v47, 31, v46
	v_lshl_add_u64 v[2:3], v[2:3], 2, s[56:57]
	v_lshl_add_u64 v[6:7], v[6:7], 2, s[56:57]
	v_lshl_add_u64 v[10:11], v[10:11], 2, s[56:57]
	v_lshl_add_u64 v[14:15], v[14:15], 2, s[56:57]
	v_lshl_add_u64 v[18:19], v[18:19], 2, s[56:57]
	v_lshl_add_u64 v[22:23], v[22:23], 2, s[56:57]
	v_lshl_add_u64 v[26:27], v[26:27], 2, s[56:57]
	v_lshl_add_u64 v[30:31], v[30:31], 2, s[56:57]
	v_lshl_add_u64 v[34:35], v[34:35], 2, s[56:57]
	v_lshl_add_u64 v[38:39], v[38:39], 2, s[56:57]
	v_lshl_add_u64 v[42:43], v[42:43], 2, s[56:57]
	v_lshl_add_u64 v[46:47], v[46:47], 2, s[56:57]
	global_load_dwordx4 v[2:5], v[2:3], off
	v_readlane_b32 s2, v224, 5
	global_load_dwordx4 v[6:9], v[6:7], off
	s_nop 0
	global_load_dwordx4 v[10:13], v[10:11], off
	v_mov_b32_e32 v65, s2
	global_load_dwordx4 v[14:17], v[14:15], off
	v_readlane_b32 s2, v224, 6
	global_load_dwordx4 v[18:21], v[18:19], off
	s_nop 0
	global_load_dwordx4 v[22:25], v[22:23], off
	v_mad_i32_i24 v61, s2, v63, v65
	global_load_dwordx4 v[26:29], v[26:27], off
	v_or_b32_e32 v63, 16, v63
	global_load_dwordx4 v[30:33], v[30:31], off
	v_mad_i32_i24 v62, s2, v62, v65
	global_load_dwordx4 v[34:37], v[34:35], off
	v_mad_i32_i24 v63, s2, v63, v65
	global_load_dwordx4 v[38:41], v[38:39], off
	v_mad_i32_i24 v64, s2, v64, v65
	global_load_dwordx4 v[42:45], v[42:43], off
	s_nop 0
	global_load_dwordx4 v[46:49], v[46:47], off
	s_mul_i32 s2, s83, 5
	s_add_i32 s2, s2, s31
	s_mulk_i32 s2, 0x300
	v_add_u32_e32 v134, s2, v58
	v_add_u32_e32 v136, s2, v59
	v_add_u32_e32 v142, s2, v60
	v_ashrrev_i32_e32 v135, 31, v134
	v_ashrrev_i32_e32 v137, 31, v136
	v_ashrrev_i32_e32 v143, 31, v142
	v_lshl_add_u64 v[134:135], v[134:135], 2, s[56:57]
	v_lshl_add_u64 v[138:139], v[136:137], 2, s[56:57]
	v_lshl_add_u64 v[142:143], v[142:143], 2, s[56:57]
	global_load_dwordx4 v[134:137], v[134:135], off
	s_nop 0
	global_load_dwordx4 v[138:141], v[138:139], off
	s_nop 0
	global_load_dwordx4 v[142:145], v[142:143], off
	s_mul_i32 s2, s83, 6
	s_add_i32 s2, s2, s31
	s_mulk_i32 s2, 0x300
	v_add_u32_e32 v180, s2, v58
	v_add_u32_e32 v182, s2, v59
	v_add_u32_e32 v188, s2, v60
	v_ashrrev_i32_e32 v181, 31, v180
	v_ashrrev_i32_e32 v183, 31, v182
	v_ashrrev_i32_e32 v189, 31, v188
	v_lshl_add_u64 v[180:181], v[180:181], 2, s[56:57]
	v_lshl_add_u64 v[184:185], v[182:183], 2, s[56:57]
	v_lshl_add_u64 v[188:189], v[188:189], 2, s[56:57]
	global_load_dwordx4 v[180:183], v[180:181], off
	s_nop 0
	global_load_dwordx4 v[184:187], v[184:185], off
	s_nop 0
	global_load_dwordx4 v[188:191], v[188:189], off
	s_mul_i32 s2, s83, 7
	s_add_i32 s2, s2, s31
	s_mulk_i32 s2, 0x300
	v_add_u32_e32 v192, s2, v58
	v_add_u32_e32 v194, s2, v59
	v_add_u32_e32 v200, s2, v60
	v_ashrrev_i32_e32 v193, 31, v192
	v_ashrrev_i32_e32 v195, 31, v194
	v_ashrrev_i32_e32 v201, 31, v200
	v_lshl_add_u64 v[192:193], v[192:193], 2, s[56:57]
	v_lshl_add_u64 v[196:197], v[194:195], 2, s[56:57]
	v_lshl_add_u64 v[200:201], v[200:201], 2, s[56:57]
	global_load_dwordx4 v[192:195], v[192:193], off
	s_nop 0
	global_load_dwordx4 v[196:199], v[196:197], off
	s_nop 0
	global_load_dwordx4 v[200:203], v[200:201], off
	s_mul_i32 s2, s83, 8
	s_add_i32 s2, s2, s31
	s_mulk_i32 s2, 0x300
	v_add_u32_e32 v204, s2, v58
	v_add_u32_e32 v206, s2, v59
	v_add_u32_e32 v212, s2, v60
	v_ashrrev_i32_e32 v205, 31, v204
	v_ashrrev_i32_e32 v207, 31, v206
	v_ashrrev_i32_e32 v213, 31, v212
	v_lshl_add_u64 v[204:205], v[204:205], 2, s[56:57]
	v_lshl_add_u64 v[208:209], v[206:207], 2, s[56:57]
	v_lshl_add_u64 v[212:213], v[212:213], 2, s[56:57]
	global_load_dwordx4 v[204:207], v[204:205], off
	s_nop 0
	global_load_dwordx4 v[208:211], v[208:209], off
	s_nop 0
	global_load_dwordx4 v[212:215], v[212:213], off
	v_readlane_b32 s100, v224, 7
	v_readlane_b32 s2, v224, 6
	s_add_i32 s100, s100, s7
	s_mov_b32 s6, -8
	v_lshrrev_b32_e32 v66, 5, v0
	v_mad_i32_i24 v61, s2, v66, v65
	v_add_u32_e32 v67, 8, v66
	v_mad_i32_i24 v62, s2, v67, v65
	v_add_u32_e32 v67, 16, v66
	v_mad_i32_i24 v63, s2, v67, v65
	v_add_u32_e32 v67, 24, v66
	v_mad_i32_i24 v64, s2, v67, v65
	v_and_b32_e32 v66, 0x80, v0
	v_cmp_ne_u32_e64 s[40:41], 0, v66
	v_and_b32_e32 v66, 64, v0
	v_cmp_ne_u32_e64 s[42:43], 0, v66
	v_and_b32_e32 v66, 32, v0
	v_cmp_ne_u32_e64 s[44:45], 0, v66
	v_and_b32_e32 v66, 16, v0
	v_cmp_eq_u32_e32 vcc, 0, v66
	s_waitcnt lgkmcnt(0)
	s_barrier
	s_branch .LBB0_279
.LBB0_279:
	s_add_i32 s6, s6, 8
	ds_read_b128 v[68:71], v0 offset:0
	ds_read_b128 v[76:79], v0 offset:1280
	ds_read_b32 v88, v56 offset:512
	ds_read_b128 v[72:75], v0 offset:768
	ds_read_b128 v[100:103], v0 offset:2816
	ds_read_b32 v90, v56 offset:2048
	ds_read_b128 v[80:83], v0 offset:1024
	ds_read_b128 v[92:95], v0 offset:1536
	ds_read_b128 v[84:87], v0 offset:256
	ds_read_b128 v[96:99], v0 offset:2304
	ds_read_b128 v[104:107], v0 offset:2560
	s_min_u32 s2, s6, 246
	s_add_i32 s2, s2, 9
	s_mul_i32 s2, s2, s83
	s_add_i32 s2, s2, s31
	s_mulk_i32 s2, 0x300
	s_waitcnt vmcnt(23)
	ds_write_b128 v57, v[2:5] offset:12288
	s_waitcnt vmcnt(22)
	ds_write_b128 v57, v[6:9] offset:16384
	s_waitcnt vmcnt(21)
	ds_write_b128 v57, v[10:13] offset:20480
	v_add_u32_e32 v2, s2, v58
	v_add_u32_e32 v4, s2, v59
	v_add_u32_e32 v10, s2, v60
	v_ashrrev_i32_e32 v3, 31, v2
	v_ashrrev_i32_e32 v5, 31, v4
	v_ashrrev_i32_e32 v11, 31, v10
	v_lshl_add_u64 v[2:3], v[2:3], 2, s[56:57]
	v_lshl_add_u64 v[6:7], v[4:5], 2, s[56:57]
	v_lshl_add_u64 v[10:11], v[10:11], 2, s[56:57]
	global_load_dwordx4 v[2:5], v[2:3], off
	s_nop 0
	global_load_dwordx4 v[6:9], v[6:7], off
	s_nop 0
	global_load_dwordx4 v[10:13], v[10:11], off
	s_waitcnt lgkmcnt(11)
	v_pk_mul_f32 v[112:113], v[76:77], v[88:89] op_sel_hi:[1,0]
	v_pk_mul_f32 v[114:115], v[78:79], v[88:89] op_sel_hi:[1,0]
	ds_read_b128 v[76:79], v0 offset:4352
	ds_read_b32 v88, v56 offset:3584
	s_waitcnt lgkmcnt(9)
	v_pk_mul_f32 v[120:121], v[52:53], v[70:71]
	v_pk_fma_f32 v[120:121], v[50:51], v[68:69], v[120:121]
	ds_read_b128 v[68:71], v0 offset:3072
	v_add_f32_e32 v124, v120, v121
	v_pk_fma_f32 v[112:113], v[50:51], v[72:73], v[112:113]
	v_pk_fma_f32 v[114:115], v[52:53], v[74:75], v[114:115]
	ds_read_b128 v[72:75], v0 offset:3840
	v_add_f32_dpp v124, v124, v124 quad_perm:[1,0,3,2] row_mask:0xf bank_mask:0xf bound_ctrl:1
	ds_read_b128 v[108:111], v0 offset:1792
	s_nop 0
	v_add_f32_dpp v124, v124, v124 quad_perm:[2,3,0,1] row_mask:0xf bank_mask:0xf bound_ctrl:1
	v_pk_mul_f32 v[116:117], v[100:101], v[90:91] op_sel_hi:[1,0]
	v_pk_mul_f32 v[118:119], v[102:103], v[90:91] op_sel_hi:[1,0]
	v_add_f32_dpp v124, v124, v124 row_half_mirror row_mask:0xf bank_mask:0xf bound_ctrl:1
	ds_read_b128 v[100:103], v0 offset:5888
	ds_read_b32 v90, v56 offset:5120
	v_add_f32_dpp v124, v124, v124 row_mirror row_mask:0xf bank_mask:0xf bound_ctrl:1
	v_pk_fma_f32 v[50:51], v[80:81], v[124:125], v[112:113] op_sel_hi:[1,0,1]
	v_pk_fma_f32 v[52:53], v[82:83], v[124:125], v[114:115] op_sel_hi:[1,0,1]
	ds_read_b128 v[80:83], v0 offset:4096
	s_waitcnt lgkmcnt(6)
	v_pk_mul_f32 v[120:121], v[52:53], v[94:95]
	v_pk_fma_f32 v[120:121], v[50:51], v[92:93], v[120:121]
	ds_read_b128 v[92:95], v0 offset:4608
	v_add_f32_e32 v124, v120, v121
	v_pk_fma_f32 v[116:117], v[50:51], v[96:97], v[116:117]
	v_pk_fma_f32 v[118:119], v[52:53], v[98:99], v[118:119]
	ds_read_b128 v[96:99], v0 offset:5376
	v_add_f32_dpp v124, v124, v124 quad_perm:[1,0,3,2] row_mask:0xf bank_mask:0xf bound_ctrl:1
	v_pk_mul_f32 v[122:123], v[52:53], v[86:87]
	v_pk_fma_f32 v[122:123], v[50:51], v[84:85], v[122:123]
	ds_read_b128 v[84:87], v0 offset:3328
	v_add_f32_dpp v124, v124, v124 quad_perm:[2,3,0,1] row_mask:0xf bank_mask:0xf bound_ctrl:1
	v_pk_mul_f32 v[112:113], v[76:77], v[88:89] op_sel_hi:[1,0]
	v_pk_mul_f32 v[114:115], v[78:79], v[88:89] op_sel_hi:[1,0]
	v_add_f32_dpp v124, v124, v124 row_half_mirror row_mask:0xf bank_mask:0xf bound_ctrl:1
	v_add_f32_e32 v216, v122, v123
	ds_read_b128 v[76:79], v0 offset:7424
	ds_read_b32 v88, v56 offset:6656
	v_add_f32_dpp v124, v124, v124 row_mirror row_mask:0xf bank_mask:0xf bound_ctrl:1
	v_pk_fma_f32 v[50:51], v[104:105], v[124:125], v[116:117] op_sel_hi:[1,0,1]
	v_pk_fma_f32 v[52:53], v[106:107], v[124:125], v[118:119] op_sel_hi:[1,0,1]
	ds_read_b128 v[104:107], v0 offset:5632
	s_waitcnt lgkmcnt(6)
	v_pk_mul_f32 v[120:121], v[52:53], v[70:71]
	v_pk_fma_f32 v[120:121], v[50:51], v[68:69], v[120:121]
	ds_read_b128 v[68:71], v0 offset:6144
	v_add_f32_e32 v124, v120, v121
	v_pk_fma_f32 v[112:113], v[50:51], v[72:73], v[112:113]
	v_pk_fma_f32 v[114:115], v[52:53], v[74:75], v[114:115]
	ds_read_b128 v[72:75], v0 offset:6912
	v_add_f32_dpp v124, v124, v124 quad_perm:[1,0,3,2] row_mask:0xf bank_mask:0xf bound_ctrl:1
	v_pk_mul_f32 v[122:123], v[52:53], v[110:111]
	v_pk_fma_f32 v[122:123], v[50:51], v[108:109], v[122:123]
	ds_read_b128 v[108:111], v0 offset:4864
	v_add_f32_dpp v124, v124, v124 quad_perm:[2,3,0,1] row_mask:0xf bank_mask:0xf bound_ctrl:1
	v_pk_mul_f32 v[116:117], v[100:101], v[90:91] op_sel_hi:[1,0]
	v_pk_mul_f32 v[118:119], v[102:103], v[90:91] op_sel_hi:[1,0]
	v_add_f32_dpp v124, v124, v124 row_half_mirror row_mask:0xf bank_mask:0xf bound_ctrl:1
	v_add_f32_e32 v217, v122, v123
	ds_read_b128 v[100:103], v0 offset:8960
	ds_read_b32 v90, v56 offset:8192
	v_add_f32_dpp v124, v124, v124 row_mirror row_mask:0xf bank_mask:0xf bound_ctrl:1
	v_pk_fma_f32 v[50:51], v[80:81], v[124:125], v[112:113] op_sel_hi:[1,0,1]
	v_pk_fma_f32 v[52:53], v[82:83], v[124:125], v[114:115] op_sel_hi:[1,0,1]
	ds_read_b128 v[80:83], v0 offset:7168
	s_waitcnt lgkmcnt(6)
	v_pk_mul_f32 v[120:121], v[52:53], v[94:95]
	v_pk_fma_f32 v[120:121], v[50:51], v[92:93], v[120:121]
	ds_read_b128 v[92:95], v0 offset:7680
	v_add_f32_e32 v124, v120, v121
	v_pk_fma_f32 v[116:117], v[50:51], v[96:97], v[116:117]
	v_pk_fma_f32 v[118:119], v[52:53], v[98:99], v[118:119]
	ds_read_b128 v[96:99], v0 offset:8448
	v_add_f32_dpp v124, v124, v124 quad_perm:[1,0,3,2] row_mask:0xf bank_mask:0xf bound_ctrl:1
	v_pk_mul_f32 v[122:123], v[52:53], v[86:87]
	v_pk_fma_f32 v[122:123], v[50:51], v[84:85], v[122:123]
	ds_read_b128 v[84:87], v0 offset:6400
	v_add_f32_dpp v124, v124, v124 quad_perm:[2,3,0,1] row_mask:0xf bank_mask:0xf bound_ctrl:1
	v_pk_mul_f32 v[112:113], v[76:77], v[88:89] op_sel_hi:[1,0]
	v_pk_mul_f32 v[114:115], v[78:79], v[88:89] op_sel_hi:[1,0]
	v_add_f32_dpp v124, v124, v124 row_half_mirror row_mask:0xf bank_mask:0xf bound_ctrl:1
	v_add_f32_e32 v218, v122, v123
	ds_read_b128 v[76:79], v0 offset:10496
	ds_read_b32 v88, v56 offset:9728
	v_add_f32_dpp v124, v124, v124 row_mirror row_mask:0xf bank_mask:0xf bound_ctrl:1
	v_pk_fma_f32 v[50:51], v[104:105], v[124:125], v[116:117] op_sel_hi:[1,0,1]
	v_pk_fma_f32 v[52:53], v[106:107], v[124:125], v[118:119] op_sel_hi:[1,0,1]
	ds_read_b128 v[104:107], v0 offset:8704
	s_waitcnt lgkmcnt(6)
	v_pk_mul_f32 v[120:121], v[52:53], v[70:71]
	v_pk_fma_f32 v[120:121], v[50:51], v[68:69], v[120:121]
	ds_read_b128 v[68:71], v0 offset:9216
	v_add_f32_e32 v124, v120, v121
	v_pk_fma_f32 v[112:113], v[50:51], v[72:73], v[112:113]
	v_pk_fma_f32 v[114:115], v[52:53], v[74:75], v[114:115]
	ds_read_b128 v[72:75], v0 offset:9984
	v_add_f32_dpp v124, v124, v124 quad_perm:[1,0,3,2] row_mask:0xf bank_mask:0xf bound_ctrl:1
	v_pk_mul_f32 v[122:123], v[52:53], v[110:111]
	v_pk_fma_f32 v[122:123], v[50:51], v[108:109], v[122:123]
	ds_read_b128 v[108:111], v0 offset:7936
	v_add_f32_dpp v124, v124, v124 quad_perm:[2,3,0,1] row_mask:0xf bank_mask:0xf bound_ctrl:1
	v_pk_mul_f32 v[116:117], v[100:101], v[90:91] op_sel_hi:[1,0]
	v_pk_mul_f32 v[118:119], v[102:103], v[90:91] op_sel_hi:[1,0]
	v_add_f32_dpp v124, v124, v124 row_half_mirror row_mask:0xf bank_mask:0xf bound_ctrl:1
	v_add_f32_e32 v219, v122, v123
	ds_read_b128 v[100:103], v0 offset:12032
	ds_read_b32 v90, v56 offset:11264
	v_add_f32_dpp v124, v124, v124 row_mirror row_mask:0xf bank_mask:0xf bound_ctrl:1
	v_pk_fma_f32 v[50:51], v[80:81], v[124:125], v[112:113] op_sel_hi:[1,0,1]
	v_pk_fma_f32 v[52:53], v[82:83], v[124:125], v[114:115] op_sel_hi:[1,0,1]
	ds_read_b128 v[80:83], v0 offset:10240
	s_waitcnt lgkmcnt(6)
	v_pk_mul_f32 v[120:121], v[52:53], v[94:95]
	v_pk_fma_f32 v[120:121], v[50:51], v[92:93], v[120:121]
	ds_read_b128 v[92:95], v0 offset:10752
	v_add_f32_e32 v124, v120, v121
	v_pk_fma_f32 v[116:117], v[50:51], v[96:97], v[116:117]
	v_pk_fma_f32 v[118:119], v[52:53], v[98:99], v[118:119]
	ds_read_b128 v[96:99], v0 offset:11520
	v_add_f32_dpp v124, v124, v124 quad_perm:[1,0,3,2] row_mask:0xf bank_mask:0xf bound_ctrl:1
	v_pk_mul_f32 v[122:123], v[52:53], v[86:87]
	v_pk_fma_f32 v[122:123], v[50:51], v[84:85], v[122:123]
	ds_read_b128 v[84:87], v0 offset:9472
	v_add_f32_dpp v124, v124, v124 quad_perm:[2,3,0,1] row_mask:0xf bank_mask:0xf bound_ctrl:1
	v_pk_mul_f32 v[112:113], v[76:77], v[88:89] op_sel_hi:[1,0]
	v_pk_mul_f32 v[114:115], v[78:79], v[88:89] op_sel_hi:[1,0]
	v_add_f32_dpp v124, v124, v124 row_half_mirror row_mask:0xf bank_mask:0xf bound_ctrl:1
	v_add_f32_e32 v220, v122, v123
	s_nop 0
	v_add_f32_dpp v124, v124, v124 row_mirror row_mask:0xf bank_mask:0xf bound_ctrl:1
	v_pk_fma_f32 v[50:51], v[104:105], v[124:125], v[116:117] op_sel_hi:[1,0,1]
	v_pk_fma_f32 v[52:53], v[106:107], v[124:125], v[118:119] op_sel_hi:[1,0,1]
	ds_read_b128 v[104:107], v0 offset:11776
	s_waitcnt lgkmcnt(4)
	v_pk_mul_f32 v[120:121], v[52:53], v[70:71]
	v_pk_fma_f32 v[120:121], v[50:51], v[68:69], v[120:121]
	v_add_f32_e32 v124, v120, v121
	v_pk_fma_f32 v[112:113], v[50:51], v[72:73], v[112:113]
	v_pk_fma_f32 v[114:115], v[52:53], v[74:75], v[114:115]
	v_add_f32_dpp v124, v124, v124 quad_perm:[1,0,3,2] row_mask:0xf bank_mask:0xf bound_ctrl:1
	v_pk_mul_f32 v[122:123], v[52:53], v[110:111]
	v_pk_fma_f32 v[122:123], v[50:51], v[108:109], v[122:123]
	ds_read_b128 v[108:111], v0 offset:11008
	v_add_f32_dpp v124, v124, v124 quad_perm:[2,3,0,1] row_mask:0xf bank_mask:0xf bound_ctrl:1
	v_pk_mul_f32 v[116:117], v[100:101], v[90:91] op_sel_hi:[1,0]
	v_pk_mul_f32 v[118:119], v[102:103], v[90:91] op_sel_hi:[1,0]
	v_add_f32_dpp v124, v124, v124 row_half_mirror row_mask:0xf bank_mask:0xf bound_ctrl:1
	v_add_f32_e32 v221, v122, v123
	s_nop 0
	v_add_f32_dpp v124, v124, v124 row_mirror row_mask:0xf bank_mask:0xf bound_ctrl:1
	v_pk_fma_f32 v[50:51], v[80:81], v[124:125], v[112:113] op_sel_hi:[1,0,1]
	v_pk_fma_f32 v[52:53], v[82:83], v[124:125], v[114:115] op_sel_hi:[1,0,1]
	s_waitcnt lgkmcnt(1)
	v_pk_mul_f32 v[120:121], v[52:53], v[94:95]
	v_pk_fma_f32 v[120:121], v[50:51], v[92:93], v[120:121]
	v_add_f32_e32 v124, v120, v121
	v_pk_fma_f32 v[116:117], v[50:51], v[96:97], v[116:117]
	v_pk_fma_f32 v[118:119], v[52:53], v[98:99], v[118:119]
	v_add_f32_dpp v124, v124, v124 quad_perm:[1,0,3,2] row_mask:0xf bank_mask:0xf bound_ctrl:1
	v_pk_mul_f32 v[122:123], v[52:53], v[86:87]
	v_pk_fma_f32 v[122:123], v[50:51], v[84:85], v[122:123]
	v_add_f32_dpp v124, v124, v124 quad_perm:[2,3,0,1] row_mask:0xf bank_mask:0xf bound_ctrl:1
	s_nop 1
	v_add_f32_dpp v124, v124, v124 row_half_mirror row_mask:0xf bank_mask:0xf bound_ctrl:1
	v_add_f32_e32 v222, v122, v123
	s_nop 0
	v_add_f32_dpp v124, v124, v124 row_mirror row_mask:0xf bank_mask:0xf bound_ctrl:1
	v_pk_fma_f32 v[50:51], v[104:105], v[124:125], v[116:117] op_sel_hi:[1,0,1]
	v_pk_fma_f32 v[52:53], v[106:107], v[124:125], v[118:119] op_sel_hi:[1,0,1]
	s_waitcnt lgkmcnt(0)
	v_pk_mul_f32 v[122:123], v[52:53], v[110:111]
	v_pk_fma_f32 v[122:123], v[50:51], v[108:109], v[122:123]
	v_add_f32_e32 v223, v122, v123
	v_cndmask_b32_e64 v68, v216, v220, s[40:41]
	v_cndmask_b32_e64 v72, v220, v216, s[40:41]
	v_cndmask_b32_e64 v69, v217, v221, s[40:41]
	v_cndmask_b32_e64 v73, v221, v217, s[40:41]
	v_cndmask_b32_e64 v70, v218, v222, s[40:41]
	v_cndmask_b32_e64 v74, v222, v218, s[40:41]
	v_cndmask_b32_e64 v71, v219, v223, s[40:41]
	v_cndmask_b32_e64 v75, v223, v219, s[40:41]
	v_add_f32_dpp v68, v72, v68 row_mirror row_mask:0xf bank_mask:0xf bound_ctrl:1
	v_add_f32_dpp v69, v73, v69 row_mirror row_mask:0xf bank_mask:0xf bound_ctrl:1
	v_add_f32_dpp v70, v74, v70 row_mirror row_mask:0xf bank_mask:0xf bound_ctrl:1
	v_add_f32_dpp v71, v75, v71 row_mirror row_mask:0xf bank_mask:0xf bound_ctrl:1
	v_cndmask_b32_e64 v76, v68, v70, s[42:43]
	v_cndmask_b32_e64 v78, v70, v68, s[42:43]
	v_cndmask_b32_e64 v77, v69, v71, s[42:43]
	v_cndmask_b32_e64 v79, v71, v69, s[42:43]
	v_add_u32_e32 v66, s7, v61
	v_add_f32_dpp v76, v78, v76 row_half_mirror row_mask:0xf bank_mask:0xf bound_ctrl:1
	v_add_f32_dpp v77, v79, v77 row_half_mirror row_mask:0xf bank_mask:0xf bound_ctrl:1
	v_cndmask_b32_e64 v80, v76, v77, s[44:45]
	v_cndmask_b32_e64 v81, v77, v76, s[44:45]
	v_ashrrev_i32_e32 v67, 31, v66
	v_lshlrev_b64 v[66:67], 10, v[66:67]
	v_add_f32_dpp v80, v81, v80 quad_perm:[2,3,0,1] row_mask:0xf bank_mask:0xf bound_ctrl:1
	v_lshl_add_u64 v[66:67], v[54:55], 0, v[66:67]
	s_nop 0
	v_add_f32_dpp v65, v80, v80 quad_perm:[1,0,3,2] row_mask:0xf bank_mask:0xf bound_ctrl:1
	s_and_saveexec_b64 s[2:3], vcc
	global_store_dword v[66:67], v65, off
	s_or_b64 exec, exec, s[2:3]
	s_waitcnt lgkmcnt(0)
	s_barrier
	ds_read_b128 v[68:71], v0 offset:12288
	ds_read_b128 v[76:79], v0 offset:13568
	ds_read_b32 v88, v56 offset:12800
	ds_read_b128 v[72:75], v0 offset:13056
	ds_read_b128 v[100:103], v0 offset:15104
	ds_read_b32 v90, v56 offset:14336
	ds_read_b128 v[80:83], v0 offset:13312
	ds_read_b128 v[92:95], v0 offset:13824
	ds_read_b128 v[84:87], v0 offset:12544
	ds_read_b128 v[96:99], v0 offset:14592
	ds_read_b128 v[104:107], v0 offset:14848
	s_min_u32 s2, s6, 245
	s_add_i32 s2, s2, 10
	s_mul_i32 s2, s2, s83
	s_add_i32 s2, s2, s31
	s_mulk_i32 s2, 0x300
	s_waitcnt vmcnt(23)
	ds_write_b128 v57, v[14:17] offset:0
	s_waitcnt vmcnt(22)
	ds_write_b128 v57, v[18:21] offset:4096
	s_waitcnt vmcnt(21)
	ds_write_b128 v57, v[22:25] offset:8192
	v_add_u32_e32 v14, s2, v58
	v_add_u32_e32 v16, s2, v59
	v_add_u32_e32 v22, s2, v60
	v_ashrrev_i32_e32 v15, 31, v14
	v_ashrrev_i32_e32 v17, 31, v16
	v_ashrrev_i32_e32 v23, 31, v22
	v_lshl_add_u64 v[14:15], v[14:15], 2, s[56:57]
	v_lshl_add_u64 v[18:19], v[16:17], 2, s[56:57]
	v_lshl_add_u64 v[22:23], v[22:23], 2, s[56:57]
	global_load_dwordx4 v[14:17], v[14:15], off
	s_nop 0
	global_load_dwordx4 v[18:21], v[18:19], off
	s_nop 0
	global_load_dwordx4 v[22:25], v[22:23], off
	s_waitcnt lgkmcnt(11)
	v_pk_mul_f32 v[112:113], v[76:77], v[88:89] op_sel_hi:[1,0]
	v_pk_mul_f32 v[114:115], v[78:79], v[88:89] op_sel_hi:[1,0]
	ds_read_b128 v[76:79], v0 offset:16640
	ds_read_b32 v88, v56 offset:15872
	s_waitcnt lgkmcnt(9)
	v_pk_mul_f32 v[120:121], v[52:53], v[70:71]
	v_pk_fma_f32 v[120:121], v[50:51], v[68:69], v[120:121]
	ds_read_b128 v[68:71], v0 offset:15360
	v_add_f32_e32 v124, v120, v121
	v_pk_fma_f32 v[112:113], v[50:51], v[72:73], v[112:113]
	v_pk_fma_f32 v[114:115], v[52:53], v[74:75], v[114:115]
	ds_read_b128 v[72:75], v0 offset:16128
	v_add_f32_dpp v124, v124, v124 quad_perm:[1,0,3,2] row_mask:0xf bank_mask:0xf bound_ctrl:1
	ds_read_b128 v[108:111], v0 offset:14080
	s_nop 0
	v_add_f32_dpp v124, v124, v124 quad_perm:[2,3,0,1] row_mask:0xf bank_mask:0xf bound_ctrl:1
	v_pk_mul_f32 v[116:117], v[100:101], v[90:91] op_sel_hi:[1,0]
	v_pk_mul_f32 v[118:119], v[102:103], v[90:91] op_sel_hi:[1,0]
	v_add_f32_dpp v124, v124, v124 row_half_mirror row_mask:0xf bank_mask:0xf bound_ctrl:1
	ds_read_b128 v[100:103], v0 offset:18176
	ds_read_b32 v90, v56 offset:17408
	v_add_f32_dpp v124, v124, v124 row_mirror row_mask:0xf bank_mask:0xf bound_ctrl:1
	v_pk_fma_f32 v[50:51], v[80:81], v[124:125], v[112:113] op_sel_hi:[1,0,1]
	v_pk_fma_f32 v[52:53], v[82:83], v[124:125], v[114:115] op_sel_hi:[1,0,1]
	ds_read_b128 v[80:83], v0 offset:16384
	s_waitcnt lgkmcnt(6)
	v_pk_mul_f32 v[120:121], v[52:53], v[94:95]
	v_pk_fma_f32 v[120:121], v[50:51], v[92:93], v[120:121]
	ds_read_b128 v[92:95], v0 offset:16896
	v_add_f32_e32 v124, v120, v121
	v_pk_fma_f32 v[116:117], v[50:51], v[96:97], v[116:117]
	v_pk_fma_f32 v[118:119], v[52:53], v[98:99], v[118:119]
	ds_read_b128 v[96:99], v0 offset:17664
	v_add_f32_dpp v124, v124, v124 quad_perm:[1,0,3,2] row_mask:0xf bank_mask:0xf bound_ctrl:1
	v_pk_mul_f32 v[122:123], v[52:53], v[86:87]
	v_pk_fma_f32 v[122:123], v[50:51], v[84:85], v[122:123]
	ds_read_b128 v[84:87], v0 offset:15616
	v_add_f32_dpp v124, v124, v124 quad_perm:[2,3,0,1] row_mask:0xf bank_mask:0xf bound_ctrl:1
	v_pk_mul_f32 v[112:113], v[76:77], v[88:89] op_sel_hi:[1,0]
	v_pk_mul_f32 v[114:115], v[78:79], v[88:89] op_sel_hi:[1,0]
	v_add_f32_dpp v124, v124, v124 row_half_mirror row_mask:0xf bank_mask:0xf bound_ctrl:1
	v_add_f32_e32 v216, v122, v123
	ds_read_b128 v[76:79], v0 offset:19712
	ds_read_b32 v88, v56 offset:18944
	v_add_f32_dpp v124, v124, v124 row_mirror row_mask:0xf bank_mask:0xf bound_ctrl:1
	v_pk_fma_f32 v[50:51], v[104:105], v[124:125], v[116:117] op_sel_hi:[1,0,1]
	v_pk_fma_f32 v[52:53], v[106:107], v[124:125], v[118:119] op_sel_hi:[1,0,1]
	ds_read_b128 v[104:107], v0 offset:17920
	s_waitcnt lgkmcnt(6)
	v_pk_mul_f32 v[120:121], v[52:53], v[70:71]
	v_pk_fma_f32 v[120:121], v[50:51], v[68:69], v[120:121]
	ds_read_b128 v[68:71], v0 offset:18432
	v_add_f32_e32 v124, v120, v121
	v_pk_fma_f32 v[112:113], v[50:51], v[72:73], v[112:113]
	v_pk_fma_f32 v[114:115], v[52:53], v[74:75], v[114:115]
	ds_read_b128 v[72:75], v0 offset:19200
	v_add_f32_dpp v124, v124, v124 quad_perm:[1,0,3,2] row_mask:0xf bank_mask:0xf bound_ctrl:1
	v_pk_mul_f32 v[122:123], v[52:53], v[110:111]
	v_pk_fma_f32 v[122:123], v[50:51], v[108:109], v[122:123]
	ds_read_b128 v[108:111], v0 offset:17152
	v_add_f32_dpp v124, v124, v124 quad_perm:[2,3,0,1] row_mask:0xf bank_mask:0xf bound_ctrl:1
	v_pk_mul_f32 v[116:117], v[100:101], v[90:91] op_sel_hi:[1,0]
	v_pk_mul_f32 v[118:119], v[102:103], v[90:91] op_sel_hi:[1,0]
	v_add_f32_dpp v124, v124, v124 row_half_mirror row_mask:0xf bank_mask:0xf bound_ctrl:1
	v_add_f32_e32 v217, v122, v123
	ds_read_b128 v[100:103], v0 offset:21248
	ds_read_b32 v90, v56 offset:20480
	v_add_f32_dpp v124, v124, v124 row_mirror row_mask:0xf bank_mask:0xf bound_ctrl:1
	v_pk_fma_f32 v[50:51], v[80:81], v[124:125], v[112:113] op_sel_hi:[1,0,1]
	v_pk_fma_f32 v[52:53], v[82:83], v[124:125], v[114:115] op_sel_hi:[1,0,1]
	ds_read_b128 v[80:83], v0 offset:19456
	s_waitcnt lgkmcnt(6)
	v_pk_mul_f32 v[120:121], v[52:53], v[94:95]
	v_pk_fma_f32 v[120:121], v[50:51], v[92:93], v[120:121]
	ds_read_b128 v[92:95], v0 offset:19968
	v_add_f32_e32 v124, v120, v121
	v_pk_fma_f32 v[116:117], v[50:51], v[96:97], v[116:117]
	v_pk_fma_f32 v[118:119], v[52:53], v[98:99], v[118:119]
	ds_read_b128 v[96:99], v0 offset:20736
	v_add_f32_dpp v124, v124, v124 quad_perm:[1,0,3,2] row_mask:0xf bank_mask:0xf bound_ctrl:1
	v_pk_mul_f32 v[122:123], v[52:53], v[86:87]
	v_pk_fma_f32 v[122:123], v[50:51], v[84:85], v[122:123]
	ds_read_b128 v[84:87], v0 offset:18688
	v_add_f32_dpp v124, v124, v124 quad_perm:[2,3,0,1] row_mask:0xf bank_mask:0xf bound_ctrl:1
	v_pk_mul_f32 v[112:113], v[76:77], v[88:89] op_sel_hi:[1,0]
	v_pk_mul_f32 v[114:115], v[78:79], v[88:89] op_sel_hi:[1,0]
	v_add_f32_dpp v124, v124, v124 row_half_mirror row_mask:0xf bank_mask:0xf bound_ctrl:1
	v_add_f32_e32 v218, v122, v123
	ds_read_b128 v[76:79], v0 offset:22784
	ds_read_b32 v88, v56 offset:22016
	v_add_f32_dpp v124, v124, v124 row_mirror row_mask:0xf bank_mask:0xf bound_ctrl:1
	v_pk_fma_f32 v[50:51], v[104:105], v[124:125], v[116:117] op_sel_hi:[1,0,1]
	v_pk_fma_f32 v[52:53], v[106:107], v[124:125], v[118:119] op_sel_hi:[1,0,1]
	ds_read_b128 v[104:107], v0 offset:20992
	s_waitcnt lgkmcnt(6)
	v_pk_mul_f32 v[120:121], v[52:53], v[70:71]
	v_pk_fma_f32 v[120:121], v[50:51], v[68:69], v[120:121]
	ds_read_b128 v[68:71], v0 offset:21504
	v_add_f32_e32 v124, v120, v121
	v_pk_fma_f32 v[112:113], v[50:51], v[72:73], v[112:113]
	v_pk_fma_f32 v[114:115], v[52:53], v[74:75], v[114:115]
	ds_read_b128 v[72:75], v0 offset:22272
	v_add_f32_dpp v124, v124, v124 quad_perm:[1,0,3,2] row_mask:0xf bank_mask:0xf bound_ctrl:1
	v_pk_mul_f32 v[122:123], v[52:53], v[110:111]
	v_pk_fma_f32 v[122:123], v[50:51], v[108:109], v[122:123]
	ds_read_b128 v[108:111], v0 offset:20224
	v_add_f32_dpp v124, v124, v124 quad_perm:[2,3,0,1] row_mask:0xf bank_mask:0xf bound_ctrl:1
	v_pk_mul_f32 v[116:117], v[100:101], v[90:91] op_sel_hi:[1,0]
	v_pk_mul_f32 v[118:119], v[102:103], v[90:91] op_sel_hi:[1,0]
	v_add_f32_dpp v124, v124, v124 row_half_mirror row_mask:0xf bank_mask:0xf bound_ctrl:1
	v_add_f32_e32 v219, v122, v123
	ds_read_b128 v[100:103], v0 offset:24320
	ds_read_b32 v90, v56 offset:23552
	v_add_f32_dpp v124, v124, v124 row_mirror row_mask:0xf bank_mask:0xf bound_ctrl:1
	v_pk_fma_f32 v[50:51], v[80:81], v[124:125], v[112:113] op_sel_hi:[1,0,1]
	v_pk_fma_f32 v[52:53], v[82:83], v[124:125], v[114:115] op_sel_hi:[1,0,1]
	ds_read_b128 v[80:83], v0 offset:22528
	s_waitcnt lgkmcnt(6)
	v_pk_mul_f32 v[120:121], v[52:53], v[94:95]
	v_pk_fma_f32 v[120:121], v[50:51], v[92:93], v[120:121]
	ds_read_b128 v[92:95], v0 offset:23040
	v_add_f32_e32 v124, v120, v121
	v_pk_fma_f32 v[116:117], v[50:51], v[96:97], v[116:117]
	v_pk_fma_f32 v[118:119], v[52:53], v[98:99], v[118:119]
	ds_read_b128 v[96:99], v0 offset:23808
	v_add_f32_dpp v124, v124, v124 quad_perm:[1,0,3,2] row_mask:0xf bank_mask:0xf bound_ctrl:1
	v_pk_mul_f32 v[122:123], v[52:53], v[86:87]
	v_pk_fma_f32 v[122:123], v[50:51], v[84:85], v[122:123]
	ds_read_b128 v[84:87], v0 offset:21760
	v_add_f32_dpp v124, v124, v124 quad_perm:[2,3,0,1] row_mask:0xf bank_mask:0xf bound_ctrl:1
	v_pk_mul_f32 v[112:113], v[76:77], v[88:89] op_sel_hi:[1,0]
	v_pk_mul_f32 v[114:115], v[78:79], v[88:89] op_sel_hi:[1,0]
	v_add_f32_dpp v124, v124, v124 row_half_mirror row_mask:0xf bank_mask:0xf bound_ctrl:1
	v_add_f32_e32 v220, v122, v123
	s_nop 0
	v_add_f32_dpp v124, v124, v124 row_mirror row_mask:0xf bank_mask:0xf bound_ctrl:1
	v_pk_fma_f32 v[50:51], v[104:105], v[124:125], v[116:117] op_sel_hi:[1,0,1]
	v_pk_fma_f32 v[52:53], v[106:107], v[124:125], v[118:119] op_sel_hi:[1,0,1]
	ds_read_b128 v[104:107], v0 offset:24064
	s_waitcnt lgkmcnt(4)
	v_pk_mul_f32 v[120:121], v[52:53], v[70:71]
	v_pk_fma_f32 v[120:121], v[50:51], v[68:69], v[120:121]
	v_add_f32_e32 v124, v120, v121
	v_pk_fma_f32 v[112:113], v[50:51], v[72:73], v[112:113]
	v_pk_fma_f32 v[114:115], v[52:53], v[74:75], v[114:115]
	v_add_f32_dpp v124, v124, v124 quad_perm:[1,0,3,2] row_mask:0xf bank_mask:0xf bound_ctrl:1
	v_pk_mul_f32 v[122:123], v[52:53], v[110:111]
	v_pk_fma_f32 v[122:123], v[50:51], v[108:109], v[122:123]
	ds_read_b128 v[108:111], v0 offset:23296
	v_add_f32_dpp v124, v124, v124 quad_perm:[2,3,0,1] row_mask:0xf bank_mask:0xf bound_ctrl:1
	v_pk_mul_f32 v[116:117], v[100:101], v[90:91] op_sel_hi:[1,0]
	v_pk_mul_f32 v[118:119], v[102:103], v[90:91] op_sel_hi:[1,0]
	v_add_f32_dpp v124, v124, v124 row_half_mirror row_mask:0xf bank_mask:0xf bound_ctrl:1
	v_add_f32_e32 v221, v122, v123
	s_nop 0
	v_add_f32_dpp v124, v124, v124 row_mirror row_mask:0xf bank_mask:0xf bound_ctrl:1
	v_pk_fma_f32 v[50:51], v[80:81], v[124:125], v[112:113] op_sel_hi:[1,0,1]
	v_pk_fma_f32 v[52:53], v[82:83], v[124:125], v[114:115] op_sel_hi:[1,0,1]
	s_waitcnt lgkmcnt(1)
	v_pk_mul_f32 v[120:121], v[52:53], v[94:95]
	v_pk_fma_f32 v[120:121], v[50:51], v[92:93], v[120:121]
	v_add_f32_e32 v124, v120, v121
	v_pk_fma_f32 v[116:117], v[50:51], v[96:97], v[116:117]
	v_pk_fma_f32 v[118:119], v[52:53], v[98:99], v[118:119]
	v_add_f32_dpp v124, v124, v124 quad_perm:[1,0,3,2] row_mask:0xf bank_mask:0xf bound_ctrl:1
	v_pk_mul_f32 v[122:123], v[52:53], v[86:87]
	v_pk_fma_f32 v[122:123], v[50:51], v[84:85], v[122:123]
	v_add_f32_dpp v124, v124, v124 quad_perm:[2,3,0,1] row_mask:0xf bank_mask:0xf bound_ctrl:1
	s_nop 1
	v_add_f32_dpp v124, v124, v124 row_half_mirror row_mask:0xf bank_mask:0xf bound_ctrl:1
	v_add_f32_e32 v222, v122, v123
	s_nop 0
	v_add_f32_dpp v124, v124, v124 row_mirror row_mask:0xf bank_mask:0xf bound_ctrl:1
	v_pk_fma_f32 v[50:51], v[104:105], v[124:125], v[116:117] op_sel_hi:[1,0,1]
	v_pk_fma_f32 v[52:53], v[106:107], v[124:125], v[118:119] op_sel_hi:[1,0,1]
	s_waitcnt lgkmcnt(0)
	v_pk_mul_f32 v[122:123], v[52:53], v[110:111]
	v_pk_fma_f32 v[122:123], v[50:51], v[108:109], v[122:123]
	v_add_f32_e32 v223, v122, v123
	v_cndmask_b32_e64 v68, v216, v220, s[40:41]
	v_cndmask_b32_e64 v72, v220, v216, s[40:41]
	v_cndmask_b32_e64 v69, v217, v221, s[40:41]
	v_cndmask_b32_e64 v73, v221, v217, s[40:41]
	v_cndmask_b32_e64 v70, v218, v222, s[40:41]
	v_cndmask_b32_e64 v74, v222, v218, s[40:41]
	v_cndmask_b32_e64 v71, v219, v223, s[40:41]
	v_cndmask_b32_e64 v75, v223, v219, s[40:41]
	v_add_f32_dpp v68, v72, v68 row_mirror row_mask:0xf bank_mask:0xf bound_ctrl:1
	v_add_f32_dpp v69, v73, v69 row_mirror row_mask:0xf bank_mask:0xf bound_ctrl:1
	v_add_f32_dpp v70, v74, v70 row_mirror row_mask:0xf bank_mask:0xf bound_ctrl:1
	v_add_f32_dpp v71, v75, v71 row_mirror row_mask:0xf bank_mask:0xf bound_ctrl:1
	v_cndmask_b32_e64 v76, v68, v70, s[42:43]
	v_cndmask_b32_e64 v78, v70, v68, s[42:43]
	v_cndmask_b32_e64 v77, v69, v71, s[42:43]
	v_cndmask_b32_e64 v79, v71, v69, s[42:43]
	v_add_u32_e32 v66, s7, v62
	v_add_f32_dpp v76, v78, v76 row_half_mirror row_mask:0xf bank_mask:0xf bound_ctrl:1
	v_add_f32_dpp v77, v79, v77 row_half_mirror row_mask:0xf bank_mask:0xf bound_ctrl:1
	v_cndmask_b32_e64 v80, v76, v77, s[44:45]
	v_cndmask_b32_e64 v81, v77, v76, s[44:45]
	v_ashrrev_i32_e32 v67, 31, v66
	v_lshlrev_b64 v[66:67], 10, v[66:67]
	v_add_f32_dpp v80, v81, v80 quad_perm:[2,3,0,1] row_mask:0xf bank_mask:0xf bound_ctrl:1
	v_lshl_add_u64 v[66:67], v[54:55], 0, v[66:67]
	s_nop 0
	v_add_f32_dpp v65, v80, v80 quad_perm:[1,0,3,2] row_mask:0xf bank_mask:0xf bound_ctrl:1
	s_and_saveexec_b64 s[2:3], vcc
	global_store_dword v[66:67], v65, off
	s_or_b64 exec, exec, s[2:3]
	s_waitcnt lgkmcnt(0)
	s_barrier
	ds_read_b128 v[68:71], v0 offset:0
	ds_read_b128 v[76:79], v0 offset:1280
	ds_read_b32 v88, v56 offset:512
	ds_read_b128 v[72:75], v0 offset:768
	ds_read_b128 v[100:103], v0 offset:2816
	ds_read_b32 v90, v56 offset:2048
	ds_read_b128 v[80:83], v0 offset:1024
	ds_read_b128 v[92:95], v0 offset:1536
	ds_read_b128 v[84:87], v0 offset:256
	ds_read_b128 v[96:99], v0 offset:2304
	ds_read_b128 v[104:107], v0 offset:2560
	s_min_u32 s2, s6, 244
	s_add_i32 s2, s2, 11
	s_mul_i32 s2, s2, s83
	s_add_i32 s2, s2, s31
	s_mulk_i32 s2, 0x300
	s_waitcnt vmcnt(23)
	ds_write_b128 v57, v[26:29] offset:12288
	s_waitcnt vmcnt(22)
	ds_write_b128 v57, v[30:33] offset:16384
	s_waitcnt vmcnt(21)
	ds_write_b128 v57, v[34:37] offset:20480
	v_add_u32_e32 v26, s2, v58
	v_add_u32_e32 v28, s2, v59
	v_add_u32_e32 v34, s2, v60
	v_ashrrev_i32_e32 v27, 31, v26
	v_ashrrev_i32_e32 v29, 31, v28
	v_ashrrev_i32_e32 v35, 31, v34
	v_lshl_add_u64 v[26:27], v[26:27], 2, s[56:57]
	v_lshl_add_u64 v[30:31], v[28:29], 2, s[56:57]
	v_lshl_add_u64 v[34:35], v[34:35], 2, s[56:57]
	global_load_dwordx4 v[26:29], v[26:27], off
	s_nop 0
	global_load_dwordx4 v[30:33], v[30:31], off
	s_nop 0
	global_load_dwordx4 v[34:37], v[34:35], off
	s_waitcnt lgkmcnt(11)
	v_pk_mul_f32 v[112:113], v[76:77], v[88:89] op_sel_hi:[1,0]
	v_pk_mul_f32 v[114:115], v[78:79], v[88:89] op_sel_hi:[1,0]
	ds_read_b128 v[76:79], v0 offset:4352
	ds_read_b32 v88, v56 offset:3584
	s_waitcnt lgkmcnt(9)
	v_pk_mul_f32 v[120:121], v[52:53], v[70:71]
	v_pk_fma_f32 v[120:121], v[50:51], v[68:69], v[120:121]
	ds_read_b128 v[68:71], v0 offset:3072
	v_add_f32_e32 v124, v120, v121
	v_pk_fma_f32 v[112:113], v[50:51], v[72:73], v[112:113]
	v_pk_fma_f32 v[114:115], v[52:53], v[74:75], v[114:115]
	ds_read_b128 v[72:75], v0 offset:3840
	v_add_f32_dpp v124, v124, v124 quad_perm:[1,0,3,2] row_mask:0xf bank_mask:0xf bound_ctrl:1
	ds_read_b128 v[108:111], v0 offset:1792
	s_nop 0
	v_add_f32_dpp v124, v124, v124 quad_perm:[2,3,0,1] row_mask:0xf bank_mask:0xf bound_ctrl:1
	v_pk_mul_f32 v[116:117], v[100:101], v[90:91] op_sel_hi:[1,0]
	v_pk_mul_f32 v[118:119], v[102:103], v[90:91] op_sel_hi:[1,0]
	v_add_f32_dpp v124, v124, v124 row_half_mirror row_mask:0xf bank_mask:0xf bound_ctrl:1
	ds_read_b128 v[100:103], v0 offset:5888
	ds_read_b32 v90, v56 offset:5120
	v_add_f32_dpp v124, v124, v124 row_mirror row_mask:0xf bank_mask:0xf bound_ctrl:1
	v_pk_fma_f32 v[50:51], v[80:81], v[124:125], v[112:113] op_sel_hi:[1,0,1]
	v_pk_fma_f32 v[52:53], v[82:83], v[124:125], v[114:115] op_sel_hi:[1,0,1]
	ds_read_b128 v[80:83], v0 offset:4096
	s_waitcnt lgkmcnt(6)
	v_pk_mul_f32 v[120:121], v[52:53], v[94:95]
	v_pk_fma_f32 v[120:121], v[50:51], v[92:93], v[120:121]
	ds_read_b128 v[92:95], v0 offset:4608
	v_add_f32_e32 v124, v120, v121
	v_pk_fma_f32 v[116:117], v[50:51], v[96:97], v[116:117]
	v_pk_fma_f32 v[118:119], v[52:53], v[98:99], v[118:119]
	ds_read_b128 v[96:99], v0 offset:5376
	v_add_f32_dpp v124, v124, v124 quad_perm:[1,0,3,2] row_mask:0xf bank_mask:0xf bound_ctrl:1
	v_pk_mul_f32 v[122:123], v[52:53], v[86:87]
	v_pk_fma_f32 v[122:123], v[50:51], v[84:85], v[122:123]
	ds_read_b128 v[84:87], v0 offset:3328
	v_add_f32_dpp v124, v124, v124 quad_perm:[2,3,0,1] row_mask:0xf bank_mask:0xf bound_ctrl:1
	v_pk_mul_f32 v[112:113], v[76:77], v[88:89] op_sel_hi:[1,0]
	v_pk_mul_f32 v[114:115], v[78:79], v[88:89] op_sel_hi:[1,0]
	v_add_f32_dpp v124, v124, v124 row_half_mirror row_mask:0xf bank_mask:0xf bound_ctrl:1
	v_add_f32_e32 v216, v122, v123
	ds_read_b128 v[76:79], v0 offset:7424
	ds_read_b32 v88, v56 offset:6656
	v_add_f32_dpp v124, v124, v124 row_mirror row_mask:0xf bank_mask:0xf bound_ctrl:1
	v_pk_fma_f32 v[50:51], v[104:105], v[124:125], v[116:117] op_sel_hi:[1,0,1]
	v_pk_fma_f32 v[52:53], v[106:107], v[124:125], v[118:119] op_sel_hi:[1,0,1]
	ds_read_b128 v[104:107], v0 offset:5632
	s_waitcnt lgkmcnt(6)
	v_pk_mul_f32 v[120:121], v[52:53], v[70:71]
	v_pk_fma_f32 v[120:121], v[50:51], v[68:69], v[120:121]
	ds_read_b128 v[68:71], v0 offset:6144
	v_add_f32_e32 v124, v120, v121
	v_pk_fma_f32 v[112:113], v[50:51], v[72:73], v[112:113]
	v_pk_fma_f32 v[114:115], v[52:53], v[74:75], v[114:115]
	ds_read_b128 v[72:75], v0 offset:6912
	v_add_f32_dpp v124, v124, v124 quad_perm:[1,0,3,2] row_mask:0xf bank_mask:0xf bound_ctrl:1
	v_pk_mul_f32 v[122:123], v[52:53], v[110:111]
	v_pk_fma_f32 v[122:123], v[50:51], v[108:109], v[122:123]
	ds_read_b128 v[108:111], v0 offset:4864
	v_add_f32_dpp v124, v124, v124 quad_perm:[2,3,0,1] row_mask:0xf bank_mask:0xf bound_ctrl:1
	v_pk_mul_f32 v[116:117], v[100:101], v[90:91] op_sel_hi:[1,0]
	v_pk_mul_f32 v[118:119], v[102:103], v[90:91] op_sel_hi:[1,0]
	v_add_f32_dpp v124, v124, v124 row_half_mirror row_mask:0xf bank_mask:0xf bound_ctrl:1
	v_add_f32_e32 v217, v122, v123
	ds_read_b128 v[100:103], v0 offset:8960
	ds_read_b32 v90, v56 offset:8192
	v_add_f32_dpp v124, v124, v124 row_mirror row_mask:0xf bank_mask:0xf bound_ctrl:1
	v_pk_fma_f32 v[50:51], v[80:81], v[124:125], v[112:113] op_sel_hi:[1,0,1]
	v_pk_fma_f32 v[52:53], v[82:83], v[124:125], v[114:115] op_sel_hi:[1,0,1]
	ds_read_b128 v[80:83], v0 offset:7168
	s_waitcnt lgkmcnt(6)
	v_pk_mul_f32 v[120:121], v[52:53], v[94:95]
	v_pk_fma_f32 v[120:121], v[50:51], v[92:93], v[120:121]
	ds_read_b128 v[92:95], v0 offset:7680
	v_add_f32_e32 v124, v120, v121
	v_pk_fma_f32 v[116:117], v[50:51], v[96:97], v[116:117]
	v_pk_fma_f32 v[118:119], v[52:53], v[98:99], v[118:119]
	ds_read_b128 v[96:99], v0 offset:8448
	v_add_f32_dpp v124, v124, v124 quad_perm:[1,0,3,2] row_mask:0xf bank_mask:0xf bound_ctrl:1
	v_pk_mul_f32 v[122:123], v[52:53], v[86:87]
	v_pk_fma_f32 v[122:123], v[50:51], v[84:85], v[122:123]
	ds_read_b128 v[84:87], v0 offset:6400
	v_add_f32_dpp v124, v124, v124 quad_perm:[2,3,0,1] row_mask:0xf bank_mask:0xf bound_ctrl:1
	v_pk_mul_f32 v[112:113], v[76:77], v[88:89] op_sel_hi:[1,0]
	v_pk_mul_f32 v[114:115], v[78:79], v[88:89] op_sel_hi:[1,0]
	v_add_f32_dpp v124, v124, v124 row_half_mirror row_mask:0xf bank_mask:0xf bound_ctrl:1
	v_add_f32_e32 v218, v122, v123
	ds_read_b128 v[76:79], v0 offset:10496
	ds_read_b32 v88, v56 offset:9728
	v_add_f32_dpp v124, v124, v124 row_mirror row_mask:0xf bank_mask:0xf bound_ctrl:1
	v_pk_fma_f32 v[50:51], v[104:105], v[124:125], v[116:117] op_sel_hi:[1,0,1]
	v_pk_fma_f32 v[52:53], v[106:107], v[124:125], v[118:119] op_sel_hi:[1,0,1]
	ds_read_b128 v[104:107], v0 offset:8704
	s_waitcnt lgkmcnt(6)
	v_pk_mul_f32 v[120:121], v[52:53], v[70:71]
	v_pk_fma_f32 v[120:121], v[50:51], v[68:69], v[120:121]
	ds_read_b128 v[68:71], v0 offset:9216
	v_add_f32_e32 v124, v120, v121
	v_pk_fma_f32 v[112:113], v[50:51], v[72:73], v[112:113]
	v_pk_fma_f32 v[114:115], v[52:53], v[74:75], v[114:115]
	ds_read_b128 v[72:75], v0 offset:9984
	v_add_f32_dpp v124, v124, v124 quad_perm:[1,0,3,2] row_mask:0xf bank_mask:0xf bound_ctrl:1
	v_pk_mul_f32 v[122:123], v[52:53], v[110:111]
	v_pk_fma_f32 v[122:123], v[50:51], v[108:109], v[122:123]
	ds_read_b128 v[108:111], v0 offset:7936
	v_add_f32_dpp v124, v124, v124 quad_perm:[2,3,0,1] row_mask:0xf bank_mask:0xf bound_ctrl:1
	v_pk_mul_f32 v[116:117], v[100:101], v[90:91] op_sel_hi:[1,0]
	v_pk_mul_f32 v[118:119], v[102:103], v[90:91] op_sel_hi:[1,0]
	v_add_f32_dpp v124, v124, v124 row_half_mirror row_mask:0xf bank_mask:0xf bound_ctrl:1
	v_add_f32_e32 v219, v122, v123
	ds_read_b128 v[100:103], v0 offset:12032
	ds_read_b32 v90, v56 offset:11264
	v_add_f32_dpp v124, v124, v124 row_mirror row_mask:0xf bank_mask:0xf bound_ctrl:1
	v_pk_fma_f32 v[50:51], v[80:81], v[124:125], v[112:113] op_sel_hi:[1,0,1]
	v_pk_fma_f32 v[52:53], v[82:83], v[124:125], v[114:115] op_sel_hi:[1,0,1]
	ds_read_b128 v[80:83], v0 offset:10240
	s_waitcnt lgkmcnt(6)
	v_pk_mul_f32 v[120:121], v[52:53], v[94:95]
	v_pk_fma_f32 v[120:121], v[50:51], v[92:93], v[120:121]
	ds_read_b128 v[92:95], v0 offset:10752
	v_add_f32_e32 v124, v120, v121
	v_pk_fma_f32 v[116:117], v[50:51], v[96:97], v[116:117]
	v_pk_fma_f32 v[118:119], v[52:53], v[98:99], v[118:119]
	ds_read_b128 v[96:99], v0 offset:11520
	v_add_f32_dpp v124, v124, v124 quad_perm:[1,0,3,2] row_mask:0xf bank_mask:0xf bound_ctrl:1
	v_pk_mul_f32 v[122:123], v[52:53], v[86:87]
	v_pk_fma_f32 v[122:123], v[50:51], v[84:85], v[122:123]
	ds_read_b128 v[84:87], v0 offset:9472
	v_add_f32_dpp v124, v124, v124 quad_perm:[2,3,0,1] row_mask:0xf bank_mask:0xf bound_ctrl:1
	v_pk_mul_f32 v[112:113], v[76:77], v[88:89] op_sel_hi:[1,0]
	v_pk_mul_f32 v[114:115], v[78:79], v[88:89] op_sel_hi:[1,0]
	v_add_f32_dpp v124, v124, v124 row_half_mirror row_mask:0xf bank_mask:0xf bound_ctrl:1
	v_add_f32_e32 v220, v122, v123
	s_nop 0
	v_add_f32_dpp v124, v124, v124 row_mirror row_mask:0xf bank_mask:0xf bound_ctrl:1
	v_pk_fma_f32 v[50:51], v[104:105], v[124:125], v[116:117] op_sel_hi:[1,0,1]
	v_pk_fma_f32 v[52:53], v[106:107], v[124:125], v[118:119] op_sel_hi:[1,0,1]
	ds_read_b128 v[104:107], v0 offset:11776
	s_waitcnt lgkmcnt(4)
	v_pk_mul_f32 v[120:121], v[52:53], v[70:71]
	v_pk_fma_f32 v[120:121], v[50:51], v[68:69], v[120:121]
	v_add_f32_e32 v124, v120, v121
	v_pk_fma_f32 v[112:113], v[50:51], v[72:73], v[112:113]
	v_pk_fma_f32 v[114:115], v[52:53], v[74:75], v[114:115]
	v_add_f32_dpp v124, v124, v124 quad_perm:[1,0,3,2] row_mask:0xf bank_mask:0xf bound_ctrl:1
	v_pk_mul_f32 v[122:123], v[52:53], v[110:111]
	v_pk_fma_f32 v[122:123], v[50:51], v[108:109], v[122:123]
	ds_read_b128 v[108:111], v0 offset:11008
	v_add_f32_dpp v124, v124, v124 quad_perm:[2,3,0,1] row_mask:0xf bank_mask:0xf bound_ctrl:1
	v_pk_mul_f32 v[116:117], v[100:101], v[90:91] op_sel_hi:[1,0]
	v_pk_mul_f32 v[118:119], v[102:103], v[90:91] op_sel_hi:[1,0]
	v_add_f32_dpp v124, v124, v124 row_half_mirror row_mask:0xf bank_mask:0xf bound_ctrl:1
	v_add_f32_e32 v221, v122, v123
	s_nop 0
	v_add_f32_dpp v124, v124, v124 row_mirror row_mask:0xf bank_mask:0xf bound_ctrl:1
	v_pk_fma_f32 v[50:51], v[80:81], v[124:125], v[112:113] op_sel_hi:[1,0,1]
	v_pk_fma_f32 v[52:53], v[82:83], v[124:125], v[114:115] op_sel_hi:[1,0,1]
	s_waitcnt lgkmcnt(1)
	v_pk_mul_f32 v[120:121], v[52:53], v[94:95]
	v_pk_fma_f32 v[120:121], v[50:51], v[92:93], v[120:121]
	v_add_f32_e32 v124, v120, v121
	v_pk_fma_f32 v[116:117], v[50:51], v[96:97], v[116:117]
	v_pk_fma_f32 v[118:119], v[52:53], v[98:99], v[118:119]
	v_add_f32_dpp v124, v124, v124 quad_perm:[1,0,3,2] row_mask:0xf bank_mask:0xf bound_ctrl:1
	v_pk_mul_f32 v[122:123], v[52:53], v[86:87]
	v_pk_fma_f32 v[122:123], v[50:51], v[84:85], v[122:123]
	v_add_f32_dpp v124, v124, v124 quad_perm:[2,3,0,1] row_mask:0xf bank_mask:0xf bound_ctrl:1
	s_nop 1
	v_add_f32_dpp v124, v124, v124 row_half_mirror row_mask:0xf bank_mask:0xf bound_ctrl:1
	v_add_f32_e32 v222, v122, v123
	s_nop 0
	v_add_f32_dpp v124, v124, v124 row_mirror row_mask:0xf bank_mask:0xf bound_ctrl:1
	v_pk_fma_f32 v[50:51], v[104:105], v[124:125], v[116:117] op_sel_hi:[1,0,1]
	v_pk_fma_f32 v[52:53], v[106:107], v[124:125], v[118:119] op_sel_hi:[1,0,1]
	s_waitcnt lgkmcnt(0)
	v_pk_mul_f32 v[122:123], v[52:53], v[110:111]
	v_pk_fma_f32 v[122:123], v[50:51], v[108:109], v[122:123]
	v_add_f32_e32 v223, v122, v123
	v_cndmask_b32_e64 v68, v216, v220, s[40:41]
	v_cndmask_b32_e64 v72, v220, v216, s[40:41]
	v_cndmask_b32_e64 v69, v217, v221, s[40:41]
	v_cndmask_b32_e64 v73, v221, v217, s[40:41]
	v_cndmask_b32_e64 v70, v218, v222, s[40:41]
	v_cndmask_b32_e64 v74, v222, v218, s[40:41]
	v_cndmask_b32_e64 v71, v219, v223, s[40:41]
	v_cndmask_b32_e64 v75, v223, v219, s[40:41]
	v_add_f32_dpp v68, v72, v68 row_mirror row_mask:0xf bank_mask:0xf bound_ctrl:1
	v_add_f32_dpp v69, v73, v69 row_mirror row_mask:0xf bank_mask:0xf bound_ctrl:1
	v_add_f32_dpp v70, v74, v70 row_mirror row_mask:0xf bank_mask:0xf bound_ctrl:1
	v_add_f32_dpp v71, v75, v71 row_mirror row_mask:0xf bank_mask:0xf bound_ctrl:1
	v_cndmask_b32_e64 v76, v68, v70, s[42:43]
	v_cndmask_b32_e64 v78, v70, v68, s[42:43]
	v_cndmask_b32_e64 v77, v69, v71, s[42:43]
	v_cndmask_b32_e64 v79, v71, v69, s[42:43]
	v_add_u32_e32 v66, s7, v63
	v_add_f32_dpp v76, v78, v76 row_half_mirror row_mask:0xf bank_mask:0xf bound_ctrl:1
	v_add_f32_dpp v77, v79, v77 row_half_mirror row_mask:0xf bank_mask:0xf bound_ctrl:1
	v_cndmask_b32_e64 v80, v76, v77, s[44:45]
	v_cndmask_b32_e64 v81, v77, v76, s[44:45]
	v_ashrrev_i32_e32 v67, 31, v66
	v_lshlrev_b64 v[66:67], 10, v[66:67]
	v_add_f32_dpp v80, v81, v80 quad_perm:[2,3,0,1] row_mask:0xf bank_mask:0xf bound_ctrl:1
	v_lshl_add_u64 v[66:67], v[54:55], 0, v[66:67]
	s_nop 0
	v_add_f32_dpp v65, v80, v80 quad_perm:[1,0,3,2] row_mask:0xf bank_mask:0xf bound_ctrl:1
	s_and_saveexec_b64 s[2:3], vcc
	global_store_dword v[66:67], v65, off
	s_or_b64 exec, exec, s[2:3]
	s_waitcnt lgkmcnt(0)
	s_barrier
	ds_read_b128 v[68:71], v0 offset:12288
	ds_read_b128 v[76:79], v0 offset:13568
	ds_read_b32 v88, v56 offset:12800
	ds_read_b128 v[72:75], v0 offset:13056
	ds_read_b128 v[100:103], v0 offset:15104
	ds_read_b32 v90, v56 offset:14336
	ds_read_b128 v[80:83], v0 offset:13312
	ds_read_b128 v[92:95], v0 offset:13824
	ds_read_b128 v[84:87], v0 offset:12544
	ds_read_b128 v[96:99], v0 offset:14592
	ds_read_b128 v[104:107], v0 offset:14848
	s_min_u32 s2, s6, 243
	s_add_i32 s2, s2, 12
	s_mul_i32 s2, s2, s83
	s_add_i32 s2, s2, s31
	s_mulk_i32 s2, 0x300
	s_waitcnt vmcnt(23)
	ds_write_b128 v57, v[38:41] offset:0
	s_waitcnt vmcnt(22)
	ds_write_b128 v57, v[42:45] offset:4096
	s_waitcnt vmcnt(21)
	ds_write_b128 v57, v[46:49] offset:8192
	v_add_u32_e32 v38, s2, v58
	v_add_u32_e32 v40, s2, v59
	v_add_u32_e32 v46, s2, v60
	v_ashrrev_i32_e32 v39, 31, v38
	v_ashrrev_i32_e32 v41, 31, v40
	v_ashrrev_i32_e32 v47, 31, v46
	v_lshl_add_u64 v[38:39], v[38:39], 2, s[56:57]
	v_lshl_add_u64 v[42:43], v[40:41], 2, s[56:57]
	v_lshl_add_u64 v[46:47], v[46:47], 2, s[56:57]
	global_load_dwordx4 v[38:41], v[38:39], off
	s_nop 0
	global_load_dwordx4 v[42:45], v[42:43], off
	s_nop 0
	global_load_dwordx4 v[46:49], v[46:47], off
	s_waitcnt lgkmcnt(11)
	v_pk_mul_f32 v[112:113], v[76:77], v[88:89] op_sel_hi:[1,0]
	v_pk_mul_f32 v[114:115], v[78:79], v[88:89] op_sel_hi:[1,0]
	ds_read_b128 v[76:79], v0 offset:16640
	ds_read_b32 v88, v56 offset:15872
	s_waitcnt lgkmcnt(9)
	v_pk_mul_f32 v[120:121], v[52:53], v[70:71]
	v_pk_fma_f32 v[120:121], v[50:51], v[68:69], v[120:121]
	ds_read_b128 v[68:71], v0 offset:15360
	v_add_f32_e32 v124, v120, v121
	v_pk_fma_f32 v[112:113], v[50:51], v[72:73], v[112:113]
	v_pk_fma_f32 v[114:115], v[52:53], v[74:75], v[114:115]
	ds_read_b128 v[72:75], v0 offset:16128
	v_add_f32_dpp v124, v124, v124 quad_perm:[1,0,3,2] row_mask:0xf bank_mask:0xf bound_ctrl:1
	ds_read_b128 v[108:111], v0 offset:14080
	s_nop 0
	v_add_f32_dpp v124, v124, v124 quad_perm:[2,3,0,1] row_mask:0xf bank_mask:0xf bound_ctrl:1
	v_pk_mul_f32 v[116:117], v[100:101], v[90:91] op_sel_hi:[1,0]
	v_pk_mul_f32 v[118:119], v[102:103], v[90:91] op_sel_hi:[1,0]
	v_add_f32_dpp v124, v124, v124 row_half_mirror row_mask:0xf bank_mask:0xf bound_ctrl:1
	ds_read_b128 v[100:103], v0 offset:18176
	ds_read_b32 v90, v56 offset:17408
	v_add_f32_dpp v124, v124, v124 row_mirror row_mask:0xf bank_mask:0xf bound_ctrl:1
	v_pk_fma_f32 v[50:51], v[80:81], v[124:125], v[112:113] op_sel_hi:[1,0,1]
	v_pk_fma_f32 v[52:53], v[82:83], v[124:125], v[114:115] op_sel_hi:[1,0,1]
	ds_read_b128 v[80:83], v0 offset:16384
	s_waitcnt lgkmcnt(6)
	v_pk_mul_f32 v[120:121], v[52:53], v[94:95]
	v_pk_fma_f32 v[120:121], v[50:51], v[92:93], v[120:121]
	ds_read_b128 v[92:95], v0 offset:16896
	v_add_f32_e32 v124, v120, v121
	v_pk_fma_f32 v[116:117], v[50:51], v[96:97], v[116:117]
	v_pk_fma_f32 v[118:119], v[52:53], v[98:99], v[118:119]
	ds_read_b128 v[96:99], v0 offset:17664
	v_add_f32_dpp v124, v124, v124 quad_perm:[1,0,3,2] row_mask:0xf bank_mask:0xf bound_ctrl:1
	v_pk_mul_f32 v[122:123], v[52:53], v[86:87]
	v_pk_fma_f32 v[122:123], v[50:51], v[84:85], v[122:123]
	ds_read_b128 v[84:87], v0 offset:15616
	v_add_f32_dpp v124, v124, v124 quad_perm:[2,3,0,1] row_mask:0xf bank_mask:0xf bound_ctrl:1
	v_pk_mul_f32 v[112:113], v[76:77], v[88:89] op_sel_hi:[1,0]
	v_pk_mul_f32 v[114:115], v[78:79], v[88:89] op_sel_hi:[1,0]
	v_add_f32_dpp v124, v124, v124 row_half_mirror row_mask:0xf bank_mask:0xf bound_ctrl:1
	v_add_f32_e32 v216, v122, v123
	ds_read_b128 v[76:79], v0 offset:19712
	ds_read_b32 v88, v56 offset:18944
	v_add_f32_dpp v124, v124, v124 row_mirror row_mask:0xf bank_mask:0xf bound_ctrl:1
	v_pk_fma_f32 v[50:51], v[104:105], v[124:125], v[116:117] op_sel_hi:[1,0,1]
	v_pk_fma_f32 v[52:53], v[106:107], v[124:125], v[118:119] op_sel_hi:[1,0,1]
	ds_read_b128 v[104:107], v0 offset:17920
	s_waitcnt lgkmcnt(6)
	v_pk_mul_f32 v[120:121], v[52:53], v[70:71]
	v_pk_fma_f32 v[120:121], v[50:51], v[68:69], v[120:121]
	ds_read_b128 v[68:71], v0 offset:18432
	v_add_f32_e32 v124, v120, v121
	v_pk_fma_f32 v[112:113], v[50:51], v[72:73], v[112:113]
	v_pk_fma_f32 v[114:115], v[52:53], v[74:75], v[114:115]
	ds_read_b128 v[72:75], v0 offset:19200
	v_add_f32_dpp v124, v124, v124 quad_perm:[1,0,3,2] row_mask:0xf bank_mask:0xf bound_ctrl:1
	v_pk_mul_f32 v[122:123], v[52:53], v[110:111]
	v_pk_fma_f32 v[122:123], v[50:51], v[108:109], v[122:123]
	ds_read_b128 v[108:111], v0 offset:17152
	v_add_f32_dpp v124, v124, v124 quad_perm:[2,3,0,1] row_mask:0xf bank_mask:0xf bound_ctrl:1
	v_pk_mul_f32 v[116:117], v[100:101], v[90:91] op_sel_hi:[1,0]
	v_pk_mul_f32 v[118:119], v[102:103], v[90:91] op_sel_hi:[1,0]
	v_add_f32_dpp v124, v124, v124 row_half_mirror row_mask:0xf bank_mask:0xf bound_ctrl:1
	v_add_f32_e32 v217, v122, v123
	ds_read_b128 v[100:103], v0 offset:21248
	ds_read_b32 v90, v56 offset:20480
	v_add_f32_dpp v124, v124, v124 row_mirror row_mask:0xf bank_mask:0xf bound_ctrl:1
	v_pk_fma_f32 v[50:51], v[80:81], v[124:125], v[112:113] op_sel_hi:[1,0,1]
	v_pk_fma_f32 v[52:53], v[82:83], v[124:125], v[114:115] op_sel_hi:[1,0,1]
	ds_read_b128 v[80:83], v0 offset:19456
	s_waitcnt lgkmcnt(6)
	v_pk_mul_f32 v[120:121], v[52:53], v[94:95]
	v_pk_fma_f32 v[120:121], v[50:51], v[92:93], v[120:121]
	ds_read_b128 v[92:95], v0 offset:19968
	v_add_f32_e32 v124, v120, v121
	v_pk_fma_f32 v[116:117], v[50:51], v[96:97], v[116:117]
	v_pk_fma_f32 v[118:119], v[52:53], v[98:99], v[118:119]
	ds_read_b128 v[96:99], v0 offset:20736
	v_add_f32_dpp v124, v124, v124 quad_perm:[1,0,3,2] row_mask:0xf bank_mask:0xf bound_ctrl:1
	v_pk_mul_f32 v[122:123], v[52:53], v[86:87]
	v_pk_fma_f32 v[122:123], v[50:51], v[84:85], v[122:123]
	ds_read_b128 v[84:87], v0 offset:18688
	v_add_f32_dpp v124, v124, v124 quad_perm:[2,3,0,1] row_mask:0xf bank_mask:0xf bound_ctrl:1
	v_pk_mul_f32 v[112:113], v[76:77], v[88:89] op_sel_hi:[1,0]
	v_pk_mul_f32 v[114:115], v[78:79], v[88:89] op_sel_hi:[1,0]
	v_add_f32_dpp v124, v124, v124 row_half_mirror row_mask:0xf bank_mask:0xf bound_ctrl:1
	v_add_f32_e32 v218, v122, v123
	ds_read_b128 v[76:79], v0 offset:22784
	ds_read_b32 v88, v56 offset:22016
	v_add_f32_dpp v124, v124, v124 row_mirror row_mask:0xf bank_mask:0xf bound_ctrl:1
	v_pk_fma_f32 v[50:51], v[104:105], v[124:125], v[116:117] op_sel_hi:[1,0,1]
	v_pk_fma_f32 v[52:53], v[106:107], v[124:125], v[118:119] op_sel_hi:[1,0,1]
	ds_read_b128 v[104:107], v0 offset:20992
	s_waitcnt lgkmcnt(6)
	v_pk_mul_f32 v[120:121], v[52:53], v[70:71]
	v_pk_fma_f32 v[120:121], v[50:51], v[68:69], v[120:121]
	ds_read_b128 v[68:71], v0 offset:21504
	v_add_f32_e32 v124, v120, v121
	v_pk_fma_f32 v[112:113], v[50:51], v[72:73], v[112:113]
	v_pk_fma_f32 v[114:115], v[52:53], v[74:75], v[114:115]
	ds_read_b128 v[72:75], v0 offset:22272
	v_add_f32_dpp v124, v124, v124 quad_perm:[1,0,3,2] row_mask:0xf bank_mask:0xf bound_ctrl:1
	v_pk_mul_f32 v[122:123], v[52:53], v[110:111]
	v_pk_fma_f32 v[122:123], v[50:51], v[108:109], v[122:123]
	ds_read_b128 v[108:111], v0 offset:20224
	v_add_f32_dpp v124, v124, v124 quad_perm:[2,3,0,1] row_mask:0xf bank_mask:0xf bound_ctrl:1
	v_pk_mul_f32 v[116:117], v[100:101], v[90:91] op_sel_hi:[1,0]
	v_pk_mul_f32 v[118:119], v[102:103], v[90:91] op_sel_hi:[1,0]
	v_add_f32_dpp v124, v124, v124 row_half_mirror row_mask:0xf bank_mask:0xf bound_ctrl:1
	v_add_f32_e32 v219, v122, v123
	ds_read_b128 v[100:103], v0 offset:24320
	ds_read_b32 v90, v56 offset:23552
	v_add_f32_dpp v124, v124, v124 row_mirror row_mask:0xf bank_mask:0xf bound_ctrl:1
	v_pk_fma_f32 v[50:51], v[80:81], v[124:125], v[112:113] op_sel_hi:[1,0,1]
	v_pk_fma_f32 v[52:53], v[82:83], v[124:125], v[114:115] op_sel_hi:[1,0,1]
	ds_read_b128 v[80:83], v0 offset:22528
	s_waitcnt lgkmcnt(6)
	v_pk_mul_f32 v[120:121], v[52:53], v[94:95]
	v_pk_fma_f32 v[120:121], v[50:51], v[92:93], v[120:121]
	ds_read_b128 v[92:95], v0 offset:23040
	v_add_f32_e32 v124, v120, v121
	v_pk_fma_f32 v[116:117], v[50:51], v[96:97], v[116:117]
	v_pk_fma_f32 v[118:119], v[52:53], v[98:99], v[118:119]
	ds_read_b128 v[96:99], v0 offset:23808
	v_add_f32_dpp v124, v124, v124 quad_perm:[1,0,3,2] row_mask:0xf bank_mask:0xf bound_ctrl:1
	v_pk_mul_f32 v[122:123], v[52:53], v[86:87]
	v_pk_fma_f32 v[122:123], v[50:51], v[84:85], v[122:123]
	ds_read_b128 v[84:87], v0 offset:21760
	v_add_f32_dpp v124, v124, v124 quad_perm:[2,3,0,1] row_mask:0xf bank_mask:0xf bound_ctrl:1
	v_pk_mul_f32 v[112:113], v[76:77], v[88:89] op_sel_hi:[1,0]
	v_pk_mul_f32 v[114:115], v[78:79], v[88:89] op_sel_hi:[1,0]
	v_add_f32_dpp v124, v124, v124 row_half_mirror row_mask:0xf bank_mask:0xf bound_ctrl:1
	v_add_f32_e32 v220, v122, v123
	s_nop 0
	v_add_f32_dpp v124, v124, v124 row_mirror row_mask:0xf bank_mask:0xf bound_ctrl:1
	v_pk_fma_f32 v[50:51], v[104:105], v[124:125], v[116:117] op_sel_hi:[1,0,1]
	v_pk_fma_f32 v[52:53], v[106:107], v[124:125], v[118:119] op_sel_hi:[1,0,1]
	ds_read_b128 v[104:107], v0 offset:24064
	s_waitcnt lgkmcnt(4)
	v_pk_mul_f32 v[120:121], v[52:53], v[70:71]
	v_pk_fma_f32 v[120:121], v[50:51], v[68:69], v[120:121]
	v_add_f32_e32 v124, v120, v121
	v_pk_fma_f32 v[112:113], v[50:51], v[72:73], v[112:113]
	v_pk_fma_f32 v[114:115], v[52:53], v[74:75], v[114:115]
	v_add_f32_dpp v124, v124, v124 quad_perm:[1,0,3,2] row_mask:0xf bank_mask:0xf bound_ctrl:1
	v_pk_mul_f32 v[122:123], v[52:53], v[110:111]
	v_pk_fma_f32 v[122:123], v[50:51], v[108:109], v[122:123]
	ds_read_b128 v[108:111], v0 offset:23296
	v_add_f32_dpp v124, v124, v124 quad_perm:[2,3,0,1] row_mask:0xf bank_mask:0xf bound_ctrl:1
	v_pk_mul_f32 v[116:117], v[100:101], v[90:91] op_sel_hi:[1,0]
	v_pk_mul_f32 v[118:119], v[102:103], v[90:91] op_sel_hi:[1,0]
	v_add_f32_dpp v124, v124, v124 row_half_mirror row_mask:0xf bank_mask:0xf bound_ctrl:1
	v_add_f32_e32 v221, v122, v123
	s_nop 0
	v_add_f32_dpp v124, v124, v124 row_mirror row_mask:0xf bank_mask:0xf bound_ctrl:1
	v_pk_fma_f32 v[50:51], v[80:81], v[124:125], v[112:113] op_sel_hi:[1,0,1]
	v_pk_fma_f32 v[52:53], v[82:83], v[124:125], v[114:115] op_sel_hi:[1,0,1]
	s_waitcnt lgkmcnt(1)
	v_pk_mul_f32 v[120:121], v[52:53], v[94:95]
	v_pk_fma_f32 v[120:121], v[50:51], v[92:93], v[120:121]
	v_add_f32_e32 v124, v120, v121
	v_pk_fma_f32 v[116:117], v[50:51], v[96:97], v[116:117]
	v_pk_fma_f32 v[118:119], v[52:53], v[98:99], v[118:119]
	v_add_f32_dpp v124, v124, v124 quad_perm:[1,0,3,2] row_mask:0xf bank_mask:0xf bound_ctrl:1
	v_pk_mul_f32 v[122:123], v[52:53], v[86:87]
	v_pk_fma_f32 v[122:123], v[50:51], v[84:85], v[122:123]
	v_add_f32_dpp v124, v124, v124 quad_perm:[2,3,0,1] row_mask:0xf bank_mask:0xf bound_ctrl:1
	s_nop 1
	v_add_f32_dpp v124, v124, v124 row_half_mirror row_mask:0xf bank_mask:0xf bound_ctrl:1
	v_add_f32_e32 v222, v122, v123
	s_nop 0
	v_add_f32_dpp v124, v124, v124 row_mirror row_mask:0xf bank_mask:0xf bound_ctrl:1
	v_pk_fma_f32 v[50:51], v[104:105], v[124:125], v[116:117] op_sel_hi:[1,0,1]
	v_pk_fma_f32 v[52:53], v[106:107], v[124:125], v[118:119] op_sel_hi:[1,0,1]
	s_waitcnt lgkmcnt(0)
	v_pk_mul_f32 v[122:123], v[52:53], v[110:111]
	v_pk_fma_f32 v[122:123], v[50:51], v[108:109], v[122:123]
	v_add_f32_e32 v223, v122, v123
	v_cndmask_b32_e64 v68, v216, v220, s[40:41]
	v_cndmask_b32_e64 v72, v220, v216, s[40:41]
	v_cndmask_b32_e64 v69, v217, v221, s[40:41]
	v_cndmask_b32_e64 v73, v221, v217, s[40:41]
	v_cndmask_b32_e64 v70, v218, v222, s[40:41]
	v_cndmask_b32_e64 v74, v222, v218, s[40:41]
	v_cndmask_b32_e64 v71, v219, v223, s[40:41]
	v_cndmask_b32_e64 v75, v223, v219, s[40:41]
	v_add_f32_dpp v68, v72, v68 row_mirror row_mask:0xf bank_mask:0xf bound_ctrl:1
	v_add_f32_dpp v69, v73, v69 row_mirror row_mask:0xf bank_mask:0xf bound_ctrl:1
	v_add_f32_dpp v70, v74, v70 row_mirror row_mask:0xf bank_mask:0xf bound_ctrl:1
	v_add_f32_dpp v71, v75, v71 row_mirror row_mask:0xf bank_mask:0xf bound_ctrl:1
	v_cndmask_b32_e64 v76, v68, v70, s[42:43]
	v_cndmask_b32_e64 v78, v70, v68, s[42:43]
	v_cndmask_b32_e64 v77, v69, v71, s[42:43]
	v_cndmask_b32_e64 v79, v71, v69, s[42:43]
	v_add_u32_e32 v66, s7, v64
	v_add_f32_dpp v76, v78, v76 row_half_mirror row_mask:0xf bank_mask:0xf bound_ctrl:1
	v_add_f32_dpp v77, v79, v77 row_half_mirror row_mask:0xf bank_mask:0xf bound_ctrl:1
	v_cndmask_b32_e64 v80, v76, v77, s[44:45]
	v_cndmask_b32_e64 v81, v77, v76, s[44:45]
	v_ashrrev_i32_e32 v67, 31, v66
	v_lshlrev_b64 v[66:67], 10, v[66:67]
	v_add_f32_dpp v80, v81, v80 quad_perm:[2,3,0,1] row_mask:0xf bank_mask:0xf bound_ctrl:1
	v_lshl_add_u64 v[66:67], v[54:55], 0, v[66:67]
	s_nop 0
	v_add_f32_dpp v65, v80, v80 quad_perm:[1,0,3,2] row_mask:0xf bank_mask:0xf bound_ctrl:1
	s_and_saveexec_b64 s[2:3], vcc
	global_store_dword v[66:67], v65, off
	s_or_b64 exec, exec, s[2:3]
	s_waitcnt lgkmcnt(0)
	s_barrier
	ds_read_b128 v[68:71], v0 offset:0
	ds_read_b128 v[76:79], v0 offset:1280
	ds_read_b32 v88, v56 offset:512
	ds_read_b128 v[72:75], v0 offset:768
	ds_read_b128 v[100:103], v0 offset:2816
	ds_read_b32 v90, v56 offset:2048
	ds_read_b128 v[80:83], v0 offset:1024
	ds_read_b128 v[92:95], v0 offset:1536
	ds_read_b128 v[84:87], v0 offset:256
	ds_read_b128 v[96:99], v0 offset:2304
	ds_read_b128 v[104:107], v0 offset:2560
	s_min_u32 s2, s6, 242
	s_add_i32 s2, s2, 13
	s_mul_i32 s2, s2, s83
	s_add_i32 s2, s2, s31
	s_mulk_i32 s2, 0x300
	s_waitcnt vmcnt(23)
	ds_write_b128 v57, v[134:137] offset:12288
	s_waitcnt vmcnt(22)
	ds_write_b128 v57, v[138:141] offset:16384
	s_waitcnt vmcnt(21)
	ds_write_b128 v57, v[142:145] offset:20480
	v_add_u32_e32 v134, s2, v58
	v_add_u32_e32 v136, s2, v59
	v_add_u32_e32 v142, s2, v60
	v_ashrrev_i32_e32 v135, 31, v134
	v_ashrrev_i32_e32 v137, 31, v136
	v_ashrrev_i32_e32 v143, 31, v142
	v_lshl_add_u64 v[134:135], v[134:135], 2, s[56:57]
	v_lshl_add_u64 v[138:139], v[136:137], 2, s[56:57]
	v_lshl_add_u64 v[142:143], v[142:143], 2, s[56:57]
	global_load_dwordx4 v[134:137], v[134:135], off
	s_nop 0
	global_load_dwordx4 v[138:141], v[138:139], off
	s_nop 0
	global_load_dwordx4 v[142:145], v[142:143], off
	s_waitcnt lgkmcnt(11)
	v_pk_mul_f32 v[112:113], v[76:77], v[88:89] op_sel_hi:[1,0]
	v_pk_mul_f32 v[114:115], v[78:79], v[88:89] op_sel_hi:[1,0]
	ds_read_b128 v[76:79], v0 offset:4352
	ds_read_b32 v88, v56 offset:3584
	s_waitcnt lgkmcnt(9)
	v_pk_mul_f32 v[120:121], v[52:53], v[70:71]
	v_pk_fma_f32 v[120:121], v[50:51], v[68:69], v[120:121]
	ds_read_b128 v[68:71], v0 offset:3072
	v_add_f32_e32 v124, v120, v121
	v_pk_fma_f32 v[112:113], v[50:51], v[72:73], v[112:113]
	v_pk_fma_f32 v[114:115], v[52:53], v[74:75], v[114:115]
	ds_read_b128 v[72:75], v0 offset:3840
	v_add_f32_dpp v124, v124, v124 quad_perm:[1,0,3,2] row_mask:0xf bank_mask:0xf bound_ctrl:1
	ds_read_b128 v[108:111], v0 offset:1792
	s_nop 0
	v_add_f32_dpp v124, v124, v124 quad_perm:[2,3,0,1] row_mask:0xf bank_mask:0xf bound_ctrl:1
	v_pk_mul_f32 v[116:117], v[100:101], v[90:91] op_sel_hi:[1,0]
	v_pk_mul_f32 v[118:119], v[102:103], v[90:91] op_sel_hi:[1,0]
	v_add_f32_dpp v124, v124, v124 row_half_mirror row_mask:0xf bank_mask:0xf bound_ctrl:1
	ds_read_b128 v[100:103], v0 offset:5888
	ds_read_b32 v90, v56 offset:5120
	v_add_f32_dpp v124, v124, v124 row_mirror row_mask:0xf bank_mask:0xf bound_ctrl:1
	v_pk_fma_f32 v[50:51], v[80:81], v[124:125], v[112:113] op_sel_hi:[1,0,1]
	v_pk_fma_f32 v[52:53], v[82:83], v[124:125], v[114:115] op_sel_hi:[1,0,1]
	ds_read_b128 v[80:83], v0 offset:4096
	s_waitcnt lgkmcnt(6)
	v_pk_mul_f32 v[120:121], v[52:53], v[94:95]
	v_pk_fma_f32 v[120:121], v[50:51], v[92:93], v[120:121]
	ds_read_b128 v[92:95], v0 offset:4608
	v_add_f32_e32 v124, v120, v121
	v_pk_fma_f32 v[116:117], v[50:51], v[96:97], v[116:117]
	v_pk_fma_f32 v[118:119], v[52:53], v[98:99], v[118:119]
	ds_read_b128 v[96:99], v0 offset:5376
	v_add_f32_dpp v124, v124, v124 quad_perm:[1,0,3,2] row_mask:0xf bank_mask:0xf bound_ctrl:1
	v_pk_mul_f32 v[122:123], v[52:53], v[86:87]
	v_pk_fma_f32 v[122:123], v[50:51], v[84:85], v[122:123]
	ds_read_b128 v[84:87], v0 offset:3328
	v_add_f32_dpp v124, v124, v124 quad_perm:[2,3,0,1] row_mask:0xf bank_mask:0xf bound_ctrl:1
	v_pk_mul_f32 v[112:113], v[76:77], v[88:89] op_sel_hi:[1,0]
	v_pk_mul_f32 v[114:115], v[78:79], v[88:89] op_sel_hi:[1,0]
	v_add_f32_dpp v124, v124, v124 row_half_mirror row_mask:0xf bank_mask:0xf bound_ctrl:1
	v_add_f32_e32 v216, v122, v123
	ds_read_b128 v[76:79], v0 offset:7424
	ds_read_b32 v88, v56 offset:6656
	v_add_f32_dpp v124, v124, v124 row_mirror row_mask:0xf bank_mask:0xf bound_ctrl:1
	v_pk_fma_f32 v[50:51], v[104:105], v[124:125], v[116:117] op_sel_hi:[1,0,1]
	v_pk_fma_f32 v[52:53], v[106:107], v[124:125], v[118:119] op_sel_hi:[1,0,1]
	ds_read_b128 v[104:107], v0 offset:5632
	s_waitcnt lgkmcnt(6)
	v_pk_mul_f32 v[120:121], v[52:53], v[70:71]
	v_pk_fma_f32 v[120:121], v[50:51], v[68:69], v[120:121]
	ds_read_b128 v[68:71], v0 offset:6144
	v_add_f32_e32 v124, v120, v121
	v_pk_fma_f32 v[112:113], v[50:51], v[72:73], v[112:113]
	v_pk_fma_f32 v[114:115], v[52:53], v[74:75], v[114:115]
	ds_read_b128 v[72:75], v0 offset:6912
	v_add_f32_dpp v124, v124, v124 quad_perm:[1,0,3,2] row_mask:0xf bank_mask:0xf bound_ctrl:1
	v_pk_mul_f32 v[122:123], v[52:53], v[110:111]
	v_pk_fma_f32 v[122:123], v[50:51], v[108:109], v[122:123]
	ds_read_b128 v[108:111], v0 offset:4864
	v_add_f32_dpp v124, v124, v124 quad_perm:[2,3,0,1] row_mask:0xf bank_mask:0xf bound_ctrl:1
	v_pk_mul_f32 v[116:117], v[100:101], v[90:91] op_sel_hi:[1,0]
	v_pk_mul_f32 v[118:119], v[102:103], v[90:91] op_sel_hi:[1,0]
	v_add_f32_dpp v124, v124, v124 row_half_mirror row_mask:0xf bank_mask:0xf bound_ctrl:1
	v_add_f32_e32 v217, v122, v123
	ds_read_b128 v[100:103], v0 offset:8960
	ds_read_b32 v90, v56 offset:8192
	v_add_f32_dpp v124, v124, v124 row_mirror row_mask:0xf bank_mask:0xf bound_ctrl:1
	v_pk_fma_f32 v[50:51], v[80:81], v[124:125], v[112:113] op_sel_hi:[1,0,1]
	v_pk_fma_f32 v[52:53], v[82:83], v[124:125], v[114:115] op_sel_hi:[1,0,1]
	ds_read_b128 v[80:83], v0 offset:7168
	s_waitcnt lgkmcnt(6)
	v_pk_mul_f32 v[120:121], v[52:53], v[94:95]
	v_pk_fma_f32 v[120:121], v[50:51], v[92:93], v[120:121]
	ds_read_b128 v[92:95], v0 offset:7680
	v_add_f32_e32 v124, v120, v121
	v_pk_fma_f32 v[116:117], v[50:51], v[96:97], v[116:117]
	v_pk_fma_f32 v[118:119], v[52:53], v[98:99], v[118:119]
	ds_read_b128 v[96:99], v0 offset:8448
	v_add_f32_dpp v124, v124, v124 quad_perm:[1,0,3,2] row_mask:0xf bank_mask:0xf bound_ctrl:1
	v_pk_mul_f32 v[122:123], v[52:53], v[86:87]
	v_pk_fma_f32 v[122:123], v[50:51], v[84:85], v[122:123]
	ds_read_b128 v[84:87], v0 offset:6400
	v_add_f32_dpp v124, v124, v124 quad_perm:[2,3,0,1] row_mask:0xf bank_mask:0xf bound_ctrl:1
	v_pk_mul_f32 v[112:113], v[76:77], v[88:89] op_sel_hi:[1,0]
	v_pk_mul_f32 v[114:115], v[78:79], v[88:89] op_sel_hi:[1,0]
	v_add_f32_dpp v124, v124, v124 row_half_mirror row_mask:0xf bank_mask:0xf bound_ctrl:1
	v_add_f32_e32 v218, v122, v123
	ds_read_b128 v[76:79], v0 offset:10496
	ds_read_b32 v88, v56 offset:9728
	v_add_f32_dpp v124, v124, v124 row_mirror row_mask:0xf bank_mask:0xf bound_ctrl:1
	v_pk_fma_f32 v[50:51], v[104:105], v[124:125], v[116:117] op_sel_hi:[1,0,1]
	v_pk_fma_f32 v[52:53], v[106:107], v[124:125], v[118:119] op_sel_hi:[1,0,1]
	ds_read_b128 v[104:107], v0 offset:8704
	s_waitcnt lgkmcnt(6)
	v_pk_mul_f32 v[120:121], v[52:53], v[70:71]
	v_pk_fma_f32 v[120:121], v[50:51], v[68:69], v[120:121]
	ds_read_b128 v[68:71], v0 offset:9216
	v_add_f32_e32 v124, v120, v121
	v_pk_fma_f32 v[112:113], v[50:51], v[72:73], v[112:113]
	v_pk_fma_f32 v[114:115], v[52:53], v[74:75], v[114:115]
	ds_read_b128 v[72:75], v0 offset:9984
	v_add_f32_dpp v124, v124, v124 quad_perm:[1,0,3,2] row_mask:0xf bank_mask:0xf bound_ctrl:1
	v_pk_mul_f32 v[122:123], v[52:53], v[110:111]
	v_pk_fma_f32 v[122:123], v[50:51], v[108:109], v[122:123]
	ds_read_b128 v[108:111], v0 offset:7936
	v_add_f32_dpp v124, v124, v124 quad_perm:[2,3,0,1] row_mask:0xf bank_mask:0xf bound_ctrl:1
	v_pk_mul_f32 v[116:117], v[100:101], v[90:91] op_sel_hi:[1,0]
	v_pk_mul_f32 v[118:119], v[102:103], v[90:91] op_sel_hi:[1,0]
	v_add_f32_dpp v124, v124, v124 row_half_mirror row_mask:0xf bank_mask:0xf bound_ctrl:1
	v_add_f32_e32 v219, v122, v123
	ds_read_b128 v[100:103], v0 offset:12032
	ds_read_b32 v90, v56 offset:11264
	v_add_f32_dpp v124, v124, v124 row_mirror row_mask:0xf bank_mask:0xf bound_ctrl:1
	v_pk_fma_f32 v[50:51], v[80:81], v[124:125], v[112:113] op_sel_hi:[1,0,1]
	v_pk_fma_f32 v[52:53], v[82:83], v[124:125], v[114:115] op_sel_hi:[1,0,1]
	ds_read_b128 v[80:83], v0 offset:10240
	s_waitcnt lgkmcnt(6)
	v_pk_mul_f32 v[120:121], v[52:53], v[94:95]
	v_pk_fma_f32 v[120:121], v[50:51], v[92:93], v[120:121]
	ds_read_b128 v[92:95], v0 offset:10752
	v_add_f32_e32 v124, v120, v121
	v_pk_fma_f32 v[116:117], v[50:51], v[96:97], v[116:117]
	v_pk_fma_f32 v[118:119], v[52:53], v[98:99], v[118:119]
	ds_read_b128 v[96:99], v0 offset:11520
	v_add_f32_dpp v124, v124, v124 quad_perm:[1,0,3,2] row_mask:0xf bank_mask:0xf bound_ctrl:1
	v_pk_mul_f32 v[122:123], v[52:53], v[86:87]
	v_pk_fma_f32 v[122:123], v[50:51], v[84:85], v[122:123]
	ds_read_b128 v[84:87], v0 offset:9472
	v_add_f32_dpp v124, v124, v124 quad_perm:[2,3,0,1] row_mask:0xf bank_mask:0xf bound_ctrl:1
	v_pk_mul_f32 v[112:113], v[76:77], v[88:89] op_sel_hi:[1,0]
	v_pk_mul_f32 v[114:115], v[78:79], v[88:89] op_sel_hi:[1,0]
	v_add_f32_dpp v124, v124, v124 row_half_mirror row_mask:0xf bank_mask:0xf bound_ctrl:1
	v_add_f32_e32 v220, v122, v123
	s_nop 0
	v_add_f32_dpp v124, v124, v124 row_mirror row_mask:0xf bank_mask:0xf bound_ctrl:1
	v_pk_fma_f32 v[50:51], v[104:105], v[124:125], v[116:117] op_sel_hi:[1,0,1]
	v_pk_fma_f32 v[52:53], v[106:107], v[124:125], v[118:119] op_sel_hi:[1,0,1]
	ds_read_b128 v[104:107], v0 offset:11776
	s_waitcnt lgkmcnt(4)
	v_pk_mul_f32 v[120:121], v[52:53], v[70:71]
	v_pk_fma_f32 v[120:121], v[50:51], v[68:69], v[120:121]
	v_add_f32_e32 v124, v120, v121
	v_pk_fma_f32 v[112:113], v[50:51], v[72:73], v[112:113]
	v_pk_fma_f32 v[114:115], v[52:53], v[74:75], v[114:115]
	v_add_f32_dpp v124, v124, v124 quad_perm:[1,0,3,2] row_mask:0xf bank_mask:0xf bound_ctrl:1
	v_pk_mul_f32 v[122:123], v[52:53], v[110:111]
	v_pk_fma_f32 v[122:123], v[50:51], v[108:109], v[122:123]
	ds_read_b128 v[108:111], v0 offset:11008
	v_add_f32_dpp v124, v124, v124 quad_perm:[2,3,0,1] row_mask:0xf bank_mask:0xf bound_ctrl:1
	v_pk_mul_f32 v[116:117], v[100:101], v[90:91] op_sel_hi:[1,0]
	v_pk_mul_f32 v[118:119], v[102:103], v[90:91] op_sel_hi:[1,0]
	v_add_f32_dpp v124, v124, v124 row_half_mirror row_mask:0xf bank_mask:0xf bound_ctrl:1
	v_add_f32_e32 v221, v122, v123
	s_nop 0
	v_add_f32_dpp v124, v124, v124 row_mirror row_mask:0xf bank_mask:0xf bound_ctrl:1
	v_pk_fma_f32 v[50:51], v[80:81], v[124:125], v[112:113] op_sel_hi:[1,0,1]
	v_pk_fma_f32 v[52:53], v[82:83], v[124:125], v[114:115] op_sel_hi:[1,0,1]
	s_waitcnt lgkmcnt(1)
	v_pk_mul_f32 v[120:121], v[52:53], v[94:95]
	v_pk_fma_f32 v[120:121], v[50:51], v[92:93], v[120:121]
	v_add_f32_e32 v124, v120, v121
	v_pk_fma_f32 v[116:117], v[50:51], v[96:97], v[116:117]
	v_pk_fma_f32 v[118:119], v[52:53], v[98:99], v[118:119]
	v_add_f32_dpp v124, v124, v124 quad_perm:[1,0,3,2] row_mask:0xf bank_mask:0xf bound_ctrl:1
	v_pk_mul_f32 v[122:123], v[52:53], v[86:87]
	v_pk_fma_f32 v[122:123], v[50:51], v[84:85], v[122:123]
	v_add_f32_dpp v124, v124, v124 quad_perm:[2,3,0,1] row_mask:0xf bank_mask:0xf bound_ctrl:1
	s_nop 1
	v_add_f32_dpp v124, v124, v124 row_half_mirror row_mask:0xf bank_mask:0xf bound_ctrl:1
	v_add_f32_e32 v222, v122, v123
	s_nop 0
	v_add_f32_dpp v124, v124, v124 row_mirror row_mask:0xf bank_mask:0xf bound_ctrl:1
	v_pk_fma_f32 v[50:51], v[104:105], v[124:125], v[116:117] op_sel_hi:[1,0,1]
	v_pk_fma_f32 v[52:53], v[106:107], v[124:125], v[118:119] op_sel_hi:[1,0,1]
	s_waitcnt lgkmcnt(0)
	v_pk_mul_f32 v[122:123], v[52:53], v[110:111]
	v_pk_fma_f32 v[122:123], v[50:51], v[108:109], v[122:123]
	v_add_f32_e32 v223, v122, v123
	v_cndmask_b32_e64 v68, v216, v220, s[40:41]
	v_cndmask_b32_e64 v72, v220, v216, s[40:41]
	v_cndmask_b32_e64 v69, v217, v221, s[40:41]
	v_cndmask_b32_e64 v73, v221, v217, s[40:41]
	v_cndmask_b32_e64 v70, v218, v222, s[40:41]
	v_cndmask_b32_e64 v74, v222, v218, s[40:41]
	v_cndmask_b32_e64 v71, v219, v223, s[40:41]
	v_cndmask_b32_e64 v75, v223, v219, s[40:41]
	v_add_f32_dpp v68, v72, v68 row_mirror row_mask:0xf bank_mask:0xf bound_ctrl:1
	v_add_f32_dpp v69, v73, v69 row_mirror row_mask:0xf bank_mask:0xf bound_ctrl:1
	v_add_f32_dpp v70, v74, v70 row_mirror row_mask:0xf bank_mask:0xf bound_ctrl:1
	v_add_f32_dpp v71, v75, v71 row_mirror row_mask:0xf bank_mask:0xf bound_ctrl:1
	v_cndmask_b32_e64 v76, v68, v70, s[42:43]
	v_cndmask_b32_e64 v78, v70, v68, s[42:43]
	v_cndmask_b32_e64 v77, v69, v71, s[42:43]
	v_cndmask_b32_e64 v79, v71, v69, s[42:43]
	v_add_u32_e32 v66, s100, v61
	v_add_f32_dpp v76, v78, v76 row_half_mirror row_mask:0xf bank_mask:0xf bound_ctrl:1
	v_add_f32_dpp v77, v79, v77 row_half_mirror row_mask:0xf bank_mask:0xf bound_ctrl:1
	v_cndmask_b32_e64 v80, v76, v77, s[44:45]
	v_cndmask_b32_e64 v81, v77, v76, s[44:45]
	v_ashrrev_i32_e32 v67, 31, v66
	v_lshlrev_b64 v[66:67], 10, v[66:67]
	v_add_f32_dpp v80, v81, v80 quad_perm:[2,3,0,1] row_mask:0xf bank_mask:0xf bound_ctrl:1
	v_lshl_add_u64 v[66:67], v[54:55], 0, v[66:67]
	s_nop 0
	v_add_f32_dpp v65, v80, v80 quad_perm:[1,0,3,2] row_mask:0xf bank_mask:0xf bound_ctrl:1
	s_and_saveexec_b64 s[2:3], vcc
	global_store_dword v[66:67], v65, off
	s_or_b64 exec, exec, s[2:3]
	s_waitcnt lgkmcnt(0)
	s_barrier
	ds_read_b128 v[68:71], v0 offset:12288
	ds_read_b128 v[76:79], v0 offset:13568
	ds_read_b32 v88, v56 offset:12800
	ds_read_b128 v[72:75], v0 offset:13056
	ds_read_b128 v[100:103], v0 offset:15104
	ds_read_b32 v90, v56 offset:14336
	ds_read_b128 v[80:83], v0 offset:13312
	ds_read_b128 v[92:95], v0 offset:13824
	ds_read_b128 v[84:87], v0 offset:12544
	ds_read_b128 v[96:99], v0 offset:14592
	ds_read_b128 v[104:107], v0 offset:14848
	s_min_u32 s2, s6, 241
	s_add_i32 s2, s2, 14
	s_mul_i32 s2, s2, s83
	s_add_i32 s2, s2, s31
	s_mulk_i32 s2, 0x300
	s_waitcnt vmcnt(23)
	ds_write_b128 v57, v[180:183] offset:0
	s_waitcnt vmcnt(22)
	ds_write_b128 v57, v[184:187] offset:4096
	s_waitcnt vmcnt(21)
	ds_write_b128 v57, v[188:191] offset:8192
	v_add_u32_e32 v180, s2, v58
	v_add_u32_e32 v182, s2, v59
	v_add_u32_e32 v188, s2, v60
	v_ashrrev_i32_e32 v181, 31, v180
	v_ashrrev_i32_e32 v183, 31, v182
	v_ashrrev_i32_e32 v189, 31, v188
	v_lshl_add_u64 v[180:181], v[180:181], 2, s[56:57]
	v_lshl_add_u64 v[184:185], v[182:183], 2, s[56:57]
	v_lshl_add_u64 v[188:189], v[188:189], 2, s[56:57]
	global_load_dwordx4 v[180:183], v[180:181], off
	s_nop 0
	global_load_dwordx4 v[184:187], v[184:185], off
	s_nop 0
	global_load_dwordx4 v[188:191], v[188:189], off
	s_waitcnt lgkmcnt(11)
	v_pk_mul_f32 v[112:113], v[76:77], v[88:89] op_sel_hi:[1,0]
	v_pk_mul_f32 v[114:115], v[78:79], v[88:89] op_sel_hi:[1,0]
	ds_read_b128 v[76:79], v0 offset:16640
	ds_read_b32 v88, v56 offset:15872
	s_waitcnt lgkmcnt(9)
	v_pk_mul_f32 v[120:121], v[52:53], v[70:71]
	v_pk_fma_f32 v[120:121], v[50:51], v[68:69], v[120:121]
	ds_read_b128 v[68:71], v0 offset:15360
	v_add_f32_e32 v124, v120, v121
	v_pk_fma_f32 v[112:113], v[50:51], v[72:73], v[112:113]
	v_pk_fma_f32 v[114:115], v[52:53], v[74:75], v[114:115]
	ds_read_b128 v[72:75], v0 offset:16128
	v_add_f32_dpp v124, v124, v124 quad_perm:[1,0,3,2] row_mask:0xf bank_mask:0xf bound_ctrl:1
	ds_read_b128 v[108:111], v0 offset:14080
	s_nop 0
	v_add_f32_dpp v124, v124, v124 quad_perm:[2,3,0,1] row_mask:0xf bank_mask:0xf bound_ctrl:1
	v_pk_mul_f32 v[116:117], v[100:101], v[90:91] op_sel_hi:[1,0]
	v_pk_mul_f32 v[118:119], v[102:103], v[90:91] op_sel_hi:[1,0]
	v_add_f32_dpp v124, v124, v124 row_half_mirror row_mask:0xf bank_mask:0xf bound_ctrl:1
	ds_read_b128 v[100:103], v0 offset:18176
	ds_read_b32 v90, v56 offset:17408
	v_add_f32_dpp v124, v124, v124 row_mirror row_mask:0xf bank_mask:0xf bound_ctrl:1
	v_pk_fma_f32 v[50:51], v[80:81], v[124:125], v[112:113] op_sel_hi:[1,0,1]
	v_pk_fma_f32 v[52:53], v[82:83], v[124:125], v[114:115] op_sel_hi:[1,0,1]
	ds_read_b128 v[80:83], v0 offset:16384
	s_waitcnt lgkmcnt(6)
	v_pk_mul_f32 v[120:121], v[52:53], v[94:95]
	v_pk_fma_f32 v[120:121], v[50:51], v[92:93], v[120:121]
	ds_read_b128 v[92:95], v0 offset:16896
	v_add_f32_e32 v124, v120, v121
	v_pk_fma_f32 v[116:117], v[50:51], v[96:97], v[116:117]
	v_pk_fma_f32 v[118:119], v[52:53], v[98:99], v[118:119]
	ds_read_b128 v[96:99], v0 offset:17664
	v_add_f32_dpp v124, v124, v124 quad_perm:[1,0,3,2] row_mask:0xf bank_mask:0xf bound_ctrl:1
	v_pk_mul_f32 v[122:123], v[52:53], v[86:87]
	v_pk_fma_f32 v[122:123], v[50:51], v[84:85], v[122:123]
	ds_read_b128 v[84:87], v0 offset:15616
	v_add_f32_dpp v124, v124, v124 quad_perm:[2,3,0,1] row_mask:0xf bank_mask:0xf bound_ctrl:1
	v_pk_mul_f32 v[112:113], v[76:77], v[88:89] op_sel_hi:[1,0]
	v_pk_mul_f32 v[114:115], v[78:79], v[88:89] op_sel_hi:[1,0]
	v_add_f32_dpp v124, v124, v124 row_half_mirror row_mask:0xf bank_mask:0xf bound_ctrl:1
	v_add_f32_e32 v216, v122, v123
	ds_read_b128 v[76:79], v0 offset:19712
	ds_read_b32 v88, v56 offset:18944
	v_add_f32_dpp v124, v124, v124 row_mirror row_mask:0xf bank_mask:0xf bound_ctrl:1
	v_pk_fma_f32 v[50:51], v[104:105], v[124:125], v[116:117] op_sel_hi:[1,0,1]
	v_pk_fma_f32 v[52:53], v[106:107], v[124:125], v[118:119] op_sel_hi:[1,0,1]
	ds_read_b128 v[104:107], v0 offset:17920
	s_waitcnt lgkmcnt(6)
	v_pk_mul_f32 v[120:121], v[52:53], v[70:71]
	v_pk_fma_f32 v[120:121], v[50:51], v[68:69], v[120:121]
	ds_read_b128 v[68:71], v0 offset:18432
	v_add_f32_e32 v124, v120, v121
	v_pk_fma_f32 v[112:113], v[50:51], v[72:73], v[112:113]
	v_pk_fma_f32 v[114:115], v[52:53], v[74:75], v[114:115]
	ds_read_b128 v[72:75], v0 offset:19200
	v_add_f32_dpp v124, v124, v124 quad_perm:[1,0,3,2] row_mask:0xf bank_mask:0xf bound_ctrl:1
	v_pk_mul_f32 v[122:123], v[52:53], v[110:111]
	v_pk_fma_f32 v[122:123], v[50:51], v[108:109], v[122:123]
	ds_read_b128 v[108:111], v0 offset:17152
	v_add_f32_dpp v124, v124, v124 quad_perm:[2,3,0,1] row_mask:0xf bank_mask:0xf bound_ctrl:1
	v_pk_mul_f32 v[116:117], v[100:101], v[90:91] op_sel_hi:[1,0]
	v_pk_mul_f32 v[118:119], v[102:103], v[90:91] op_sel_hi:[1,0]
	v_add_f32_dpp v124, v124, v124 row_half_mirror row_mask:0xf bank_mask:0xf bound_ctrl:1
	v_add_f32_e32 v217, v122, v123
	ds_read_b128 v[100:103], v0 offset:21248
	ds_read_b32 v90, v56 offset:20480
	v_add_f32_dpp v124, v124, v124 row_mirror row_mask:0xf bank_mask:0xf bound_ctrl:1
	v_pk_fma_f32 v[50:51], v[80:81], v[124:125], v[112:113] op_sel_hi:[1,0,1]
	v_pk_fma_f32 v[52:53], v[82:83], v[124:125], v[114:115] op_sel_hi:[1,0,1]
	ds_read_b128 v[80:83], v0 offset:19456
	s_waitcnt lgkmcnt(6)
	v_pk_mul_f32 v[120:121], v[52:53], v[94:95]
	v_pk_fma_f32 v[120:121], v[50:51], v[92:93], v[120:121]
	ds_read_b128 v[92:95], v0 offset:19968
	v_add_f32_e32 v124, v120, v121
	v_pk_fma_f32 v[116:117], v[50:51], v[96:97], v[116:117]
	v_pk_fma_f32 v[118:119], v[52:53], v[98:99], v[118:119]
	ds_read_b128 v[96:99], v0 offset:20736
	v_add_f32_dpp v124, v124, v124 quad_perm:[1,0,3,2] row_mask:0xf bank_mask:0xf bound_ctrl:1
	v_pk_mul_f32 v[122:123], v[52:53], v[86:87]
	v_pk_fma_f32 v[122:123], v[50:51], v[84:85], v[122:123]
	ds_read_b128 v[84:87], v0 offset:18688
	v_add_f32_dpp v124, v124, v124 quad_perm:[2,3,0,1] row_mask:0xf bank_mask:0xf bound_ctrl:1
	v_pk_mul_f32 v[112:113], v[76:77], v[88:89] op_sel_hi:[1,0]
	v_pk_mul_f32 v[114:115], v[78:79], v[88:89] op_sel_hi:[1,0]
	v_add_f32_dpp v124, v124, v124 row_half_mirror row_mask:0xf bank_mask:0xf bound_ctrl:1
	v_add_f32_e32 v218, v122, v123
	ds_read_b128 v[76:79], v0 offset:22784
	ds_read_b32 v88, v56 offset:22016
	v_add_f32_dpp v124, v124, v124 row_mirror row_mask:0xf bank_mask:0xf bound_ctrl:1
	v_pk_fma_f32 v[50:51], v[104:105], v[124:125], v[116:117] op_sel_hi:[1,0,1]
	v_pk_fma_f32 v[52:53], v[106:107], v[124:125], v[118:119] op_sel_hi:[1,0,1]
	ds_read_b128 v[104:107], v0 offset:20992
	s_waitcnt lgkmcnt(6)
	v_pk_mul_f32 v[120:121], v[52:53], v[70:71]
	v_pk_fma_f32 v[120:121], v[50:51], v[68:69], v[120:121]
	ds_read_b128 v[68:71], v0 offset:21504
	v_add_f32_e32 v124, v120, v121
	v_pk_fma_f32 v[112:113], v[50:51], v[72:73], v[112:113]
	v_pk_fma_f32 v[114:115], v[52:53], v[74:75], v[114:115]
	ds_read_b128 v[72:75], v0 offset:22272
	v_add_f32_dpp v124, v124, v124 quad_perm:[1,0,3,2] row_mask:0xf bank_mask:0xf bound_ctrl:1
	v_pk_mul_f32 v[122:123], v[52:53], v[110:111]
	v_pk_fma_f32 v[122:123], v[50:51], v[108:109], v[122:123]
	ds_read_b128 v[108:111], v0 offset:20224
	v_add_f32_dpp v124, v124, v124 quad_perm:[2,3,0,1] row_mask:0xf bank_mask:0xf bound_ctrl:1
	v_pk_mul_f32 v[116:117], v[100:101], v[90:91] op_sel_hi:[1,0]
	v_pk_mul_f32 v[118:119], v[102:103], v[90:91] op_sel_hi:[1,0]
	v_add_f32_dpp v124, v124, v124 row_half_mirror row_mask:0xf bank_mask:0xf bound_ctrl:1
	v_add_f32_e32 v219, v122, v123
	ds_read_b128 v[100:103], v0 offset:24320
	ds_read_b32 v90, v56 offset:23552
	v_add_f32_dpp v124, v124, v124 row_mirror row_mask:0xf bank_mask:0xf bound_ctrl:1
	v_pk_fma_f32 v[50:51], v[80:81], v[124:125], v[112:113] op_sel_hi:[1,0,1]
	v_pk_fma_f32 v[52:53], v[82:83], v[124:125], v[114:115] op_sel_hi:[1,0,1]
	ds_read_b128 v[80:83], v0 offset:22528
	s_waitcnt lgkmcnt(6)
	v_pk_mul_f32 v[120:121], v[52:53], v[94:95]
	v_pk_fma_f32 v[120:121], v[50:51], v[92:93], v[120:121]
	ds_read_b128 v[92:95], v0 offset:23040
	v_add_f32_e32 v124, v120, v121
	v_pk_fma_f32 v[116:117], v[50:51], v[96:97], v[116:117]
	v_pk_fma_f32 v[118:119], v[52:53], v[98:99], v[118:119]
	ds_read_b128 v[96:99], v0 offset:23808
	v_add_f32_dpp v124, v124, v124 quad_perm:[1,0,3,2] row_mask:0xf bank_mask:0xf bound_ctrl:1
	v_pk_mul_f32 v[122:123], v[52:53], v[86:87]
	v_pk_fma_f32 v[122:123], v[50:51], v[84:85], v[122:123]
	ds_read_b128 v[84:87], v0 offset:21760
	v_add_f32_dpp v124, v124, v124 quad_perm:[2,3,0,1] row_mask:0xf bank_mask:0xf bound_ctrl:1
	v_pk_mul_f32 v[112:113], v[76:77], v[88:89] op_sel_hi:[1,0]
	v_pk_mul_f32 v[114:115], v[78:79], v[88:89] op_sel_hi:[1,0]
	v_add_f32_dpp v124, v124, v124 row_half_mirror row_mask:0xf bank_mask:0xf bound_ctrl:1
	v_add_f32_e32 v220, v122, v123
	s_nop 0
	v_add_f32_dpp v124, v124, v124 row_mirror row_mask:0xf bank_mask:0xf bound_ctrl:1
	v_pk_fma_f32 v[50:51], v[104:105], v[124:125], v[116:117] op_sel_hi:[1,0,1]
	v_pk_fma_f32 v[52:53], v[106:107], v[124:125], v[118:119] op_sel_hi:[1,0,1]
	ds_read_b128 v[104:107], v0 offset:24064
	s_waitcnt lgkmcnt(4)
	v_pk_mul_f32 v[120:121], v[52:53], v[70:71]
	v_pk_fma_f32 v[120:121], v[50:51], v[68:69], v[120:121]
	v_add_f32_e32 v124, v120, v121
	v_pk_fma_f32 v[112:113], v[50:51], v[72:73], v[112:113]
	v_pk_fma_f32 v[114:115], v[52:53], v[74:75], v[114:115]
	v_add_f32_dpp v124, v124, v124 quad_perm:[1,0,3,2] row_mask:0xf bank_mask:0xf bound_ctrl:1
	v_pk_mul_f32 v[122:123], v[52:53], v[110:111]
	v_pk_fma_f32 v[122:123], v[50:51], v[108:109], v[122:123]
	ds_read_b128 v[108:111], v0 offset:23296
	v_add_f32_dpp v124, v124, v124 quad_perm:[2,3,0,1] row_mask:0xf bank_mask:0xf bound_ctrl:1
	v_pk_mul_f32 v[116:117], v[100:101], v[90:91] op_sel_hi:[1,0]
	v_pk_mul_f32 v[118:119], v[102:103], v[90:91] op_sel_hi:[1,0]
	v_add_f32_dpp v124, v124, v124 row_half_mirror row_mask:0xf bank_mask:0xf bound_ctrl:1
	v_add_f32_e32 v221, v122, v123
	s_nop 0
	v_add_f32_dpp v124, v124, v124 row_mirror row_mask:0xf bank_mask:0xf bound_ctrl:1
	v_pk_fma_f32 v[50:51], v[80:81], v[124:125], v[112:113] op_sel_hi:[1,0,1]
	v_pk_fma_f32 v[52:53], v[82:83], v[124:125], v[114:115] op_sel_hi:[1,0,1]
	s_waitcnt lgkmcnt(1)
	v_pk_mul_f32 v[120:121], v[52:53], v[94:95]
	v_pk_fma_f32 v[120:121], v[50:51], v[92:93], v[120:121]
	v_add_f32_e32 v124, v120, v121
	v_pk_fma_f32 v[116:117], v[50:51], v[96:97], v[116:117]
	v_pk_fma_f32 v[118:119], v[52:53], v[98:99], v[118:119]
	v_add_f32_dpp v124, v124, v124 quad_perm:[1,0,3,2] row_mask:0xf bank_mask:0xf bound_ctrl:1
	v_pk_mul_f32 v[122:123], v[52:53], v[86:87]
	v_pk_fma_f32 v[122:123], v[50:51], v[84:85], v[122:123]
	v_add_f32_dpp v124, v124, v124 quad_perm:[2,3,0,1] row_mask:0xf bank_mask:0xf bound_ctrl:1
	s_nop 1
	v_add_f32_dpp v124, v124, v124 row_half_mirror row_mask:0xf bank_mask:0xf bound_ctrl:1
	v_add_f32_e32 v222, v122, v123
	s_nop 0
	v_add_f32_dpp v124, v124, v124 row_mirror row_mask:0xf bank_mask:0xf bound_ctrl:1
	v_pk_fma_f32 v[50:51], v[104:105], v[124:125], v[116:117] op_sel_hi:[1,0,1]
	v_pk_fma_f32 v[52:53], v[106:107], v[124:125], v[118:119] op_sel_hi:[1,0,1]
	s_waitcnt lgkmcnt(0)
	v_pk_mul_f32 v[122:123], v[52:53], v[110:111]
	v_pk_fma_f32 v[122:123], v[50:51], v[108:109], v[122:123]
	v_add_f32_e32 v223, v122, v123
	v_cndmask_b32_e64 v68, v216, v220, s[40:41]
	v_cndmask_b32_e64 v72, v220, v216, s[40:41]
	v_cndmask_b32_e64 v69, v217, v221, s[40:41]
	v_cndmask_b32_e64 v73, v221, v217, s[40:41]
	v_cndmask_b32_e64 v70, v218, v222, s[40:41]
	v_cndmask_b32_e64 v74, v222, v218, s[40:41]
	v_cndmask_b32_e64 v71, v219, v223, s[40:41]
	v_cndmask_b32_e64 v75, v223, v219, s[40:41]
	v_add_f32_dpp v68, v72, v68 row_mirror row_mask:0xf bank_mask:0xf bound_ctrl:1
	v_add_f32_dpp v69, v73, v69 row_mirror row_mask:0xf bank_mask:0xf bound_ctrl:1
	v_add_f32_dpp v70, v74, v70 row_mirror row_mask:0xf bank_mask:0xf bound_ctrl:1
	v_add_f32_dpp v71, v75, v71 row_mirror row_mask:0xf bank_mask:0xf bound_ctrl:1
	v_cndmask_b32_e64 v76, v68, v70, s[42:43]
	v_cndmask_b32_e64 v78, v70, v68, s[42:43]
	v_cndmask_b32_e64 v77, v69, v71, s[42:43]
	v_cndmask_b32_e64 v79, v71, v69, s[42:43]
	v_add_u32_e32 v66, s100, v62
	v_add_f32_dpp v76, v78, v76 row_half_mirror row_mask:0xf bank_mask:0xf bound_ctrl:1
	v_add_f32_dpp v77, v79, v77 row_half_mirror row_mask:0xf bank_mask:0xf bound_ctrl:1
	v_cndmask_b32_e64 v80, v76, v77, s[44:45]
	v_cndmask_b32_e64 v81, v77, v76, s[44:45]
	v_ashrrev_i32_e32 v67, 31, v66
	v_lshlrev_b64 v[66:67], 10, v[66:67]
	v_add_f32_dpp v80, v81, v80 quad_perm:[2,3,0,1] row_mask:0xf bank_mask:0xf bound_ctrl:1
	v_lshl_add_u64 v[66:67], v[54:55], 0, v[66:67]
	s_nop 0
	v_add_f32_dpp v65, v80, v80 quad_perm:[1,0,3,2] row_mask:0xf bank_mask:0xf bound_ctrl:1
	s_and_saveexec_b64 s[2:3], vcc
	global_store_dword v[66:67], v65, off
	s_or_b64 exec, exec, s[2:3]
	s_waitcnt lgkmcnt(0)
	s_barrier
	ds_read_b128 v[68:71], v0 offset:0
	ds_read_b128 v[76:79], v0 offset:1280
	ds_read_b32 v88, v56 offset:512
	ds_read_b128 v[72:75], v0 offset:768
	ds_read_b128 v[100:103], v0 offset:2816
	ds_read_b32 v90, v56 offset:2048
	ds_read_b128 v[80:83], v0 offset:1024
	ds_read_b128 v[92:95], v0 offset:1536
	ds_read_b128 v[84:87], v0 offset:256
	ds_read_b128 v[96:99], v0 offset:2304
	ds_read_b128 v[104:107], v0 offset:2560
	s_min_u32 s2, s6, 240
	s_add_i32 s2, s2, 15
	s_mul_i32 s2, s2, s83
	s_add_i32 s2, s2, s31
	s_mulk_i32 s2, 0x300
	s_waitcnt vmcnt(23)
	ds_write_b128 v57, v[192:195] offset:12288
	s_waitcnt vmcnt(22)
	ds_write_b128 v57, v[196:199] offset:16384
	s_waitcnt vmcnt(21)
	ds_write_b128 v57, v[200:203] offset:20480
	v_add_u32_e32 v192, s2, v58
	v_add_u32_e32 v194, s2, v59
	v_add_u32_e32 v200, s2, v60
	v_ashrrev_i32_e32 v193, 31, v192
	v_ashrrev_i32_e32 v195, 31, v194
	v_ashrrev_i32_e32 v201, 31, v200
	v_lshl_add_u64 v[192:193], v[192:193], 2, s[56:57]
	v_lshl_add_u64 v[196:197], v[194:195], 2, s[56:57]
	v_lshl_add_u64 v[200:201], v[200:201], 2, s[56:57]
	global_load_dwordx4 v[192:195], v[192:193], off
	s_nop 0
	global_load_dwordx4 v[196:199], v[196:197], off
	s_nop 0
	global_load_dwordx4 v[200:203], v[200:201], off
	s_waitcnt lgkmcnt(11)
	v_pk_mul_f32 v[112:113], v[76:77], v[88:89] op_sel_hi:[1,0]
	v_pk_mul_f32 v[114:115], v[78:79], v[88:89] op_sel_hi:[1,0]
	ds_read_b128 v[76:79], v0 offset:4352
	ds_read_b32 v88, v56 offset:3584
	s_waitcnt lgkmcnt(9)
	v_pk_mul_f32 v[120:121], v[52:53], v[70:71]
	v_pk_fma_f32 v[120:121], v[50:51], v[68:69], v[120:121]
	ds_read_b128 v[68:71], v0 offset:3072
	v_add_f32_e32 v124, v120, v121
	v_pk_fma_f32 v[112:113], v[50:51], v[72:73], v[112:113]
	v_pk_fma_f32 v[114:115], v[52:53], v[74:75], v[114:115]
	ds_read_b128 v[72:75], v0 offset:3840
	v_add_f32_dpp v124, v124, v124 quad_perm:[1,0,3,2] row_mask:0xf bank_mask:0xf bound_ctrl:1
	ds_read_b128 v[108:111], v0 offset:1792
	s_nop 0
	v_add_f32_dpp v124, v124, v124 quad_perm:[2,3,0,1] row_mask:0xf bank_mask:0xf bound_ctrl:1
	v_pk_mul_f32 v[116:117], v[100:101], v[90:91] op_sel_hi:[1,0]
	v_pk_mul_f32 v[118:119], v[102:103], v[90:91] op_sel_hi:[1,0]
	v_add_f32_dpp v124, v124, v124 row_half_mirror row_mask:0xf bank_mask:0xf bound_ctrl:1
	ds_read_b128 v[100:103], v0 offset:5888
	ds_read_b32 v90, v56 offset:5120
	v_add_f32_dpp v124, v124, v124 row_mirror row_mask:0xf bank_mask:0xf bound_ctrl:1
	v_pk_fma_f32 v[50:51], v[80:81], v[124:125], v[112:113] op_sel_hi:[1,0,1]
	v_pk_fma_f32 v[52:53], v[82:83], v[124:125], v[114:115] op_sel_hi:[1,0,1]
	ds_read_b128 v[80:83], v0 offset:4096
	s_waitcnt lgkmcnt(6)
	v_pk_mul_f32 v[120:121], v[52:53], v[94:95]
	v_pk_fma_f32 v[120:121], v[50:51], v[92:93], v[120:121]
	ds_read_b128 v[92:95], v0 offset:4608
	v_add_f32_e32 v124, v120, v121
	v_pk_fma_f32 v[116:117], v[50:51], v[96:97], v[116:117]
	v_pk_fma_f32 v[118:119], v[52:53], v[98:99], v[118:119]
	ds_read_b128 v[96:99], v0 offset:5376
	v_add_f32_dpp v124, v124, v124 quad_perm:[1,0,3,2] row_mask:0xf bank_mask:0xf bound_ctrl:1
	v_pk_mul_f32 v[122:123], v[52:53], v[86:87]
	v_pk_fma_f32 v[122:123], v[50:51], v[84:85], v[122:123]
	ds_read_b128 v[84:87], v0 offset:3328
	v_add_f32_dpp v124, v124, v124 quad_perm:[2,3,0,1] row_mask:0xf bank_mask:0xf bound_ctrl:1
	v_pk_mul_f32 v[112:113], v[76:77], v[88:89] op_sel_hi:[1,0]
	v_pk_mul_f32 v[114:115], v[78:79], v[88:89] op_sel_hi:[1,0]
	v_add_f32_dpp v124, v124, v124 row_half_mirror row_mask:0xf bank_mask:0xf bound_ctrl:1
	v_add_f32_e32 v216, v122, v123
	ds_read_b128 v[76:79], v0 offset:7424
	ds_read_b32 v88, v56 offset:6656
	v_add_f32_dpp v124, v124, v124 row_mirror row_mask:0xf bank_mask:0xf bound_ctrl:1
	v_pk_fma_f32 v[50:51], v[104:105], v[124:125], v[116:117] op_sel_hi:[1,0,1]
	v_pk_fma_f32 v[52:53], v[106:107], v[124:125], v[118:119] op_sel_hi:[1,0,1]
	ds_read_b128 v[104:107], v0 offset:5632
	s_waitcnt lgkmcnt(6)
	v_pk_mul_f32 v[120:121], v[52:53], v[70:71]
	v_pk_fma_f32 v[120:121], v[50:51], v[68:69], v[120:121]
	ds_read_b128 v[68:71], v0 offset:6144
	v_add_f32_e32 v124, v120, v121
	v_pk_fma_f32 v[112:113], v[50:51], v[72:73], v[112:113]
	v_pk_fma_f32 v[114:115], v[52:53], v[74:75], v[114:115]
	ds_read_b128 v[72:75], v0 offset:6912
	v_add_f32_dpp v124, v124, v124 quad_perm:[1,0,3,2] row_mask:0xf bank_mask:0xf bound_ctrl:1
	v_pk_mul_f32 v[122:123], v[52:53], v[110:111]
	v_pk_fma_f32 v[122:123], v[50:51], v[108:109], v[122:123]
	ds_read_b128 v[108:111], v0 offset:4864
	v_add_f32_dpp v124, v124, v124 quad_perm:[2,3,0,1] row_mask:0xf bank_mask:0xf bound_ctrl:1
	v_pk_mul_f32 v[116:117], v[100:101], v[90:91] op_sel_hi:[1,0]
	v_pk_mul_f32 v[118:119], v[102:103], v[90:91] op_sel_hi:[1,0]
	v_add_f32_dpp v124, v124, v124 row_half_mirror row_mask:0xf bank_mask:0xf bound_ctrl:1
	v_add_f32_e32 v217, v122, v123
	ds_read_b128 v[100:103], v0 offset:8960
	ds_read_b32 v90, v56 offset:8192
	v_add_f32_dpp v124, v124, v124 row_mirror row_mask:0xf bank_mask:0xf bound_ctrl:1
	v_pk_fma_f32 v[50:51], v[80:81], v[124:125], v[112:113] op_sel_hi:[1,0,1]
	v_pk_fma_f32 v[52:53], v[82:83], v[124:125], v[114:115] op_sel_hi:[1,0,1]
	ds_read_b128 v[80:83], v0 offset:7168
	s_waitcnt lgkmcnt(6)
	v_pk_mul_f32 v[120:121], v[52:53], v[94:95]
	v_pk_fma_f32 v[120:121], v[50:51], v[92:93], v[120:121]
	ds_read_b128 v[92:95], v0 offset:7680
	v_add_f32_e32 v124, v120, v121
	v_pk_fma_f32 v[116:117], v[50:51], v[96:97], v[116:117]
	v_pk_fma_f32 v[118:119], v[52:53], v[98:99], v[118:119]
	ds_read_b128 v[96:99], v0 offset:8448
	v_add_f32_dpp v124, v124, v124 quad_perm:[1,0,3,2] row_mask:0xf bank_mask:0xf bound_ctrl:1
	v_pk_mul_f32 v[122:123], v[52:53], v[86:87]
	v_pk_fma_f32 v[122:123], v[50:51], v[84:85], v[122:123]
	ds_read_b128 v[84:87], v0 offset:6400
	v_add_f32_dpp v124, v124, v124 quad_perm:[2,3,0,1] row_mask:0xf bank_mask:0xf bound_ctrl:1
	v_pk_mul_f32 v[112:113], v[76:77], v[88:89] op_sel_hi:[1,0]
	v_pk_mul_f32 v[114:115], v[78:79], v[88:89] op_sel_hi:[1,0]
	v_add_f32_dpp v124, v124, v124 row_half_mirror row_mask:0xf bank_mask:0xf bound_ctrl:1
	v_add_f32_e32 v218, v122, v123
	ds_read_b128 v[76:79], v0 offset:10496
	ds_read_b32 v88, v56 offset:9728
	v_add_f32_dpp v124, v124, v124 row_mirror row_mask:0xf bank_mask:0xf bound_ctrl:1
	v_pk_fma_f32 v[50:51], v[104:105], v[124:125], v[116:117] op_sel_hi:[1,0,1]
	v_pk_fma_f32 v[52:53], v[106:107], v[124:125], v[118:119] op_sel_hi:[1,0,1]
	ds_read_b128 v[104:107], v0 offset:8704
	s_waitcnt lgkmcnt(6)
	v_pk_mul_f32 v[120:121], v[52:53], v[70:71]
	v_pk_fma_f32 v[120:121], v[50:51], v[68:69], v[120:121]
	ds_read_b128 v[68:71], v0 offset:9216
	v_add_f32_e32 v124, v120, v121
	v_pk_fma_f32 v[112:113], v[50:51], v[72:73], v[112:113]
	v_pk_fma_f32 v[114:115], v[52:53], v[74:75], v[114:115]
	ds_read_b128 v[72:75], v0 offset:9984
	v_add_f32_dpp v124, v124, v124 quad_perm:[1,0,3,2] row_mask:0xf bank_mask:0xf bound_ctrl:1
	v_pk_mul_f32 v[122:123], v[52:53], v[110:111]
	v_pk_fma_f32 v[122:123], v[50:51], v[108:109], v[122:123]
	ds_read_b128 v[108:111], v0 offset:7936
	v_add_f32_dpp v124, v124, v124 quad_perm:[2,3,0,1] row_mask:0xf bank_mask:0xf bound_ctrl:1
	v_pk_mul_f32 v[116:117], v[100:101], v[90:91] op_sel_hi:[1,0]
	v_pk_mul_f32 v[118:119], v[102:103], v[90:91] op_sel_hi:[1,0]
	v_add_f32_dpp v124, v124, v124 row_half_mirror row_mask:0xf bank_mask:0xf bound_ctrl:1
	v_add_f32_e32 v219, v122, v123
	ds_read_b128 v[100:103], v0 offset:12032
	ds_read_b32 v90, v56 offset:11264
	v_add_f32_dpp v124, v124, v124 row_mirror row_mask:0xf bank_mask:0xf bound_ctrl:1
	v_pk_fma_f32 v[50:51], v[80:81], v[124:125], v[112:113] op_sel_hi:[1,0,1]
	v_pk_fma_f32 v[52:53], v[82:83], v[124:125], v[114:115] op_sel_hi:[1,0,1]
	ds_read_b128 v[80:83], v0 offset:10240
	s_waitcnt lgkmcnt(6)
	v_pk_mul_f32 v[120:121], v[52:53], v[94:95]
	v_pk_fma_f32 v[120:121], v[50:51], v[92:93], v[120:121]
	ds_read_b128 v[92:95], v0 offset:10752
	v_add_f32_e32 v124, v120, v121
	v_pk_fma_f32 v[116:117], v[50:51], v[96:97], v[116:117]
	v_pk_fma_f32 v[118:119], v[52:53], v[98:99], v[118:119]
	ds_read_b128 v[96:99], v0 offset:11520
	v_add_f32_dpp v124, v124, v124 quad_perm:[1,0,3,2] row_mask:0xf bank_mask:0xf bound_ctrl:1
	v_pk_mul_f32 v[122:123], v[52:53], v[86:87]
	v_pk_fma_f32 v[122:123], v[50:51], v[84:85], v[122:123]
	ds_read_b128 v[84:87], v0 offset:9472
	v_add_f32_dpp v124, v124, v124 quad_perm:[2,3,0,1] row_mask:0xf bank_mask:0xf bound_ctrl:1
	v_pk_mul_f32 v[112:113], v[76:77], v[88:89] op_sel_hi:[1,0]
	v_pk_mul_f32 v[114:115], v[78:79], v[88:89] op_sel_hi:[1,0]
	v_add_f32_dpp v124, v124, v124 row_half_mirror row_mask:0xf bank_mask:0xf bound_ctrl:1
	v_add_f32_e32 v220, v122, v123
	s_nop 0
	v_add_f32_dpp v124, v124, v124 row_mirror row_mask:0xf bank_mask:0xf bound_ctrl:1
	v_pk_fma_f32 v[50:51], v[104:105], v[124:125], v[116:117] op_sel_hi:[1,0,1]
	v_pk_fma_f32 v[52:53], v[106:107], v[124:125], v[118:119] op_sel_hi:[1,0,1]
	ds_read_b128 v[104:107], v0 offset:11776
	s_waitcnt lgkmcnt(4)
	v_pk_mul_f32 v[120:121], v[52:53], v[70:71]
	v_pk_fma_f32 v[120:121], v[50:51], v[68:69], v[120:121]
	v_add_f32_e32 v124, v120, v121
	v_pk_fma_f32 v[112:113], v[50:51], v[72:73], v[112:113]
	v_pk_fma_f32 v[114:115], v[52:53], v[74:75], v[114:115]
	v_add_f32_dpp v124, v124, v124 quad_perm:[1,0,3,2] row_mask:0xf bank_mask:0xf bound_ctrl:1
	v_pk_mul_f32 v[122:123], v[52:53], v[110:111]
	v_pk_fma_f32 v[122:123], v[50:51], v[108:109], v[122:123]
	ds_read_b128 v[108:111], v0 offset:11008
	v_add_f32_dpp v124, v124, v124 quad_perm:[2,3,0,1] row_mask:0xf bank_mask:0xf bound_ctrl:1
	v_pk_mul_f32 v[116:117], v[100:101], v[90:91] op_sel_hi:[1,0]
	v_pk_mul_f32 v[118:119], v[102:103], v[90:91] op_sel_hi:[1,0]
	v_add_f32_dpp v124, v124, v124 row_half_mirror row_mask:0xf bank_mask:0xf bound_ctrl:1
	v_add_f32_e32 v221, v122, v123
	s_nop 0
	v_add_f32_dpp v124, v124, v124 row_mirror row_mask:0xf bank_mask:0xf bound_ctrl:1
	v_pk_fma_f32 v[50:51], v[80:81], v[124:125], v[112:113] op_sel_hi:[1,0,1]
	v_pk_fma_f32 v[52:53], v[82:83], v[124:125], v[114:115] op_sel_hi:[1,0,1]
	s_waitcnt lgkmcnt(1)
	v_pk_mul_f32 v[120:121], v[52:53], v[94:95]
	v_pk_fma_f32 v[120:121], v[50:51], v[92:93], v[120:121]
	v_add_f32_e32 v124, v120, v121
	v_pk_fma_f32 v[116:117], v[50:51], v[96:97], v[116:117]
	v_pk_fma_f32 v[118:119], v[52:53], v[98:99], v[118:119]
	v_add_f32_dpp v124, v124, v124 quad_perm:[1,0,3,2] row_mask:0xf bank_mask:0xf bound_ctrl:1
	v_pk_mul_f32 v[122:123], v[52:53], v[86:87]
	v_pk_fma_f32 v[122:123], v[50:51], v[84:85], v[122:123]
	v_add_f32_dpp v124, v124, v124 quad_perm:[2,3,0,1] row_mask:0xf bank_mask:0xf bound_ctrl:1
	s_nop 1
	v_add_f32_dpp v124, v124, v124 row_half_mirror row_mask:0xf bank_mask:0xf bound_ctrl:1
	v_add_f32_e32 v222, v122, v123
	s_nop 0
	v_add_f32_dpp v124, v124, v124 row_mirror row_mask:0xf bank_mask:0xf bound_ctrl:1
	v_pk_fma_f32 v[50:51], v[104:105], v[124:125], v[116:117] op_sel_hi:[1,0,1]
	v_pk_fma_f32 v[52:53], v[106:107], v[124:125], v[118:119] op_sel_hi:[1,0,1]
	s_waitcnt lgkmcnt(0)
	v_pk_mul_f32 v[122:123], v[52:53], v[110:111]
	v_pk_fma_f32 v[122:123], v[50:51], v[108:109], v[122:123]
	v_add_f32_e32 v223, v122, v123
	v_cndmask_b32_e64 v68, v216, v220, s[40:41]
	v_cndmask_b32_e64 v72, v220, v216, s[40:41]
	v_cndmask_b32_e64 v69, v217, v221, s[40:41]
	v_cndmask_b32_e64 v73, v221, v217, s[40:41]
	v_cndmask_b32_e64 v70, v218, v222, s[40:41]
	v_cndmask_b32_e64 v74, v222, v218, s[40:41]
	v_cndmask_b32_e64 v71, v219, v223, s[40:41]
	v_cndmask_b32_e64 v75, v223, v219, s[40:41]
	v_add_f32_dpp v68, v72, v68 row_mirror row_mask:0xf bank_mask:0xf bound_ctrl:1
	v_add_f32_dpp v69, v73, v69 row_mirror row_mask:0xf bank_mask:0xf bound_ctrl:1
	v_add_f32_dpp v70, v74, v70 row_mirror row_mask:0xf bank_mask:0xf bound_ctrl:1
	v_add_f32_dpp v71, v75, v71 row_mirror row_mask:0xf bank_mask:0xf bound_ctrl:1
	v_cndmask_b32_e64 v76, v68, v70, s[42:43]
	v_cndmask_b32_e64 v78, v70, v68, s[42:43]
	v_cndmask_b32_e64 v77, v69, v71, s[42:43]
	v_cndmask_b32_e64 v79, v71, v69, s[42:43]
	v_add_u32_e32 v66, s100, v63
	v_add_f32_dpp v76, v78, v76 row_half_mirror row_mask:0xf bank_mask:0xf bound_ctrl:1
	v_add_f32_dpp v77, v79, v77 row_half_mirror row_mask:0xf bank_mask:0xf bound_ctrl:1
	v_cndmask_b32_e64 v80, v76, v77, s[44:45]
	v_cndmask_b32_e64 v81, v77, v76, s[44:45]
	v_ashrrev_i32_e32 v67, 31, v66
	v_lshlrev_b64 v[66:67], 10, v[66:67]
	v_add_f32_dpp v80, v81, v80 quad_perm:[2,3,0,1] row_mask:0xf bank_mask:0xf bound_ctrl:1
	v_lshl_add_u64 v[66:67], v[54:55], 0, v[66:67]
	s_nop 0
	v_add_f32_dpp v65, v80, v80 quad_perm:[1,0,3,2] row_mask:0xf bank_mask:0xf bound_ctrl:1
	s_and_saveexec_b64 s[2:3], vcc
	global_store_dword v[66:67], v65, off
	s_or_b64 exec, exec, s[2:3]
	s_waitcnt lgkmcnt(0)
	s_barrier
	ds_read_b128 v[68:71], v0 offset:12288
	ds_read_b128 v[76:79], v0 offset:13568
	ds_read_b32 v88, v56 offset:12800
	ds_read_b128 v[72:75], v0 offset:13056
	ds_read_b128 v[100:103], v0 offset:15104
	ds_read_b32 v90, v56 offset:14336
	ds_read_b128 v[80:83], v0 offset:13312
	ds_read_b128 v[92:95], v0 offset:13824
	ds_read_b128 v[84:87], v0 offset:12544
	ds_read_b128 v[96:99], v0 offset:14592
	ds_read_b128 v[104:107], v0 offset:14848
	s_min_u32 s2, s6, 239
	s_add_i32 s2, s2, 16
	s_mul_i32 s2, s2, s83
	s_add_i32 s2, s2, s31
	s_mulk_i32 s2, 0x300
	s_waitcnt vmcnt(23)
	ds_write_b128 v57, v[204:207] offset:0
	s_waitcnt vmcnt(22)
	ds_write_b128 v57, v[208:211] offset:4096
	s_waitcnt vmcnt(21)
	ds_write_b128 v57, v[212:215] offset:8192
	v_add_u32_e32 v204, s2, v58
	v_add_u32_e32 v206, s2, v59
	v_add_u32_e32 v212, s2, v60
	v_ashrrev_i32_e32 v205, 31, v204
	v_ashrrev_i32_e32 v207, 31, v206
	v_ashrrev_i32_e32 v213, 31, v212
	v_lshl_add_u64 v[204:205], v[204:205], 2, s[56:57]
	v_lshl_add_u64 v[208:209], v[206:207], 2, s[56:57]
	v_lshl_add_u64 v[212:213], v[212:213], 2, s[56:57]
	global_load_dwordx4 v[204:207], v[204:205], off
	s_nop 0
	global_load_dwordx4 v[208:211], v[208:209], off
	s_nop 0
	global_load_dwordx4 v[212:215], v[212:213], off
	s_waitcnt lgkmcnt(11)
	v_pk_mul_f32 v[112:113], v[76:77], v[88:89] op_sel_hi:[1,0]
	v_pk_mul_f32 v[114:115], v[78:79], v[88:89] op_sel_hi:[1,0]
	ds_read_b128 v[76:79], v0 offset:16640
	ds_read_b32 v88, v56 offset:15872
	s_waitcnt lgkmcnt(9)
	v_pk_mul_f32 v[120:121], v[52:53], v[70:71]
	v_pk_fma_f32 v[120:121], v[50:51], v[68:69], v[120:121]
	ds_read_b128 v[68:71], v0 offset:15360
	v_add_f32_e32 v124, v120, v121
	v_pk_fma_f32 v[112:113], v[50:51], v[72:73], v[112:113]
	v_pk_fma_f32 v[114:115], v[52:53], v[74:75], v[114:115]
	ds_read_b128 v[72:75], v0 offset:16128
	v_add_f32_dpp v124, v124, v124 quad_perm:[1,0,3,2] row_mask:0xf bank_mask:0xf bound_ctrl:1
	ds_read_b128 v[108:111], v0 offset:14080
	s_nop 0
	v_add_f32_dpp v124, v124, v124 quad_perm:[2,3,0,1] row_mask:0xf bank_mask:0xf bound_ctrl:1
	v_pk_mul_f32 v[116:117], v[100:101], v[90:91] op_sel_hi:[1,0]
	v_pk_mul_f32 v[118:119], v[102:103], v[90:91] op_sel_hi:[1,0]
	v_add_f32_dpp v124, v124, v124 row_half_mirror row_mask:0xf bank_mask:0xf bound_ctrl:1
	ds_read_b128 v[100:103], v0 offset:18176
	ds_read_b32 v90, v56 offset:17408
	v_add_f32_dpp v124, v124, v124 row_mirror row_mask:0xf bank_mask:0xf bound_ctrl:1
	v_pk_fma_f32 v[50:51], v[80:81], v[124:125], v[112:113] op_sel_hi:[1,0,1]
	v_pk_fma_f32 v[52:53], v[82:83], v[124:125], v[114:115] op_sel_hi:[1,0,1]
	ds_read_b128 v[80:83], v0 offset:16384
	s_waitcnt lgkmcnt(6)
	v_pk_mul_f32 v[120:121], v[52:53], v[94:95]
	v_pk_fma_f32 v[120:121], v[50:51], v[92:93], v[120:121]
	ds_read_b128 v[92:95], v0 offset:16896
	v_add_f32_e32 v124, v120, v121
	v_pk_fma_f32 v[116:117], v[50:51], v[96:97], v[116:117]
	v_pk_fma_f32 v[118:119], v[52:53], v[98:99], v[118:119]
	ds_read_b128 v[96:99], v0 offset:17664
	v_add_f32_dpp v124, v124, v124 quad_perm:[1,0,3,2] row_mask:0xf bank_mask:0xf bound_ctrl:1
	v_pk_mul_f32 v[122:123], v[52:53], v[86:87]
	v_pk_fma_f32 v[122:123], v[50:51], v[84:85], v[122:123]
	ds_read_b128 v[84:87], v0 offset:15616
	v_add_f32_dpp v124, v124, v124 quad_perm:[2,3,0,1] row_mask:0xf bank_mask:0xf bound_ctrl:1
	v_pk_mul_f32 v[112:113], v[76:77], v[88:89] op_sel_hi:[1,0]
	v_pk_mul_f32 v[114:115], v[78:79], v[88:89] op_sel_hi:[1,0]
	v_add_f32_dpp v124, v124, v124 row_half_mirror row_mask:0xf bank_mask:0xf bound_ctrl:1
	v_add_f32_e32 v216, v122, v123
	ds_read_b128 v[76:79], v0 offset:19712
	ds_read_b32 v88, v56 offset:18944
	v_add_f32_dpp v124, v124, v124 row_mirror row_mask:0xf bank_mask:0xf bound_ctrl:1
	v_pk_fma_f32 v[50:51], v[104:105], v[124:125], v[116:117] op_sel_hi:[1,0,1]
	v_pk_fma_f32 v[52:53], v[106:107], v[124:125], v[118:119] op_sel_hi:[1,0,1]
	ds_read_b128 v[104:107], v0 offset:17920
	s_waitcnt lgkmcnt(6)
	v_pk_mul_f32 v[120:121], v[52:53], v[70:71]
	v_pk_fma_f32 v[120:121], v[50:51], v[68:69], v[120:121]
	ds_read_b128 v[68:71], v0 offset:18432
	v_add_f32_e32 v124, v120, v121
	v_pk_fma_f32 v[112:113], v[50:51], v[72:73], v[112:113]
	v_pk_fma_f32 v[114:115], v[52:53], v[74:75], v[114:115]
	ds_read_b128 v[72:75], v0 offset:19200
	v_add_f32_dpp v124, v124, v124 quad_perm:[1,0,3,2] row_mask:0xf bank_mask:0xf bound_ctrl:1
	v_pk_mul_f32 v[122:123], v[52:53], v[110:111]
	v_pk_fma_f32 v[122:123], v[50:51], v[108:109], v[122:123]
	ds_read_b128 v[108:111], v0 offset:17152
	v_add_f32_dpp v124, v124, v124 quad_perm:[2,3,0,1] row_mask:0xf bank_mask:0xf bound_ctrl:1
	v_pk_mul_f32 v[116:117], v[100:101], v[90:91] op_sel_hi:[1,0]
	v_pk_mul_f32 v[118:119], v[102:103], v[90:91] op_sel_hi:[1,0]
	v_add_f32_dpp v124, v124, v124 row_half_mirror row_mask:0xf bank_mask:0xf bound_ctrl:1
	v_add_f32_e32 v217, v122, v123
	ds_read_b128 v[100:103], v0 offset:21248
	ds_read_b32 v90, v56 offset:20480
	v_add_f32_dpp v124, v124, v124 row_mirror row_mask:0xf bank_mask:0xf bound_ctrl:1
	v_pk_fma_f32 v[50:51], v[80:81], v[124:125], v[112:113] op_sel_hi:[1,0,1]
	v_pk_fma_f32 v[52:53], v[82:83], v[124:125], v[114:115] op_sel_hi:[1,0,1]
	ds_read_b128 v[80:83], v0 offset:19456
	s_waitcnt lgkmcnt(6)
	v_pk_mul_f32 v[120:121], v[52:53], v[94:95]
	v_pk_fma_f32 v[120:121], v[50:51], v[92:93], v[120:121]
	ds_read_b128 v[92:95], v0 offset:19968
	v_add_f32_e32 v124, v120, v121
	v_pk_fma_f32 v[116:117], v[50:51], v[96:97], v[116:117]
	v_pk_fma_f32 v[118:119], v[52:53], v[98:99], v[118:119]
	ds_read_b128 v[96:99], v0 offset:20736
	v_add_f32_dpp v124, v124, v124 quad_perm:[1,0,3,2] row_mask:0xf bank_mask:0xf bound_ctrl:1
	v_pk_mul_f32 v[122:123], v[52:53], v[86:87]
	v_pk_fma_f32 v[122:123], v[50:51], v[84:85], v[122:123]
	ds_read_b128 v[84:87], v0 offset:18688
	v_add_f32_dpp v124, v124, v124 quad_perm:[2,3,0,1] row_mask:0xf bank_mask:0xf bound_ctrl:1
	v_pk_mul_f32 v[112:113], v[76:77], v[88:89] op_sel_hi:[1,0]
	v_pk_mul_f32 v[114:115], v[78:79], v[88:89] op_sel_hi:[1,0]
	v_add_f32_dpp v124, v124, v124 row_half_mirror row_mask:0xf bank_mask:0xf bound_ctrl:1
	v_add_f32_e32 v218, v122, v123
	ds_read_b128 v[76:79], v0 offset:22784
	ds_read_b32 v88, v56 offset:22016
	v_add_f32_dpp v124, v124, v124 row_mirror row_mask:0xf bank_mask:0xf bound_ctrl:1
	v_pk_fma_f32 v[50:51], v[104:105], v[124:125], v[116:117] op_sel_hi:[1,0,1]
	v_pk_fma_f32 v[52:53], v[106:107], v[124:125], v[118:119] op_sel_hi:[1,0,1]
	ds_read_b128 v[104:107], v0 offset:20992
	s_waitcnt lgkmcnt(6)
	v_pk_mul_f32 v[120:121], v[52:53], v[70:71]
	v_pk_fma_f32 v[120:121], v[50:51], v[68:69], v[120:121]
	ds_read_b128 v[68:71], v0 offset:21504
	v_add_f32_e32 v124, v120, v121
	v_pk_fma_f32 v[112:113], v[50:51], v[72:73], v[112:113]
	v_pk_fma_f32 v[114:115], v[52:53], v[74:75], v[114:115]
	ds_read_b128 v[72:75], v0 offset:22272
	v_add_f32_dpp v124, v124, v124 quad_perm:[1,0,3,2] row_mask:0xf bank_mask:0xf bound_ctrl:1
	v_pk_mul_f32 v[122:123], v[52:53], v[110:111]
	v_pk_fma_f32 v[122:123], v[50:51], v[108:109], v[122:123]
	ds_read_b128 v[108:111], v0 offset:20224
	v_add_f32_dpp v124, v124, v124 quad_perm:[2,3,0,1] row_mask:0xf bank_mask:0xf bound_ctrl:1
	v_pk_mul_f32 v[116:117], v[100:101], v[90:91] op_sel_hi:[1,0]
	v_pk_mul_f32 v[118:119], v[102:103], v[90:91] op_sel_hi:[1,0]
	v_add_f32_dpp v124, v124, v124 row_half_mirror row_mask:0xf bank_mask:0xf bound_ctrl:1
	v_add_f32_e32 v219, v122, v123
	ds_read_b128 v[100:103], v0 offset:24320
	ds_read_b32 v90, v56 offset:23552
	v_add_f32_dpp v124, v124, v124 row_mirror row_mask:0xf bank_mask:0xf bound_ctrl:1
	v_pk_fma_f32 v[50:51], v[80:81], v[124:125], v[112:113] op_sel_hi:[1,0,1]
	v_pk_fma_f32 v[52:53], v[82:83], v[124:125], v[114:115] op_sel_hi:[1,0,1]
	ds_read_b128 v[80:83], v0 offset:22528
	s_waitcnt lgkmcnt(6)
	v_pk_mul_f32 v[120:121], v[52:53], v[94:95]
	v_pk_fma_f32 v[120:121], v[50:51], v[92:93], v[120:121]
	ds_read_b128 v[92:95], v0 offset:23040
	v_add_f32_e32 v124, v120, v121
	v_pk_fma_f32 v[116:117], v[50:51], v[96:97], v[116:117]
	v_pk_fma_f32 v[118:119], v[52:53], v[98:99], v[118:119]
	ds_read_b128 v[96:99], v0 offset:23808
	v_add_f32_dpp v124, v124, v124 quad_perm:[1,0,3,2] row_mask:0xf bank_mask:0xf bound_ctrl:1
	v_pk_mul_f32 v[122:123], v[52:53], v[86:87]
	v_pk_fma_f32 v[122:123], v[50:51], v[84:85], v[122:123]
	ds_read_b128 v[84:87], v0 offset:21760
	v_add_f32_dpp v124, v124, v124 quad_perm:[2,3,0,1] row_mask:0xf bank_mask:0xf bound_ctrl:1
	v_pk_mul_f32 v[112:113], v[76:77], v[88:89] op_sel_hi:[1,0]
	v_pk_mul_f32 v[114:115], v[78:79], v[88:89] op_sel_hi:[1,0]
	v_add_f32_dpp v124, v124, v124 row_half_mirror row_mask:0xf bank_mask:0xf bound_ctrl:1
	v_add_f32_e32 v220, v122, v123
	s_nop 0
	v_add_f32_dpp v124, v124, v124 row_mirror row_mask:0xf bank_mask:0xf bound_ctrl:1
	v_pk_fma_f32 v[50:51], v[104:105], v[124:125], v[116:117] op_sel_hi:[1,0,1]
	v_pk_fma_f32 v[52:53], v[106:107], v[124:125], v[118:119] op_sel_hi:[1,0,1]
	ds_read_b128 v[104:107], v0 offset:24064
	s_waitcnt lgkmcnt(4)
	v_pk_mul_f32 v[120:121], v[52:53], v[70:71]
	v_pk_fma_f32 v[120:121], v[50:51], v[68:69], v[120:121]
	v_add_f32_e32 v124, v120, v121
	v_pk_fma_f32 v[112:113], v[50:51], v[72:73], v[112:113]
	v_pk_fma_f32 v[114:115], v[52:53], v[74:75], v[114:115]
	v_add_f32_dpp v124, v124, v124 quad_perm:[1,0,3,2] row_mask:0xf bank_mask:0xf bound_ctrl:1
	v_pk_mul_f32 v[122:123], v[52:53], v[110:111]
	v_pk_fma_f32 v[122:123], v[50:51], v[108:109], v[122:123]
	ds_read_b128 v[108:111], v0 offset:23296
	v_add_f32_dpp v124, v124, v124 quad_perm:[2,3,0,1] row_mask:0xf bank_mask:0xf bound_ctrl:1
	v_pk_mul_f32 v[116:117], v[100:101], v[90:91] op_sel_hi:[1,0]
	v_pk_mul_f32 v[118:119], v[102:103], v[90:91] op_sel_hi:[1,0]
	v_add_f32_dpp v124, v124, v124 row_half_mirror row_mask:0xf bank_mask:0xf bound_ctrl:1
	v_add_f32_e32 v221, v122, v123
	s_nop 0
	v_add_f32_dpp v124, v124, v124 row_mirror row_mask:0xf bank_mask:0xf bound_ctrl:1
	v_pk_fma_f32 v[50:51], v[80:81], v[124:125], v[112:113] op_sel_hi:[1,0,1]
	v_pk_fma_f32 v[52:53], v[82:83], v[124:125], v[114:115] op_sel_hi:[1,0,1]
	s_waitcnt lgkmcnt(1)
	v_pk_mul_f32 v[120:121], v[52:53], v[94:95]
	v_pk_fma_f32 v[120:121], v[50:51], v[92:93], v[120:121]
	v_add_f32_e32 v124, v120, v121
	v_pk_fma_f32 v[116:117], v[50:51], v[96:97], v[116:117]
	v_pk_fma_f32 v[118:119], v[52:53], v[98:99], v[118:119]
	v_add_f32_dpp v124, v124, v124 quad_perm:[1,0,3,2] row_mask:0xf bank_mask:0xf bound_ctrl:1
	v_pk_mul_f32 v[122:123], v[52:53], v[86:87]
	v_pk_fma_f32 v[122:123], v[50:51], v[84:85], v[122:123]
	v_add_f32_dpp v124, v124, v124 quad_perm:[2,3,0,1] row_mask:0xf bank_mask:0xf bound_ctrl:1
	s_nop 1
	v_add_f32_dpp v124, v124, v124 row_half_mirror row_mask:0xf bank_mask:0xf bound_ctrl:1
	v_add_f32_e32 v222, v122, v123
	s_nop 0
	v_add_f32_dpp v124, v124, v124 row_mirror row_mask:0xf bank_mask:0xf bound_ctrl:1
	v_pk_fma_f32 v[50:51], v[104:105], v[124:125], v[116:117] op_sel_hi:[1,0,1]
	v_pk_fma_f32 v[52:53], v[106:107], v[124:125], v[118:119] op_sel_hi:[1,0,1]
	s_waitcnt lgkmcnt(0)
	v_pk_mul_f32 v[122:123], v[52:53], v[110:111]
	v_pk_fma_f32 v[122:123], v[50:51], v[108:109], v[122:123]
	v_add_f32_e32 v223, v122, v123
	v_cndmask_b32_e64 v68, v216, v220, s[40:41]
	v_cndmask_b32_e64 v72, v220, v216, s[40:41]
	v_cndmask_b32_e64 v69, v217, v221, s[40:41]
	v_cndmask_b32_e64 v73, v221, v217, s[40:41]
	v_cndmask_b32_e64 v70, v218, v222, s[40:41]
	v_cndmask_b32_e64 v74, v222, v218, s[40:41]
	v_cndmask_b32_e64 v71, v219, v223, s[40:41]
	v_cndmask_b32_e64 v75, v223, v219, s[40:41]
	v_add_f32_dpp v68, v72, v68 row_mirror row_mask:0xf bank_mask:0xf bound_ctrl:1
	v_add_f32_dpp v69, v73, v69 row_mirror row_mask:0xf bank_mask:0xf bound_ctrl:1
	v_add_f32_dpp v70, v74, v70 row_mirror row_mask:0xf bank_mask:0xf bound_ctrl:1
	v_add_f32_dpp v71, v75, v71 row_mirror row_mask:0xf bank_mask:0xf bound_ctrl:1
	v_cndmask_b32_e64 v76, v68, v70, s[42:43]
	v_cndmask_b32_e64 v78, v70, v68, s[42:43]
	v_cndmask_b32_e64 v77, v69, v71, s[42:43]
	v_cndmask_b32_e64 v79, v71, v69, s[42:43]
	v_add_u32_e32 v66, s100, v64
	v_add_f32_dpp v76, v78, v76 row_half_mirror row_mask:0xf bank_mask:0xf bound_ctrl:1
	v_add_f32_dpp v77, v79, v77 row_half_mirror row_mask:0xf bank_mask:0xf bound_ctrl:1
	v_cndmask_b32_e64 v80, v76, v77, s[44:45]
	v_cndmask_b32_e64 v81, v77, v76, s[44:45]
	v_ashrrev_i32_e32 v67, 31, v66
	v_lshlrev_b64 v[66:67], 10, v[66:67]
	v_add_f32_dpp v80, v81, v80 quad_perm:[2,3,0,1] row_mask:0xf bank_mask:0xf bound_ctrl:1
	v_lshl_add_u64 v[66:67], v[54:55], 0, v[66:67]
	s_nop 0
	v_add_f32_dpp v65, v80, v80 quad_perm:[1,0,3,2] row_mask:0xf bank_mask:0xf bound_ctrl:1
	s_and_saveexec_b64 s[2:3], vcc
	global_store_dword v[66:67], v65, off
	s_or_b64 exec, exec, s[2:3]
	v_readlane_b32 s2, v224, 7
	s_nop 1
	s_lshl_b32 s2, s2, 1
	s_cmpk_lt_u32 s6, 0xf8
	v_add_u32_e32 v61, s2, v61
	v_add_u32_e32 v62, s2, v62
	v_add_u32_e32 v63, s2, v63
	v_add_u32_e32 v64, s2, v64
	s_waitcnt lgkmcnt(0)
	s_barrier
	s_cbranch_scc1 .LBB0_279
